# GEMM K-loops: per-segment s_setprio flips deleted, one static priority raise for waves 4-7 in front of each loop
# speedup vs baseline: 1.0048x; 1.0022x over previous
;     __host__ __device__ bool next(int i, Unit& u) const { return i < cnt ? so.next(base + i, u) : false; }
; template <class Epi, class Sched, bool ALIGN_EPI = false, bool SP2 = false>
; __device__ __forceinline__ void gemm_phase(PG8_LAS unsigned char* lds, const Gemm g, const Sched& S, const Epi& E) {
;     ...
;     f32x4 acc[2][2][4][2];
; #pragma unroll
;     for (int a = 0; a < 2; ++a)
; #pragma unroll
;         for (int b = 0; b < 2; ++b)
; #pragma unroll
;             for (int m = 0; m < 4; ++m)
; #pragma unroll
;                 for (int n = 0; n < 2; ++n) acc[a][b][m][n] = (f32x4){0.f, 0.f, 0.f, 0.f};
;     bf16x8 At[4][2], B0[2][2], B1[2][2];
;     const char* cA = (const char*)(g.A + (size_t)cur.g * g.gsA) + (size_t)cur.pm * tstepA; const char* cB = (const char*)(g.Bt + (size_t)cur.g * g.gsB) + (size_t)cur.pn * tstepB;
;     S.a_ready(cur);
;     if constexpr (SP2) {
;         PG8_STAGE(PG8_SB(0, 0), cB, voffB); PG8_STAGE(PG8_SB(0, 1), cB + hstepB, voffB); PG8_STAGE(PG8_SA(0, 0), cA, voffA); PG8_STAGE(PG8_SA(0, 1), cA + hstepA, voffA);
;         if (wr == 1) PG8_BAR;
;         PG8_WAIT_V(2); PG8_BAR;
;         PG8_STAGE(PG8_SB(1, 0), cB + kstep, voffB); PG8_STAGE(PG8_SA(1, 0), cA + kstep, voffA); PG8_STAGE(PG8_SB(1, 1), cB + hstepB + kstep, voffB);
;         PG8_WAIT_V(6); PG8_BAR;
;     } else {
;         PG8_STAGE(PG8_SB(0, 0), cB, voffB); PG8_STAGE(PG8_SA(0, 0), cA, voffA); PG8_STAGE(PG8_SB(0, 1), cB + hstepB, voffB); PG8_STAGE(PG8_SA(0, 1), cA + hstepA, voffA);
;         if (wr == 1) PG8_BAR;
;         PG8_WAIT_V(4); PG8_BAR;
;         PG8_STAGE(PG8_SB(1, 0), cB + kstep, voffB); PG8_STAGE(PG8_SA(1, 0), cA + kstep, voffA); PG8_STAGE(PG8_SB(1, 1), cB + hstepB + kstep, voffB);
;         PG8_WAIT_V(6); PG8_BAR;
;     }
;     for (;;) {
;         const bool has_next = S.next(ui + 1, nxt);
;         const char* nA = has_next ? (const char*)(g.A + (size_t)nxt.g * g.gsA) + (size_t)nxt.pm * tstepA : cA; const char* nB = has_next ? (const char*)(g.Bt + (size_t)nxt.g * g.gsB) + (size_t)nxt.pn * tstepB : cB;
;         for (int t = 0; t < nt; t += 2) {
;             if constexpr (Epi::MIDK) { if (t == (nt >> 1)) { asm volatile("s_waitcnt vmcnt(0)" ::: "memory"); E.mid(acc, cur, wr, wc, fr, fq); asm volatile("s_waitcnt vmcnt(0)" ::: "memory"); } }
;             const bool last = (t == nt - 2);
;             const char* a1 = cA + (size_t)(t + 1) * kstep;
.LBB0_84:
	s_ashr_i32 s25, s24, 31
	s_lshl_b64 s[26:27], s[24:25], 20
	s_add_u32 s26, s37, s26
	s_addc_u32 s27, s38, s27
	s_ashr_i32 s23, s22, 31
	s_lshl_b64 s[28:29], s[22:23], 20
	s_add_u32 s28, s39, s28
	v_mov_b32_e32 v127, 0
	s_addc_u32 s29, s44, s29
	s_and_b64 vcc, exec, s[6:7]
	v_mov_b32_e32 v126, v127
	v_mov_b32_e32 v125, v127
	v_mov_b32_e32 v124, v127
	v_mov_b32_e32 v123, v127
	v_mov_b32_e32 v122, v127
	v_mov_b32_e32 v121, v127
	v_mov_b32_e32 v120, v127
	v_mov_b32_e32 v111, v127
	v_mov_b32_e32 v110, v127
	v_mov_b32_e32 v109, v127
	v_mov_b32_e32 v108, v127
	v_mov_b32_e32 v107, v127
	v_mov_b32_e32 v106, v127
	v_mov_b32_e32 v105, v127
	v_mov_b32_e32 v104, v127
	v_mov_b32_e32 v95, v127
	v_mov_b32_e32 v94, v127
	v_mov_b32_e32 v93, v127
	v_mov_b32_e32 v92, v127
	v_mov_b32_e32 v91, v127
	v_mov_b32_e32 v90, v127
	v_mov_b32_e32 v89, v127
	v_mov_b32_e32 v88, v127
	v_mov_b32_e32 v79, v127
	v_mov_b32_e32 v78, v127
	v_mov_b32_e32 v77, v127
	v_mov_b32_e32 v76, v127
	v_mov_b32_e32 v75, v127
	v_mov_b32_e32 v74, v127
	v_mov_b32_e32 v73, v127
	v_mov_b32_e32 v72, v127
	v_mov_b32_e32 v119, v127
	v_mov_b32_e32 v118, v127
	v_mov_b32_e32 v117, v127
	v_mov_b32_e32 v116, v127
	v_mov_b32_e32 v115, v127
	v_mov_b32_e32 v114, v127
	v_mov_b32_e32 v113, v127
	v_mov_b32_e32 v112, v127
	v_mov_b32_e32 v103, v127
	v_mov_b32_e32 v102, v127
	v_mov_b32_e32 v101, v127
	v_mov_b32_e32 v100, v127
	v_mov_b32_e32 v99, v127
	v_mov_b32_e32 v98, v127
	v_mov_b32_e32 v97, v127
	v_mov_b32_e32 v96, v127
	v_mov_b32_e32 v87, v127
	v_mov_b32_e32 v86, v127
	v_mov_b32_e32 v85, v127
	v_mov_b32_e32 v84, v127
	v_mov_b32_e32 v83, v127
	v_mov_b32_e32 v82, v127
	v_mov_b32_e32 v81, v127
	v_mov_b32_e32 v80, v127
	v_mov_b32_e32 v71, v127
	v_mov_b32_e32 v70, v127
	v_mov_b32_e32 v69, v127
	v_mov_b32_e32 v68, v127
	v_mov_b32_e32 v67, v127
	v_mov_b32_e32 v66, v127
	v_mov_b32_e32 v65, v127
	v_mov_b32_e32 v64, v127
	v_mov_b32_e32 v63, v127
	v_mov_b32_e32 v62, v127
	v_mov_b32_e32 v61, v127
	v_mov_b32_e32 v60, v127
	v_mov_b32_e32 v59, v127
	v_mov_b32_e32 v58, v127
	v_mov_b32_e32 v57, v127
	v_mov_b32_e32 v56, v127
	v_mov_b32_e32 v47, v127
	v_mov_b32_e32 v46, v127
	v_mov_b32_e32 v45, v127
	v_mov_b32_e32 v44, v127
	v_mov_b32_e32 v43, v127
	v_mov_b32_e32 v42, v127
	v_mov_b32_e32 v41, v127
	v_mov_b32_e32 v40, v127
	v_mov_b32_e32 v31, v127
	v_mov_b32_e32 v30, v127
	v_mov_b32_e32 v29, v127
	v_mov_b32_e32 v28, v127
	v_mov_b32_e32 v27, v127
	v_mov_b32_e32 v26, v127
	v_mov_b32_e32 v25, v127
	v_mov_b32_e32 v24, v127
	v_mov_b32_e32 v15, v127
	v_mov_b32_e32 v14, v127
	v_mov_b32_e32 v13, v127
	v_mov_b32_e32 v12, v127
	v_mov_b32_e32 v11, v127
	v_mov_b32_e32 v10, v127
	v_mov_b32_e32 v9, v127
	v_mov_b32_e32 v8, v127
	v_mov_b32_e32 v55, v127
	v_mov_b32_e32 v54, v127
	v_mov_b32_e32 v53, v127
	v_mov_b32_e32 v52, v127
	v_mov_b32_e32 v51, v127
	v_mov_b32_e32 v50, v127
	v_mov_b32_e32 v49, v127
	v_mov_b32_e32 v48, v127
	v_mov_b32_e32 v39, v127
	v_mov_b32_e32 v38, v127
	v_mov_b32_e32 v37, v127
	v_mov_b32_e32 v36, v127
	v_mov_b32_e32 v35, v127
	v_mov_b32_e32 v34, v127
	v_mov_b32_e32 v33, v127
	v_mov_b32_e32 v32, v127
	v_mov_b32_e32 v23, v127
	v_mov_b32_e32 v22, v127
	v_mov_b32_e32 v21, v127
	v_mov_b32_e32 v20, v127
	v_mov_b32_e32 v19, v127
	v_mov_b32_e32 v18, v127
	v_mov_b32_e32 v17, v127
	v_mov_b32_e32 v16, v127
	v_mov_b32_e32 v7, v127
	v_mov_b32_e32 v6, v127
	v_mov_b32_e32 v5, v127
	v_mov_b32_e32 v4, v127
	v_mov_b32_e32 v3, v127
	v_mov_b32_e32 v2, v127
	s_waitcnt lgkmcnt(0)
	v_mov_b32_e32 v1, v127
	v_mov_b32_e32 v0, v127
	s_cbranch_vccnz .LBB0_87
	s_and_b64 s[34:35], s[8:9], exec
	s_cselect_b32 s11, s27, s31
	s_cselect_b32 s23, s26, s30
	s_cselect_b32 s25, s29, s13
	s_cselect_b32 s40, s28, s12
	s_add_u32 s41, s12, 0x100
	s_addc_u32 s42, s13, 0
	s_add_u32 s12, s30, 0x80080
	s_addc_u32 s13, s31, 0
	s_mov_b32 s30, 0
	v_readfirstlane_b32 s32, v227
	s_nop 3
	s_lshr_b32 s32, s32, 6
	s_cmp_ge_u32 s32, 4
	s_cbranch_scc0 .Lprio_0
	s_setprio 1
.Lprio_0:
.LBB0_86:
	ds_read_b128 v[146:149], v159
	ds_read_b128 v[150:153], v159 offset:1024
	ds_read_b128 v[164:167], v159 offset:2048
	ds_read_b128 v[168:171], v159 offset:3072
	ds_read_b128 v[172:175], v160
	ds_read_b128 v[176:179], v160 offset:1024
	ds_read_b128 v[180:183], v160 offset:2048
	ds_read_b128 v[184:187], v160 offset:3072
	s_add_i32 s43, s30, 2
	s_add_u32 s31, s12, 0xfff80080
	s_addc_u32 s34, s13, -1
	s_cmp_eq_u32 s60, s30
	s_cselect_b32 s30, s40, s41
	s_cselect_b32 s35, s11, s34
	s_cselect_b32 s34, s23, s31
	s_cselect_b32 s31, s25, s42
	v_lshl_add_u64 v[154:155], s[12:13], 0, v[140:141]
	s_add_i32 m0, s46, 0xc000
	ds_read_b128 v[188:191], v161
	ds_read_b128 v[192:195], v161 offset:1024
	ds_read_b128 v[196:199], v161 offset:2048
	ds_read_b128 v[200:203], v161 offset:3072
	ds_read_b128 v[204:207], v161 offset:4096
	ds_read_b128 v[208:211], v161 offset:5120
	ds_read_b128 v[212:215], v161 offset:6144
	ds_read_b128 v[216:219], v161 offset:7168
	global_load_lds_dwordx4 v[154:155], off
	v_lshl_add_u64 v[154:155], s[12:13], 0, v[138:139]
	s_add_i32 m0, s46, 0xe000
	s_nop 0
	global_load_lds_dwordx4 v[154:155], off
	s_waitcnt vmcnt(8)
	s_waitcnt lgkmcnt(0)
	s_barrier
; #define PG8_STAGE(bufoff, gbase, voff) do { _Pragma("unroll") for (int _i = 0; _i < 2; ++_i) \
;         __builtin_amdgcn_global_load_lds((const unsigned*)((const char*)(gbase) + (voff)[_i]), (PG8_LAS unsigned*)(lds + (bufoff) + ldsw + _i * 8192), 16, 0, 0); } while (0)
; #define PG8_LDA(dst, b, h) do { _Pragma("unroll") for (int m = 0; m < 4; ++m) _Pragma("unroll") for (int k = 0; k < 2; ++k) dst[m][k] = *(const PG8_LAS bf16x8*)(lds + PG8_SA(b, h) + aoff + m * 2048 + k * 1024); } while (0)
; #define PG8_MMA(ai, bj, At, Bt) do { __builtin_amdgcn_s_setprio(1); _Pragma("unroll") for (int m = 0; m < 4; ++m) _Pragma("unroll") for (int n = 0; n < 2; ++n) _Pragma("unroll") for (int k = 0; k < 2; ++k) \
;         acc[ai][bj][m][n] = __builtin_amdgcn_mfma_f32_16x16x32_bf16(Bt[n][k], At[m][k], acc[ai][bj][m][n], 0, 0, 0); __builtin_amdgcn_s_setprio(0); } while (0)
; #define PG8_WAIT_V(n) asm volatile("s_waitcnt vmcnt(" #n ")" ::: "memory")
; #define PG8_WAIT_L(n) asm volatile("s_waitcnt lgkmcnt(" #n ")" ::: "memory")
; #define PG8_BAR __builtin_amdgcn_s_barrier()
; #define PG8_SCHED __builtin_amdgcn_sched_barrier(0)
; template <class Epi, class Sched, bool ALIGN_EPI = false, bool SP2 = false>
; __device__ __forceinline__ void gemm_phase(PG8_LAS unsigned char* lds, const Gemm g, const Sched& S, const Epi& E) {
;     ...
;             PG8_WAIT_V(8); PG8_WAIT_L(0); PG8_BAR; PG8_MMA(0, 0, At, B0); PG8_MMA(0, 1, At, B1); PG8_BAR; PG8_SCHED;
;             PG8_LDA(At, 0, 1); PG8_STAGE(PG8_SB(0, 0), b2, voffB); PG8_STAGE(PG8_SB(0, 1), b2 + hstepB, voffB); PG8_STAGE(PG8_SA(0, 0), a2, voffA);
;             PG8_WAIT_V(8); PG8_WAIT_L(0); PG8_BAR; PG8_MMA(1, 0, At, B0); PG8_MMA(1, 1, At, B1); PG8_BAR; PG8_SCHED;
	s_waitcnt lgkmcnt(0)
	v_mfma_f32_16x16x32_bf16 v[124:127], v[146:149], v[188:191], v[124:127]
	v_mfma_f32_16x16x32_bf16 v[120:123], v[164:167], v[188:191], v[120:123]
	v_mfma_f32_16x16x32_bf16 v[108:111], v[146:149], v[196:199], v[108:111]
	v_mfma_f32_16x16x32_bf16 v[104:107], v[164:167], v[196:199], v[104:107]
	v_mfma_f32_16x16x32_bf16 v[92:95], v[146:149], v[204:207], v[92:95]
	v_mfma_f32_16x16x32_bf16 v[88:91], v[164:167], v[204:207], v[88:91]
	v_mfma_f32_16x16x32_bf16 v[76:79], v[146:149], v[212:215], v[76:79]
	v_mfma_f32_16x16x32_bf16 v[72:75], v[164:167], v[212:215], v[72:75]
	v_mfma_f32_16x16x32_bf16 v[124:127], v[150:153], v[192:195], v[124:127]
	v_mfma_f32_16x16x32_bf16 v[120:123], v[168:171], v[192:195], v[120:123]
	v_mfma_f32_16x16x32_bf16 v[108:111], v[150:153], v[200:203], v[108:111]
	v_mfma_f32_16x16x32_bf16 v[104:107], v[168:171], v[200:203], v[104:107]
	v_mfma_f32_16x16x32_bf16 v[92:95], v[150:153], v[208:211], v[92:95]
	v_mfma_f32_16x16x32_bf16 v[88:91], v[168:171], v[208:211], v[88:91]
	v_mfma_f32_16x16x32_bf16 v[76:79], v[150:153], v[216:219], v[76:79]
	v_mfma_f32_16x16x32_bf16 v[72:75], v[168:171], v[216:219], v[72:75]
	v_mfma_f32_16x16x32_bf16 v[116:119], v[172:175], v[188:191], v[116:119]
	v_mfma_f32_16x16x32_bf16 v[112:115], v[180:183], v[188:191], v[112:115]
	v_mfma_f32_16x16x32_bf16 v[100:103], v[172:175], v[196:199], v[100:103]
	v_mfma_f32_16x16x32_bf16 v[96:99], v[180:183], v[196:199], v[96:99]
	v_mfma_f32_16x16x32_bf16 v[84:87], v[172:175], v[204:207], v[84:87]
	v_mfma_f32_16x16x32_bf16 v[80:83], v[180:183], v[204:207], v[80:83]
	v_mfma_f32_16x16x32_bf16 v[68:71], v[172:175], v[212:215], v[68:71]
	v_mfma_f32_16x16x32_bf16 v[64:67], v[180:183], v[212:215], v[64:67]
	v_mfma_f32_16x16x32_bf16 v[116:119], v[176:179], v[192:195], v[116:119]
	v_mfma_f32_16x16x32_bf16 v[112:115], v[184:187], v[192:195], v[112:115]
	v_mfma_f32_16x16x32_bf16 v[100:103], v[176:179], v[200:203], v[100:103]
	v_mfma_f32_16x16x32_bf16 v[96:99], v[184:187], v[200:203], v[96:99]
	v_mfma_f32_16x16x32_bf16 v[84:87], v[176:179], v[208:211], v[84:87]
	v_mfma_f32_16x16x32_bf16 v[80:83], v[184:187], v[208:211], v[80:83]
	v_mfma_f32_16x16x32_bf16 v[68:71], v[176:179], v[216:219], v[68:71]
	v_mfma_f32_16x16x32_bf16 v[64:67], v[184:187], v[216:219], v[64:67]
	s_barrier
	s_add_i32 s64, s61, s45
	v_lshl_add_u64 v[154:155], s[30:31], 0, v[130:131]
	s_mov_b32 m0, s64
	ds_read_b128 v[188:191], v161 offset:16384
	ds_read_b128 v[192:195], v161 offset:17408
	ds_read_b128 v[196:199], v161 offset:18432
	ds_read_b128 v[200:203], v161 offset:19456
	ds_read_b128 v[204:207], v161 offset:20480
	ds_read_b128 v[208:211], v161 offset:21504
	ds_read_b128 v[212:215], v161 offset:22528
	ds_read_b128 v[216:219], v161 offset:23552
	global_load_lds_dwordx4 v[154:155], off
	s_add_i32 m0, s64, 0x2000
	s_add_u32 s64, s30, 0x80000
	v_lshl_add_u64 v[220:221], s[30:31], 0, v[134:135]
	s_addc_u32 s65, s31, 0
	s_add_i32 s66, s62, s45
	global_load_lds_dwordx4 v[220:221], off
	v_lshl_add_u64 v[222:223], s[64:65], 0, v[130:131]
	s_mov_b32 m0, s66
	v_lshl_add_u64 v[224:225], s[34:35], 0, v[132:133]
	global_load_lds_dwordx4 v[222:223], off
	v_lshl_add_u64 v[222:223], s[64:65], 0, v[134:135]
	s_add_i32 m0, s66, 0x2000
	s_nop 0
	global_load_lds_dwordx4 v[222:223], off
	v_lshl_add_u64 v[222:223], s[34:35], 0, v[128:129]
	s_mov_b32 m0, s46
	s_nop 0
	global_load_lds_dwordx4 v[222:223], off
	s_mov_b32 m0, s47
	s_nop 0
	global_load_lds_dwordx4 v[224:225], off
	s_waitcnt vmcnt(8)
	s_waitcnt lgkmcnt(0)
	s_barrier
	s_waitcnt lgkmcnt(0)
	v_mfma_f32_16x16x32_bf16 v[60:63], v[146:149], v[188:191], v[60:63]
	v_mfma_f32_16x16x32_bf16 v[56:59], v[164:167], v[188:191], v[56:59]
	v_mfma_f32_16x16x32_bf16 v[44:47], v[146:149], v[196:199], v[44:47]
	v_mfma_f32_16x16x32_bf16 v[40:43], v[164:167], v[196:199], v[40:43]
	v_mfma_f32_16x16x32_bf16 v[28:31], v[146:149], v[204:207], v[28:31]
	v_mfma_f32_16x16x32_bf16 v[24:27], v[164:167], v[204:207], v[24:27]
	v_mfma_f32_16x16x32_bf16 v[12:15], v[146:149], v[212:215], v[12:15]
	v_mfma_f32_16x16x32_bf16 v[8:11], v[164:167], v[212:215], v[8:11]
	v_mfma_f32_16x16x32_bf16 v[60:63], v[150:153], v[192:195], v[60:63]
	v_mfma_f32_16x16x32_bf16 v[56:59], v[168:171], v[192:195], v[56:59]
	v_mfma_f32_16x16x32_bf16 v[44:47], v[150:153], v[200:203], v[44:47]
	v_mfma_f32_16x16x32_bf16 v[40:43], v[168:171], v[200:203], v[40:43]
	v_mfma_f32_16x16x32_bf16 v[28:31], v[150:153], v[208:211], v[28:31]
	v_mfma_f32_16x16x32_bf16 v[24:27], v[168:171], v[208:211], v[24:27]
	v_mfma_f32_16x16x32_bf16 v[12:15], v[150:153], v[216:219], v[12:15]
	v_mfma_f32_16x16x32_bf16 v[8:11], v[168:171], v[216:219], v[8:11]
	v_mfma_f32_16x16x32_bf16 v[52:55], v[172:175], v[188:191], v[52:55]
	v_mfma_f32_16x16x32_bf16 v[48:51], v[180:183], v[188:191], v[48:51]
	v_mfma_f32_16x16x32_bf16 v[36:39], v[172:175], v[196:199], v[36:39]
	v_mfma_f32_16x16x32_bf16 v[32:35], v[180:183], v[196:199], v[32:35]
	v_mfma_f32_16x16x32_bf16 v[20:23], v[172:175], v[204:207], v[20:23]
	v_mfma_f32_16x16x32_bf16 v[16:19], v[180:183], v[204:207], v[16:19]
	v_mfma_f32_16x16x32_bf16 v[4:7], v[172:175], v[212:215], v[4:7]
	v_mfma_f32_16x16x32_bf16 v[0:3], v[180:183], v[212:215], v[0:3]
	v_mfma_f32_16x16x32_bf16 v[52:55], v[176:179], v[192:195], v[52:55]
	v_mfma_f32_16x16x32_bf16 v[48:51], v[184:187], v[192:195], v[48:51]
	v_mfma_f32_16x16x32_bf16 v[36:39], v[176:179], v[200:203], v[36:39]
	v_mfma_f32_16x16x32_bf16 v[32:35], v[184:187], v[200:203], v[32:35]
	v_mfma_f32_16x16x32_bf16 v[20:23], v[176:179], v[208:211], v[20:23]
	v_mfma_f32_16x16x32_bf16 v[16:19], v[184:187], v[208:211], v[16:19]
	v_mfma_f32_16x16x32_bf16 v[4:7], v[176:179], v[216:219], v[4:7]
	v_mfma_f32_16x16x32_bf16 v[0:3], v[184:187], v[216:219], v[0:3]
	s_barrier
; #define PG8_STAGE(bufoff, gbase, voff) do { _Pragma("unroll") for (int _i = 0; _i < 2; ++_i) \
;         __builtin_amdgcn_global_load_lds((const unsigned*)((const char*)(gbase) + (voff)[_i]), (PG8_LAS unsigned*)(lds + (bufoff) + ldsw + _i * 8192), 16, 0, 0); } while (0)
; #define PG8_LDA(dst, b, h) do { _Pragma("unroll") for (int m = 0; m < 4; ++m) _Pragma("unroll") for (int k = 0; k < 2; ++k) dst[m][k] = *(const PG8_LAS bf16x8*)(lds + PG8_SA(b, h) + aoff + m * 2048 + k * 1024); } while (0)
; #define PG8_LDB(dst, b, h) do { _Pragma("unroll") for (int n = 0; n < 2; ++n) _Pragma("unroll") for (int k = 0; k < 2; ++k) dst[n][k] = *(const PG8_LAS bf16x8*)(lds + PG8_SB(b, h) + boff + n * 2048 + k * 1024); } while (0)
; #define PG8_MMA(ai, bj, At, Bt) do { __builtin_amdgcn_s_setprio(1); _Pragma("unroll") for (int m = 0; m < 4; ++m) _Pragma("unroll") for (int n = 0; n < 2; ++n) _Pragma("unroll") for (int k = 0; k < 2; ++k) \
;         acc[ai][bj][m][n] = __builtin_amdgcn_mfma_f32_16x16x32_bf16(Bt[n][k], At[m][k], acc[ai][bj][m][n], 0, 0, 0); __builtin_amdgcn_s_setprio(0); } while (0)
; #define PG8_WAIT_V(n) asm volatile("s_waitcnt vmcnt(" #n ")" ::: "memory")
; #define PG8_WAIT_L(n) asm volatile("s_waitcnt lgkmcnt(" #n ")" ::: "memory")
; #define PG8_BAR __builtin_amdgcn_s_barrier()
; #define PG8_SCHED __builtin_amdgcn_sched_barrier(0)
; template <class Epi, class Sched, bool ALIGN_EPI = false, bool SP2 = false>
; __device__ __forceinline__ void gemm_phase(PG8_LAS unsigned char* lds, const Gemm g, const Sched& S, const Epi& E) {
;     ...
;             PG8_LDB(B0, 1, 0); PG8_LDB(B1, 1, 1); PG8_SCHED; PG8_LDA(At, 1, 0); PG8_STAGE(PG8_SA(0, 1), a2 + hstepA, voffA);
;             PG8_WAIT_V(8); PG8_WAIT_L(0); PG8_BAR; PG8_MMA(0, 0, At, B0); PG8_MMA(0, 1, At, B1); PG8_BAR; PG8_SCHED;
	s_add_i32 s64, 0, 0x18000
	v_add_u32_e32 v137, s64, v158
	s_add_i32 s65, 0, 0x1c000
	ds_read_b128 v[146:149], v137
	ds_read_b128 v[150:153], v137 offset:1024
	ds_read_b128 v[164:167], v137 offset:2048
	ds_read_b128 v[168:171], v137 offset:3072
	v_add_u32_e32 v137, s65, v158
	ds_read_b128 v[172:175], v137
	ds_read_b128 v[176:179], v137 offset:1024
	ds_read_b128 v[180:183], v137 offset:2048
	ds_read_b128 v[184:187], v137 offset:3072
	s_add_u32 s34, s34, 0x80000
	s_addc_u32 s35, s35, 0
	s_mov_b32 m0, s48
	v_lshl_add_u64 v[228:229], s[34:35], 0, v[128:129]
	ds_read_b128 v[188:191], v161 offset:32768
	ds_read_b128 v[192:195], v161 offset:33792
	ds_read_b128 v[196:199], v161 offset:34816
	ds_read_b128 v[200:203], v161 offset:35840
	ds_read_b128 v[204:207], v161 offset:36864
	ds_read_b128 v[208:211], v161 offset:37888
	ds_read_b128 v[212:215], v161 offset:38912
	ds_read_b128 v[216:219], v161 offset:39936
	global_load_lds_dwordx4 v[228:229], off
	v_lshl_add_u64 v[228:229], s[34:35], 0, v[132:133]
	s_mov_b32 m0, s49
	s_nop 0
	global_load_lds_dwordx4 v[228:229], off
	s_waitcnt vmcnt(8)
	s_waitcnt lgkmcnt(0)
	s_barrier
	s_waitcnt lgkmcnt(0)
	v_mfma_f32_16x16x32_bf16 v[124:127], v[146:149], v[188:191], v[124:127]
	v_mfma_f32_16x16x32_bf16 v[120:123], v[164:167], v[188:191], v[120:123]
	v_mfma_f32_16x16x32_bf16 v[108:111], v[146:149], v[196:199], v[108:111]
	v_mfma_f32_16x16x32_bf16 v[104:107], v[164:167], v[196:199], v[104:107]
	v_mfma_f32_16x16x32_bf16 v[92:95], v[146:149], v[204:207], v[92:95]
	v_mfma_f32_16x16x32_bf16 v[88:91], v[164:167], v[204:207], v[88:91]
	v_mfma_f32_16x16x32_bf16 v[76:79], v[146:149], v[212:215], v[76:79]
	v_mfma_f32_16x16x32_bf16 v[72:75], v[164:167], v[212:215], v[72:75]
	v_mfma_f32_16x16x32_bf16 v[124:127], v[150:153], v[192:195], v[124:127]
	v_mfma_f32_16x16x32_bf16 v[120:123], v[168:171], v[192:195], v[120:123]
	v_mfma_f32_16x16x32_bf16 v[108:111], v[150:153], v[200:203], v[108:111]
	v_mfma_f32_16x16x32_bf16 v[104:107], v[168:171], v[200:203], v[104:107]
	v_mfma_f32_16x16x32_bf16 v[92:95], v[150:153], v[208:211], v[92:95]
	v_mfma_f32_16x16x32_bf16 v[88:91], v[168:171], v[208:211], v[88:91]
	v_mfma_f32_16x16x32_bf16 v[76:79], v[150:153], v[216:219], v[76:79]
	v_mfma_f32_16x16x32_bf16 v[72:75], v[168:171], v[216:219], v[72:75]
	v_mfma_f32_16x16x32_bf16 v[116:119], v[172:175], v[188:191], v[116:119]
	v_mfma_f32_16x16x32_bf16 v[112:115], v[180:183], v[188:191], v[112:115]
	v_mfma_f32_16x16x32_bf16 v[100:103], v[172:175], v[196:199], v[100:103]
	v_mfma_f32_16x16x32_bf16 v[96:99], v[180:183], v[196:199], v[96:99]
	v_mfma_f32_16x16x32_bf16 v[84:87], v[172:175], v[204:207], v[84:87]
	v_mfma_f32_16x16x32_bf16 v[80:83], v[180:183], v[204:207], v[80:83]
	v_mfma_f32_16x16x32_bf16 v[68:71], v[172:175], v[212:215], v[68:71]
	v_mfma_f32_16x16x32_bf16 v[64:67], v[180:183], v[212:215], v[64:67]
	v_mfma_f32_16x16x32_bf16 v[116:119], v[176:179], v[192:195], v[116:119]
	v_mfma_f32_16x16x32_bf16 v[112:115], v[184:187], v[192:195], v[112:115]
	v_mfma_f32_16x16x32_bf16 v[100:103], v[176:179], v[200:203], v[100:103]
	v_mfma_f32_16x16x32_bf16 v[96:99], v[184:187], v[200:203], v[96:99]
	v_mfma_f32_16x16x32_bf16 v[84:87], v[176:179], v[208:211], v[84:87]
	v_mfma_f32_16x16x32_bf16 v[80:83], v[184:187], v[208:211], v[80:83]
	v_mfma_f32_16x16x32_bf16 v[68:71], v[176:179], v[216:219], v[68:71]
	v_mfma_f32_16x16x32_bf16 v[64:67], v[184:187], v[216:219], v[64:67]
	s_barrier
; #define PG8_STAGE(bufoff, gbase, voff) do { _Pragma("unroll") for (int _i = 0; _i < 2; ++_i) \
;         __builtin_amdgcn_global_load_lds((const unsigned*)((const char*)(gbase) + (voff)[_i]), (PG8_LAS unsigned*)(lds + (bufoff) + ldsw + _i * 8192), 16, 0, 0); } while (0)
; #define PG8_LDA(dst, b, h) do { _Pragma("unroll") for (int m = 0; m < 4; ++m) _Pragma("unroll") for (int k = 0; k < 2; ++k) dst[m][k] = *(const PG8_LAS bf16x8*)(lds + PG8_SA(b, h) + aoff + m * 2048 + k * 1024); } while (0)
; #define PG8_MMA(ai, bj, At, Bt) do { __builtin_amdgcn_s_setprio(1); _Pragma("unroll") for (int m = 0; m < 4; ++m) _Pragma("unroll") for (int n = 0; n < 2; ++n) _Pragma("unroll") for (int k = 0; k < 2; ++k) \
;         acc[ai][bj][m][n] = __builtin_amdgcn_mfma_f32_16x16x32_bf16(Bt[n][k], At[m][k], acc[ai][bj][m][n], 0, 0, 0); __builtin_amdgcn_s_setprio(0); } while (0)
; #define PG8_WAIT_V(n) asm volatile("s_waitcnt vmcnt(" #n ")" ::: "memory")
; #define PG8_WAIT_L(n) asm volatile("s_waitcnt lgkmcnt(" #n ")" ::: "memory")
; #define PG8_BAR __builtin_amdgcn_s_barrier()
; #define PG8_SCHED __builtin_amdgcn_sched_barrier(0)
; template <class Epi, class Sched, bool ALIGN_EPI = false, bool SP2 = false>
; __device__ __forceinline__ void gemm_phase(PG8_LAS unsigned char* lds, const Gemm g, const Sched& S, const Epi& E) {
;     ...
;         for (int t = 0; t < nt; t += 2) {
;     ...
;             PG8_LDA(At, 1, 1); PG8_STAGE(PG8_SB(1, 0), b3, voffB); PG8_STAGE(PG8_SB(1, 1), b3 + hstepB, voffB); PG8_STAGE(PG8_SA(1, 0), a3, voffA);
;             PG8_WAIT_V(8); PG8_WAIT_L(0); PG8_BAR; PG8_MMA(1, 0, At, B0); PG8_MMA(1, 1, At, B1); PG8_BAR; PG8_SCHED;
	s_add_i32 s34, s64, s45
	v_lshl_add_u64 v[154:155], v[154:155], 0, s[18:19]
	s_mov_b32 m0, s34
	ds_read_b128 v[188:191], v161 offset:49152
	ds_read_b128 v[192:195], v161 offset:50176
	ds_read_b128 v[196:199], v161 offset:51200
	ds_read_b128 v[200:203], v161 offset:52224
	ds_read_b128 v[204:207], v161 offset:53248
	ds_read_b128 v[208:211], v161 offset:54272
	ds_read_b128 v[212:215], v161 offset:55296
	ds_read_b128 v[216:219], v161 offset:56320
	global_load_lds_dwordx4 v[154:155], off
	s_add_i32 m0, s34, 0x2000
	s_add_u32 s30, s30, 0x80080
	v_lshl_add_u64 v[154:155], v[220:221], 0, s[18:19]
	s_addc_u32 s31, s31, 0
	s_add_i32 s34, s65, s45
	global_load_lds_dwordx4 v[154:155], off
	v_lshl_add_u64 v[154:155], s[30:31], 0, v[130:131]
	s_mov_b32 m0, s34
	s_nop 0
	global_load_lds_dwordx4 v[154:155], off
	v_lshl_add_u64 v[154:155], s[30:31], 0, v[134:135]
	s_add_i32 m0, s34, 0x2000
	s_nop 0
	global_load_lds_dwordx4 v[154:155], off
	v_lshl_add_u64 v[154:155], v[222:223], 0, s[18:19]
	s_mov_b32 m0, s58
	s_nop 0
	global_load_lds_dwordx4 v[154:155], off
	v_lshl_add_u64 v[154:155], v[224:225], 0, s[18:19]
	s_mov_b32 m0, s59
	s_nop 0
	global_load_lds_dwordx4 v[154:155], off
	s_waitcnt vmcnt(8)
	s_waitcnt lgkmcnt(0)
	s_barrier
	s_waitcnt lgkmcnt(0)
	v_mfma_f32_16x16x32_bf16 v[60:63], v[146:149], v[188:191], v[60:63]
	v_mfma_f32_16x16x32_bf16 v[56:59], v[164:167], v[188:191], v[56:59]
	v_mfma_f32_16x16x32_bf16 v[44:47], v[146:149], v[196:199], v[44:47]
	v_mfma_f32_16x16x32_bf16 v[40:43], v[164:167], v[196:199], v[40:43]
	v_mfma_f32_16x16x32_bf16 v[28:31], v[146:149], v[204:207], v[28:31]
	v_mfma_f32_16x16x32_bf16 v[24:27], v[164:167], v[204:207], v[24:27]
	v_mfma_f32_16x16x32_bf16 v[12:15], v[146:149], v[212:215], v[12:15]
	v_mfma_f32_16x16x32_bf16 v[8:11], v[164:167], v[212:215], v[8:11]
	v_mfma_f32_16x16x32_bf16 v[60:63], v[150:153], v[192:195], v[60:63]
	v_mfma_f32_16x16x32_bf16 v[56:59], v[168:171], v[192:195], v[56:59]
	v_mfma_f32_16x16x32_bf16 v[44:47], v[150:153], v[200:203], v[44:47]
	v_mfma_f32_16x16x32_bf16 v[40:43], v[168:171], v[200:203], v[40:43]
	v_mfma_f32_16x16x32_bf16 v[28:31], v[150:153], v[208:211], v[28:31]
	v_mfma_f32_16x16x32_bf16 v[24:27], v[168:171], v[208:211], v[24:27]
	v_mfma_f32_16x16x32_bf16 v[12:15], v[150:153], v[216:219], v[12:15]
	v_mfma_f32_16x16x32_bf16 v[8:11], v[168:171], v[216:219], v[8:11]
	v_mfma_f32_16x16x32_bf16 v[52:55], v[172:175], v[188:191], v[52:55]
	v_mfma_f32_16x16x32_bf16 v[48:51], v[180:183], v[188:191], v[48:51]
	v_mfma_f32_16x16x32_bf16 v[36:39], v[172:175], v[196:199], v[36:39]
	v_mfma_f32_16x16x32_bf16 v[32:35], v[180:183], v[196:199], v[32:35]
	v_mfma_f32_16x16x32_bf16 v[20:23], v[172:175], v[204:207], v[20:23]
	v_mfma_f32_16x16x32_bf16 v[16:19], v[180:183], v[204:207], v[16:19]
	v_mfma_f32_16x16x32_bf16 v[4:7], v[172:175], v[212:215], v[4:7]
	v_mfma_f32_16x16x32_bf16 v[0:3], v[180:183], v[212:215], v[0:3]
	v_mfma_f32_16x16x32_bf16 v[52:55], v[176:179], v[192:195], v[52:55]
	v_mfma_f32_16x16x32_bf16 v[48:51], v[184:187], v[192:195], v[48:51]
	v_mfma_f32_16x16x32_bf16 v[36:39], v[176:179], v[200:203], v[36:39]
	v_mfma_f32_16x16x32_bf16 v[32:35], v[184:187], v[200:203], v[32:35]
	v_mfma_f32_16x16x32_bf16 v[20:23], v[176:179], v[208:211], v[20:23]
	v_mfma_f32_16x16x32_bf16 v[16:19], v[184:187], v[208:211], v[16:19]
	v_mfma_f32_16x16x32_bf16 v[4:7], v[176:179], v[216:219], v[4:7]
	v_mfma_f32_16x16x32_bf16 v[0:3], v[184:187], v[216:219], v[0:3]
	s_barrier
	s_add_u32 s41, s41, 0x100
	s_addc_u32 s42, s42, 0
	s_add_u32 s12, s12, 0x100
	s_addc_u32 s13, s13, 0
	s_cmp_ge_i32 s43, s56
	s_mov_b32 s30, s43
	s_cbranch_scc0 .LBB0_86
	s_setprio 0

; template <class Epi, class Sched, bool ALIGN_EPI = false, bool SP2 = false>
; __device__ __forceinline__ void gemm_phase(PG8_LAS unsigned char* lds, const Gemm g, const Sched& S, const Epi& E) {
;     ...
;         if (!has_next) break;
; #pragma unroll
;         for (int a = 0; a < 2; ++a)
; #pragma unroll
;             for (int b = 0; b < 2; ++b)
; #pragma unroll
;                 for (int m = 0; m < 4; ++m)
; #pragma unroll
;                     for (int n = 0; n < 2; ++n) acc[a][b][m][n] = (f32x4){0.f, 0.f, 0.f, 0.f};
;         cur = nxt; cA = nA; cB = nB; ++ui;
.LBB0_252:
	s_add_i32 s55, s55, 1
	s_mul_i32 s28, s55, s33
	s_add_i32 s28, s28, s2
	s_mov_b32 s19, s64
	s_mov_b32 s30, s63
	s_and_b32 s64, s28, 7
	s_ashr_i32 s63, s28, 3
	s_cmp_lt_i32 s28, 32
	s_cselect_b64 s[34:35], -1, 0
	s_and_b64 s[28:29], s[34:35], exec
	s_cselect_b32 s30, s63, s30
	s_cselect_b32 s28, s64, s19
	s_ashr_i32 s31, s30, 31
	s_lshl_b64 s[44:45], s[30:31], 9
	s_add_u32 s19, s37, s44
	s_addc_u32 s44, s38, s45
	s_ashr_i32 s29, s28, 31
	s_lshl_b64 s[28:29], s[28:29], 19
	s_add_u32 s28, s19, s28
	s_addc_u32 s29, s44, s29
	s_lshl_b64 s[30:31], s[30:31], 17
	s_add_u32 s30, s39, s30
	v_mov_b32_e32 v127, 0
	s_addc_u32 s31, s46, s31
	s_and_b64 vcc, exec, s[4:5]
	v_mov_b32_e32 v126, v127
	v_mov_b32_e32 v125, v127
	v_mov_b32_e32 v124, v127
	v_mov_b32_e32 v123, v127
	v_mov_b32_e32 v122, v127
	v_mov_b32_e32 v121, v127
	v_mov_b32_e32 v120, v127
	v_mov_b32_e32 v111, v127
	v_mov_b32_e32 v110, v127
	v_mov_b32_e32 v109, v127
	v_mov_b32_e32 v108, v127
	v_mov_b32_e32 v107, v127
	v_mov_b32_e32 v106, v127
	v_mov_b32_e32 v105, v127
	v_mov_b32_e32 v104, v127
	v_mov_b32_e32 v95, v127
	v_mov_b32_e32 v94, v127
	v_mov_b32_e32 v93, v127
	v_mov_b32_e32 v92, v127
	v_mov_b32_e32 v91, v127
	v_mov_b32_e32 v90, v127
	v_mov_b32_e32 v89, v127
	v_mov_b32_e32 v88, v127
	v_mov_b32_e32 v79, v127
	v_mov_b32_e32 v78, v127
	v_mov_b32_e32 v77, v127
	v_mov_b32_e32 v76, v127
	v_mov_b32_e32 v75, v127
	v_mov_b32_e32 v74, v127
	v_mov_b32_e32 v73, v127
	v_mov_b32_e32 v72, v127
	v_mov_b32_e32 v119, v127
	v_mov_b32_e32 v118, v127
	v_mov_b32_e32 v117, v127
	v_mov_b32_e32 v116, v127
	v_mov_b32_e32 v115, v127
	v_mov_b32_e32 v114, v127
	v_mov_b32_e32 v113, v127
	v_mov_b32_e32 v112, v127
	v_mov_b32_e32 v103, v127
	v_mov_b32_e32 v102, v127
	v_mov_b32_e32 v101, v127
	v_mov_b32_e32 v100, v127
	v_mov_b32_e32 v99, v127
	v_mov_b32_e32 v98, v127
	v_mov_b32_e32 v97, v127
	v_mov_b32_e32 v96, v127
	v_mov_b32_e32 v87, v127
	v_mov_b32_e32 v86, v127
	v_mov_b32_e32 v85, v127
	v_mov_b32_e32 v84, v127
	v_mov_b32_e32 v83, v127
	v_mov_b32_e32 v82, v127
	v_mov_b32_e32 v81, v127
	v_mov_b32_e32 v80, v127
	v_mov_b32_e32 v71, v127
	v_mov_b32_e32 v70, v127
	v_mov_b32_e32 v69, v127
	v_mov_b32_e32 v68, v127
	v_mov_b32_e32 v67, v127
	v_mov_b32_e32 v66, v127
	v_mov_b32_e32 v65, v127
	v_mov_b32_e32 v64, v127
	v_mov_b32_e32 v63, v127
	v_mov_b32_e32 v62, v127
	v_mov_b32_e32 v61, v127
	v_mov_b32_e32 v60, v127
	v_mov_b32_e32 v59, v127
	v_mov_b32_e32 v58, v127
	v_mov_b32_e32 v57, v127
	v_mov_b32_e32 v56, v127
	v_mov_b32_e32 v47, v127
	v_mov_b32_e32 v46, v127
	v_mov_b32_e32 v45, v127
	v_mov_b32_e32 v44, v127
	v_mov_b32_e32 v43, v127
	v_mov_b32_e32 v42, v127
	v_mov_b32_e32 v41, v127
	v_mov_b32_e32 v40, v127
	v_mov_b32_e32 v31, v127
	v_mov_b32_e32 v30, v127
	v_mov_b32_e32 v29, v127
	v_mov_b32_e32 v28, v127
	v_mov_b32_e32 v27, v127
	v_mov_b32_e32 v26, v127
	v_mov_b32_e32 v25, v127
	v_mov_b32_e32 v24, v127
	v_mov_b32_e32 v15, v127
	v_mov_b32_e32 v14, v127
	v_mov_b32_e32 v13, v127
	v_mov_b32_e32 v12, v127
	v_mov_b32_e32 v11, v127
	v_mov_b32_e32 v10, v127
	v_mov_b32_e32 v9, v127
	v_mov_b32_e32 v8, v127
	v_mov_b32_e32 v55, v127
	v_mov_b32_e32 v54, v127
	v_mov_b32_e32 v53, v127
	v_mov_b32_e32 v52, v127
	v_mov_b32_e32 v51, v127
	v_mov_b32_e32 v50, v127
	v_mov_b32_e32 v49, v127
	v_mov_b32_e32 v48, v127
	v_mov_b32_e32 v39, v127
	v_mov_b32_e32 v38, v127
	v_mov_b32_e32 v37, v127
	v_mov_b32_e32 v36, v127
	v_mov_b32_e32 v35, v127
	v_mov_b32_e32 v34, v127
	v_mov_b32_e32 v33, v127
	v_mov_b32_e32 v32, v127
	v_mov_b32_e32 v23, v127
	v_mov_b32_e32 v22, v127
	v_mov_b32_e32 v21, v127
	v_mov_b32_e32 v20, v127
	v_mov_b32_e32 v19, v127
	v_mov_b32_e32 v18, v127
	v_mov_b32_e32 v17, v127
	v_mov_b32_e32 v16, v127
	v_mov_b32_e32 v7, v127
	v_mov_b32_e32 v6, v127
	v_mov_b32_e32 v5, v127
	v_mov_b32_e32 v4, v127
	v_mov_b32_e32 v3, v127
	v_mov_b32_e32 v2, v127
	v_mov_b32_e32 v1, v127
	v_mov_b32_e32 v0, v127
	s_cbranch_vccnz .LBB0_255
	s_and_b64 s[44:45], s[34:35], exec
	s_cselect_b32 s19, s29, s43
	s_cselect_b32 s65, s28, s42
	s_cselect_b32 s66, s31, s41
	s_cselect_b32 s67, s30, s40
	s_add_u32 s68, s40, 0x100
	s_addc_u32 s69, s41, 0
	s_add_u32 s40, s42, 0x40080
	s_addc_u32 s41, s43, 0
	s_mov_b32 s42, 0
	v_readfirstlane_b32 s32, v227
	s_nop 3
	s_lshr_b32 s32, s32, 6
	s_cmp_ge_u32 s32, 4
	s_cbranch_scc0 .Lprio_1
	s_setprio 1
; #define PG8_STAGE(bufoff, gbase, voff) do { _Pragma("unroll") for (int _i = 0; _i < 2; ++_i) \
;         __builtin_amdgcn_global_load_lds((const unsigned*)((const char*)(gbase) + (voff)[_i]), (PG8_LAS unsigned*)(lds + (bufoff) + ldsw + _i * 8192), 16, 0, 0); } while (0)
; #define PG8_LDA(dst, b, h) do { _Pragma("unroll") for (int m = 0; m < 4; ++m) _Pragma("unroll") for (int k = 0; k < 2; ++k) dst[m][k] = *(const PG8_LAS bf16x8*)(lds + PG8_SA(b, h) + aoff + m * 2048 + k * 1024); } while (0)
; #define PG8_LDB(dst, b, h) do { _Pragma("unroll") for (int n = 0; n < 2; ++n) _Pragma("unroll") for (int k = 0; k < 2; ++k) dst[n][k] = *(const PG8_LAS bf16x8*)(lds + PG8_SB(b, h) + boff + n * 2048 + k * 1024); } while (0)
; #define PG8_MMA(ai, bj, At, Bt) do { __builtin_amdgcn_s_setprio(1); _Pragma("unroll") for (int m = 0; m < 4; ++m) _Pragma("unroll") for (int n = 0; n < 2; ++n) _Pragma("unroll") for (int k = 0; k < 2; ++k) \
;         acc[ai][bj][m][n] = __builtin_amdgcn_mfma_f32_16x16x32_bf16(Bt[n][k], At[m][k], acc[ai][bj][m][n], 0, 0, 0); __builtin_amdgcn_s_setprio(0); } while (0)
; #define PG8_WAIT_V(n) asm volatile("s_waitcnt vmcnt(" #n ")" ::: "memory")
; #define PG8_WAIT_L(n) asm volatile("s_waitcnt lgkmcnt(" #n ")" ::: "memory")
; #define PG8_BAR __builtin_amdgcn_s_barrier()
; #define PG8_SCHED __builtin_amdgcn_sched_barrier(0)
; template <class Epi, class Sched, bool ALIGN_EPI = false, bool SP2 = false>
; __device__ __forceinline__ void gemm_phase(PG8_LAS unsigned char* lds, const Gemm g, const Sched& S, const Epi& E) {
;     ...
;             PG8_LDB(B0, 0, 0); PG8_LDB(B1, 0, 1); PG8_SCHED; PG8_LDA(At, 0, 0); PG8_STAGE(PG8_SA(1, 1), a1 + hstepA, voffA);
;             PG8_WAIT_V(8); PG8_WAIT_L(0); PG8_BAR; PG8_MMA(0, 0, At, B0); PG8_MMA(0, 1, At, B1); PG8_BAR; PG8_SCHED;
;             PG8_LDA(At, 0, 1); PG8_STAGE(PG8_SB(0, 0), b2, voffB); PG8_STAGE(PG8_SB(0, 1), b2 + hstepB, voffB); PG8_STAGE(PG8_SA(0, 0), a2, voffA);
.Lprio_1:
.LBB0_254:
	ds_read_b128 v[148:151], v144
	ds_read_b128 v[152:155], v144 offset:1024
	ds_read_b128 v[156:159], v144 offset:2048
	ds_read_b128 v[160:163], v144 offset:3072
	ds_read_b128 v[164:167], v145
	ds_read_b128 v[168:171], v145 offset:1024
	ds_read_b128 v[172:175], v145 offset:2048
	ds_read_b128 v[176:179], v145 offset:3072
	s_add_i32 s70, s42, 2
	s_add_u32 s43, s40, 0xfffc0080
	s_addc_u32 s44, s41, -1
	s_cmp_eq_u32 s56, s42
	s_cselect_b32 s42, s67, s68
	s_cselect_b32 s45, s19, s44
	s_cselect_b32 s44, s65, s43
	s_cselect_b32 s43, s66, s69
	v_lshl_add_u64 v[212:213], s[40:41], 0, v[138:139]
	s_add_i32 m0, s48, 0xc000
	ds_read_b128 v[180:183], v146
	ds_read_b128 v[184:187], v146 offset:1024
	ds_read_b128 v[188:191], v146 offset:2048
	ds_read_b128 v[192:195], v146 offset:3072
	ds_read_b128 v[196:199], v146 offset:4096
	ds_read_b128 v[200:203], v146 offset:5120
	ds_read_b128 v[204:207], v146 offset:6144
	ds_read_b128 v[208:211], v146 offset:7168
	global_load_lds_dwordx4 v[212:213], off
	v_lshl_add_u64 v[212:213], s[40:41], 0, v[136:137]
	s_add_i32 m0, s48, 0xe000
	s_nop 0
	global_load_lds_dwordx4 v[212:213], off
	s_waitcnt vmcnt(8)
	s_waitcnt lgkmcnt(0)
	s_barrier
	s_waitcnt lgkmcnt(0)
	v_mfma_f32_16x16x32_bf16 v[124:127], v[148:151], v[180:183], v[124:127]
	v_mfma_f32_16x16x32_bf16 v[120:123], v[156:159], v[180:183], v[120:123]
	v_mfma_f32_16x16x32_bf16 v[108:111], v[148:151], v[188:191], v[108:111]
	v_mfma_f32_16x16x32_bf16 v[104:107], v[156:159], v[188:191], v[104:107]
	v_mfma_f32_16x16x32_bf16 v[92:95], v[148:151], v[196:199], v[92:95]
	v_mfma_f32_16x16x32_bf16 v[88:91], v[156:159], v[196:199], v[88:91]
	v_mfma_f32_16x16x32_bf16 v[76:79], v[148:151], v[204:207], v[76:79]
	v_mfma_f32_16x16x32_bf16 v[72:75], v[156:159], v[204:207], v[72:75]
	v_mfma_f32_16x16x32_bf16 v[124:127], v[152:155], v[184:187], v[124:127]
	v_mfma_f32_16x16x32_bf16 v[120:123], v[160:163], v[184:187], v[120:123]
	v_mfma_f32_16x16x32_bf16 v[108:111], v[152:155], v[192:195], v[108:111]
	v_mfma_f32_16x16x32_bf16 v[104:107], v[160:163], v[192:195], v[104:107]
	v_mfma_f32_16x16x32_bf16 v[92:95], v[152:155], v[200:203], v[92:95]
	v_mfma_f32_16x16x32_bf16 v[88:91], v[160:163], v[200:203], v[88:91]
	v_mfma_f32_16x16x32_bf16 v[76:79], v[152:155], v[208:211], v[76:79]
	v_mfma_f32_16x16x32_bf16 v[72:75], v[160:163], v[208:211], v[72:75]
	v_mfma_f32_16x16x32_bf16 v[116:119], v[164:167], v[180:183], v[116:119]
	v_mfma_f32_16x16x32_bf16 v[112:115], v[172:175], v[180:183], v[112:115]
	v_mfma_f32_16x16x32_bf16 v[100:103], v[164:167], v[188:191], v[100:103]
	v_mfma_f32_16x16x32_bf16 v[96:99], v[172:175], v[188:191], v[96:99]
	v_mfma_f32_16x16x32_bf16 v[84:87], v[164:167], v[196:199], v[84:87]
	v_mfma_f32_16x16x32_bf16 v[80:83], v[172:175], v[196:199], v[80:83]
	v_mfma_f32_16x16x32_bf16 v[68:71], v[164:167], v[204:207], v[68:71]
	v_mfma_f32_16x16x32_bf16 v[64:67], v[172:175], v[204:207], v[64:67]
	v_mfma_f32_16x16x32_bf16 v[116:119], v[168:171], v[184:187], v[116:119]
	v_mfma_f32_16x16x32_bf16 v[112:115], v[176:179], v[184:187], v[112:115]
	v_mfma_f32_16x16x32_bf16 v[100:103], v[168:171], v[192:195], v[100:103]
	v_mfma_f32_16x16x32_bf16 v[96:99], v[176:179], v[192:195], v[96:99]
	v_mfma_f32_16x16x32_bf16 v[84:87], v[168:171], v[200:203], v[84:87]
	v_mfma_f32_16x16x32_bf16 v[80:83], v[176:179], v[200:203], v[80:83]
	v_mfma_f32_16x16x32_bf16 v[68:71], v[168:171], v[208:211], v[68:71]
	v_mfma_f32_16x16x32_bf16 v[64:67], v[176:179], v[208:211], v[64:67]
	s_barrier
	s_add_i32 s71, s58, s47
	v_lshl_add_u64 v[212:213], s[42:43], 0, v[132:133]
	s_mov_b32 m0, s71
	ds_read_b128 v[180:183], v146 offset:16384
	ds_read_b128 v[184:187], v146 offset:17408
	ds_read_b128 v[188:191], v146 offset:18432
	ds_read_b128 v[192:195], v146 offset:19456
	ds_read_b128 v[196:199], v146 offset:20480
	ds_read_b128 v[200:203], v146 offset:21504
	ds_read_b128 v[204:207], v146 offset:22528
	ds_read_b128 v[208:211], v146 offset:23552
	global_load_lds_dwordx4 v[212:213], off
	s_add_i32 m0, s71, 0x2000
	s_add_u32 s72, s42, 0x10000
	v_lshl_add_u64 v[214:215], s[42:43], 0, v[128:129]
	s_addc_u32 s73, s43, 0
	s_add_i32 s71, s59, s47
	global_load_lds_dwordx4 v[214:215], off
	v_lshl_add_u64 v[216:217], s[72:73], 0, v[132:133]
	s_mov_b32 m0, s71
	v_lshl_add_u64 v[218:219], s[44:45], 0, v[130:131]
	global_load_lds_dwordx4 v[216:217], off
	v_lshl_add_u64 v[216:217], s[72:73], 0, v[128:129]
	s_add_i32 m0, s71, 0x2000
	s_nop 0
	global_load_lds_dwordx4 v[216:217], off
	v_lshl_add_u64 v[216:217], s[44:45], 0, v[134:135]
	s_mov_b32 m0, s48
	s_nop 0
	global_load_lds_dwordx4 v[216:217], off
	s_mov_b32 m0, s49
	s_nop 0
	global_load_lds_dwordx4 v[218:219], off
	s_waitcnt vmcnt(8)
	s_waitcnt lgkmcnt(0)
	s_barrier
; #define PG8_STAGE(bufoff, gbase, voff) do { _Pragma("unroll") for (int _i = 0; _i < 2; ++_i) \
;         __builtin_amdgcn_global_load_lds((const unsigned*)((const char*)(gbase) + (voff)[_i]), (PG8_LAS unsigned*)(lds + (bufoff) + ldsw + _i * 8192), 16, 0, 0); } while (0)
; #define PG8_LDA(dst, b, h) do { _Pragma("unroll") for (int m = 0; m < 4; ++m) _Pragma("unroll") for (int k = 0; k < 2; ++k) dst[m][k] = *(const PG8_LAS bf16x8*)(lds + PG8_SA(b, h) + aoff + m * 2048 + k * 1024); } while (0)
; #define PG8_LDB(dst, b, h) do { _Pragma("unroll") for (int n = 0; n < 2; ++n) _Pragma("unroll") for (int k = 0; k < 2; ++k) dst[n][k] = *(const PG8_LAS bf16x8*)(lds + PG8_SB(b, h) + boff + n * 2048 + k * 1024); } while (0)
; #define PG8_MMA(ai, bj, At, Bt) do { __builtin_amdgcn_s_setprio(1); _Pragma("unroll") for (int m = 0; m < 4; ++m) _Pragma("unroll") for (int n = 0; n < 2; ++n) _Pragma("unroll") for (int k = 0; k < 2; ++k) \
;         acc[ai][bj][m][n] = __builtin_amdgcn_mfma_f32_16x16x32_bf16(Bt[n][k], At[m][k], acc[ai][bj][m][n], 0, 0, 0); __builtin_amdgcn_s_setprio(0); } while (0)
; #define PG8_WAIT_V(n) asm volatile("s_waitcnt vmcnt(" #n ")" ::: "memory")
; #define PG8_WAIT_L(n) asm volatile("s_waitcnt lgkmcnt(" #n ")" ::: "memory")
; #define PG8_BAR __builtin_amdgcn_s_barrier()
; #define PG8_SCHED __builtin_amdgcn_sched_barrier(0)
; template <class Epi, class Sched, bool ALIGN_EPI = false, bool SP2 = false>
; __device__ __forceinline__ void gemm_phase(PG8_LAS unsigned char* lds, const Gemm g, const Sched& S, const Epi& E) {
;     ...
;             PG8_WAIT_V(8); PG8_WAIT_L(0); PG8_BAR; PG8_MMA(1, 0, At, B0); PG8_MMA(1, 1, At, B1); PG8_BAR; PG8_SCHED;
;             PG8_LDB(B0, 1, 0); PG8_LDB(B1, 1, 1); PG8_SCHED; PG8_LDA(At, 1, 0); PG8_STAGE(PG8_SA(0, 1), a2 + hstepA, voffA);
;             PG8_WAIT_V(8); PG8_WAIT_L(0); PG8_BAR; PG8_MMA(0, 0, At, B0); PG8_MMA(0, 1, At, B1); PG8_BAR; PG8_SCHED;
	s_waitcnt lgkmcnt(0)
	v_mfma_f32_16x16x32_bf16 v[60:63], v[148:151], v[180:183], v[60:63]
	v_mfma_f32_16x16x32_bf16 v[56:59], v[156:159], v[180:183], v[56:59]
	v_mfma_f32_16x16x32_bf16 v[44:47], v[148:151], v[188:191], v[44:47]
	v_mfma_f32_16x16x32_bf16 v[40:43], v[156:159], v[188:191], v[40:43]
	v_mfma_f32_16x16x32_bf16 v[28:31], v[148:151], v[196:199], v[28:31]
	v_mfma_f32_16x16x32_bf16 v[24:27], v[156:159], v[196:199], v[24:27]
	v_mfma_f32_16x16x32_bf16 v[12:15], v[148:151], v[204:207], v[12:15]
	v_mfma_f32_16x16x32_bf16 v[8:11], v[156:159], v[204:207], v[8:11]
	v_mfma_f32_16x16x32_bf16 v[60:63], v[152:155], v[184:187], v[60:63]
	v_mfma_f32_16x16x32_bf16 v[56:59], v[160:163], v[184:187], v[56:59]
	v_mfma_f32_16x16x32_bf16 v[44:47], v[152:155], v[192:195], v[44:47]
	v_mfma_f32_16x16x32_bf16 v[40:43], v[160:163], v[192:195], v[40:43]
	v_mfma_f32_16x16x32_bf16 v[28:31], v[152:155], v[200:203], v[28:31]
	v_mfma_f32_16x16x32_bf16 v[24:27], v[160:163], v[200:203], v[24:27]
	v_mfma_f32_16x16x32_bf16 v[12:15], v[152:155], v[208:211], v[12:15]
	v_mfma_f32_16x16x32_bf16 v[8:11], v[160:163], v[208:211], v[8:11]
	v_mfma_f32_16x16x32_bf16 v[52:55], v[164:167], v[180:183], v[52:55]
	v_mfma_f32_16x16x32_bf16 v[48:51], v[172:175], v[180:183], v[48:51]
	v_mfma_f32_16x16x32_bf16 v[36:39], v[164:167], v[188:191], v[36:39]
	v_mfma_f32_16x16x32_bf16 v[32:35], v[172:175], v[188:191], v[32:35]
	v_mfma_f32_16x16x32_bf16 v[20:23], v[164:167], v[196:199], v[20:23]
	v_mfma_f32_16x16x32_bf16 v[16:19], v[172:175], v[196:199], v[16:19]
	v_mfma_f32_16x16x32_bf16 v[4:7], v[164:167], v[204:207], v[4:7]
	v_mfma_f32_16x16x32_bf16 v[0:3], v[172:175], v[204:207], v[0:3]
	v_mfma_f32_16x16x32_bf16 v[52:55], v[168:171], v[184:187], v[52:55]
	v_mfma_f32_16x16x32_bf16 v[48:51], v[176:179], v[184:187], v[48:51]
	v_mfma_f32_16x16x32_bf16 v[36:39], v[168:171], v[192:195], v[36:39]
	v_mfma_f32_16x16x32_bf16 v[32:35], v[176:179], v[192:195], v[32:35]
	v_mfma_f32_16x16x32_bf16 v[20:23], v[168:171], v[200:203], v[20:23]
	v_mfma_f32_16x16x32_bf16 v[16:19], v[176:179], v[200:203], v[16:19]
	v_mfma_f32_16x16x32_bf16 v[4:7], v[168:171], v[208:211], v[4:7]
	v_mfma_f32_16x16x32_bf16 v[0:3], v[176:179], v[208:211], v[0:3]
	s_barrier
	s_add_i32 s71, 0, 0x18000
	v_add_u32_e32 v147, s71, v142
	s_add_i32 s72, 0, 0x1c000
	ds_read_b128 v[148:151], v147
	ds_read_b128 v[152:155], v147 offset:1024
	ds_read_b128 v[156:159], v147 offset:2048
	ds_read_b128 v[160:163], v147 offset:3072
	v_add_u32_e32 v147, s72, v142
	ds_read_b128 v[164:167], v147
	ds_read_b128 v[168:171], v147 offset:1024
	ds_read_b128 v[172:175], v147 offset:2048
	ds_read_b128 v[176:179], v147 offset:3072
	s_add_u32 s44, s44, 0x40000
	s_addc_u32 s45, s45, 0
	s_mov_b32 m0, s50
	v_lshl_add_u64 v[220:221], s[44:45], 0, v[134:135]
	ds_read_b128 v[180:183], v146 offset:32768
	ds_read_b128 v[184:187], v146 offset:33792
	ds_read_b128 v[188:191], v146 offset:34816
	ds_read_b128 v[192:195], v146 offset:35840
	ds_read_b128 v[196:199], v146 offset:36864
	ds_read_b128 v[200:203], v146 offset:37888
	ds_read_b128 v[204:207], v146 offset:38912
	ds_read_b128 v[208:211], v146 offset:39936
	global_load_lds_dwordx4 v[220:221], off
	v_lshl_add_u64 v[220:221], s[44:45], 0, v[130:131]
	s_mov_b32 m0, s51
	s_nop 0
	global_load_lds_dwordx4 v[220:221], off
	s_waitcnt vmcnt(8)
	s_waitcnt lgkmcnt(0)
	s_barrier
	s_waitcnt lgkmcnt(0)
	v_mfma_f32_16x16x32_bf16 v[124:127], v[148:151], v[180:183], v[124:127]
	v_mfma_f32_16x16x32_bf16 v[120:123], v[156:159], v[180:183], v[120:123]
	v_mfma_f32_16x16x32_bf16 v[108:111], v[148:151], v[188:191], v[108:111]
	v_mfma_f32_16x16x32_bf16 v[104:107], v[156:159], v[188:191], v[104:107]
	v_mfma_f32_16x16x32_bf16 v[92:95], v[148:151], v[196:199], v[92:95]
	v_mfma_f32_16x16x32_bf16 v[88:91], v[156:159], v[196:199], v[88:91]
	v_mfma_f32_16x16x32_bf16 v[76:79], v[148:151], v[204:207], v[76:79]
	v_mfma_f32_16x16x32_bf16 v[72:75], v[156:159], v[204:207], v[72:75]
	v_mfma_f32_16x16x32_bf16 v[124:127], v[152:155], v[184:187], v[124:127]
	v_mfma_f32_16x16x32_bf16 v[120:123], v[160:163], v[184:187], v[120:123]
	v_mfma_f32_16x16x32_bf16 v[108:111], v[152:155], v[192:195], v[108:111]
	v_mfma_f32_16x16x32_bf16 v[104:107], v[160:163], v[192:195], v[104:107]
	v_mfma_f32_16x16x32_bf16 v[92:95], v[152:155], v[200:203], v[92:95]
	v_mfma_f32_16x16x32_bf16 v[88:91], v[160:163], v[200:203], v[88:91]
	v_mfma_f32_16x16x32_bf16 v[76:79], v[152:155], v[208:211], v[76:79]
	v_mfma_f32_16x16x32_bf16 v[72:75], v[160:163], v[208:211], v[72:75]
	v_mfma_f32_16x16x32_bf16 v[116:119], v[164:167], v[180:183], v[116:119]
	v_mfma_f32_16x16x32_bf16 v[112:115], v[172:175], v[180:183], v[112:115]
	v_mfma_f32_16x16x32_bf16 v[100:103], v[164:167], v[188:191], v[100:103]
	v_mfma_f32_16x16x32_bf16 v[96:99], v[172:175], v[188:191], v[96:99]
	v_mfma_f32_16x16x32_bf16 v[84:87], v[164:167], v[196:199], v[84:87]
	v_mfma_f32_16x16x32_bf16 v[80:83], v[172:175], v[196:199], v[80:83]
	v_mfma_f32_16x16x32_bf16 v[68:71], v[164:167], v[204:207], v[68:71]
	v_mfma_f32_16x16x32_bf16 v[64:67], v[172:175], v[204:207], v[64:67]
	v_mfma_f32_16x16x32_bf16 v[116:119], v[168:171], v[184:187], v[116:119]
	v_mfma_f32_16x16x32_bf16 v[112:115], v[176:179], v[184:187], v[112:115]
	v_mfma_f32_16x16x32_bf16 v[100:103], v[168:171], v[192:195], v[100:103]
	v_mfma_f32_16x16x32_bf16 v[96:99], v[176:179], v[192:195], v[96:99]
	v_mfma_f32_16x16x32_bf16 v[84:87], v[168:171], v[200:203], v[84:87]
	v_mfma_f32_16x16x32_bf16 v[80:83], v[176:179], v[200:203], v[80:83]
	v_mfma_f32_16x16x32_bf16 v[68:71], v[168:171], v[208:211], v[68:71]
	v_mfma_f32_16x16x32_bf16 v[64:67], v[176:179], v[208:211], v[64:67]
	s_barrier
; #define PG8_STAGE(bufoff, gbase, voff) do { _Pragma("unroll") for (int _i = 0; _i < 2; ++_i) \
;         __builtin_amdgcn_global_load_lds((const unsigned*)((const char*)(gbase) + (voff)[_i]), (PG8_LAS unsigned*)(lds + (bufoff) + ldsw + _i * 8192), 16, 0, 0); } while (0)
; #define PG8_LDA(dst, b, h) do { _Pragma("unroll") for (int m = 0; m < 4; ++m) _Pragma("unroll") for (int k = 0; k < 2; ++k) dst[m][k] = *(const PG8_LAS bf16x8*)(lds + PG8_SA(b, h) + aoff + m * 2048 + k * 1024); } while (0)
; #define PG8_MMA(ai, bj, At, Bt) do { __builtin_amdgcn_s_setprio(1); _Pragma("unroll") for (int m = 0; m < 4; ++m) _Pragma("unroll") for (int n = 0; n < 2; ++n) _Pragma("unroll") for (int k = 0; k < 2; ++k) \
;         acc[ai][bj][m][n] = __builtin_amdgcn_mfma_f32_16x16x32_bf16(Bt[n][k], At[m][k], acc[ai][bj][m][n], 0, 0, 0); __builtin_amdgcn_s_setprio(0); } while (0)
; #define PG8_WAIT_V(n) asm volatile("s_waitcnt vmcnt(" #n ")" ::: "memory")
; #define PG8_WAIT_L(n) asm volatile("s_waitcnt lgkmcnt(" #n ")" ::: "memory")
; #define PG8_BAR __builtin_amdgcn_s_barrier()
; #define PG8_SCHED __builtin_amdgcn_sched_barrier(0)
; template <class Epi, class Sched, bool ALIGN_EPI = false, bool SP2 = false>
; __device__ __forceinline__ void gemm_phase(PG8_LAS unsigned char* lds, const Gemm g, const Sched& S, const Epi& E) {
;     ...
;         for (int t = 0; t < nt; t += 2) {
;     ...
;             PG8_LDA(At, 1, 1); PG8_STAGE(PG8_SB(1, 0), b3, voffB); PG8_STAGE(PG8_SB(1, 1), b3 + hstepB, voffB); PG8_STAGE(PG8_SA(1, 0), a3, voffA);
;             PG8_WAIT_V(8); PG8_WAIT_L(0); PG8_BAR; PG8_MMA(1, 0, At, B0); PG8_MMA(1, 1, At, B1); PG8_BAR; PG8_SCHED;
	s_add_i32 s44, s71, s47
	v_lshl_add_u64 v[212:213], v[212:213], 0, s[8:9]
	s_mov_b32 m0, s44
	ds_read_b128 v[180:183], v146 offset:49152
	ds_read_b128 v[184:187], v146 offset:50176
	ds_read_b128 v[188:191], v146 offset:51200
	ds_read_b128 v[192:195], v146 offset:52224
	ds_read_b128 v[196:199], v146 offset:53248
	ds_read_b128 v[200:203], v146 offset:54272
	ds_read_b128 v[204:207], v146 offset:55296
	ds_read_b128 v[208:211], v146 offset:56320
	global_load_lds_dwordx4 v[212:213], off
	s_add_i32 m0, s44, 0x2000
	s_add_u32 s42, s42, 0x10080
	v_lshl_add_u64 v[212:213], v[214:215], 0, s[8:9]
	s_addc_u32 s43, s43, 0
	s_add_i32 s44, s72, s47
	global_load_lds_dwordx4 v[212:213], off
	v_lshl_add_u64 v[212:213], s[42:43], 0, v[132:133]
	s_mov_b32 m0, s44
	s_nop 0
	global_load_lds_dwordx4 v[212:213], off
	v_lshl_add_u64 v[212:213], s[42:43], 0, v[128:129]
	s_add_i32 m0, s44, 0x2000
	s_nop 0
	global_load_lds_dwordx4 v[212:213], off
	v_lshl_add_u64 v[212:213], v[216:217], 0, s[8:9]
	s_mov_b32 m0, s53
	s_nop 0
	global_load_lds_dwordx4 v[212:213], off
	v_lshl_add_u64 v[212:213], v[218:219], 0, s[8:9]
	s_mov_b32 m0, s54
	s_nop 0
	global_load_lds_dwordx4 v[212:213], off
	s_waitcnt vmcnt(8)
	s_waitcnt lgkmcnt(0)
	s_barrier
	s_waitcnt lgkmcnt(0)
	v_mfma_f32_16x16x32_bf16 v[60:63], v[148:151], v[180:183], v[60:63]
	v_mfma_f32_16x16x32_bf16 v[56:59], v[156:159], v[180:183], v[56:59]
	v_mfma_f32_16x16x32_bf16 v[44:47], v[148:151], v[188:191], v[44:47]
	v_mfma_f32_16x16x32_bf16 v[40:43], v[156:159], v[188:191], v[40:43]
	v_mfma_f32_16x16x32_bf16 v[28:31], v[148:151], v[196:199], v[28:31]
	v_mfma_f32_16x16x32_bf16 v[24:27], v[156:159], v[196:199], v[24:27]
	v_mfma_f32_16x16x32_bf16 v[12:15], v[148:151], v[204:207], v[12:15]
	v_mfma_f32_16x16x32_bf16 v[8:11], v[156:159], v[204:207], v[8:11]
	v_mfma_f32_16x16x32_bf16 v[60:63], v[152:155], v[184:187], v[60:63]
	v_mfma_f32_16x16x32_bf16 v[56:59], v[160:163], v[184:187], v[56:59]
	v_mfma_f32_16x16x32_bf16 v[44:47], v[152:155], v[192:195], v[44:47]
	v_mfma_f32_16x16x32_bf16 v[40:43], v[160:163], v[192:195], v[40:43]
	v_mfma_f32_16x16x32_bf16 v[28:31], v[152:155], v[200:203], v[28:31]
	v_mfma_f32_16x16x32_bf16 v[24:27], v[160:163], v[200:203], v[24:27]
	v_mfma_f32_16x16x32_bf16 v[12:15], v[152:155], v[208:211], v[12:15]
	v_mfma_f32_16x16x32_bf16 v[8:11], v[160:163], v[208:211], v[8:11]
	v_mfma_f32_16x16x32_bf16 v[52:55], v[164:167], v[180:183], v[52:55]
	v_mfma_f32_16x16x32_bf16 v[48:51], v[172:175], v[180:183], v[48:51]
	v_mfma_f32_16x16x32_bf16 v[36:39], v[164:167], v[188:191], v[36:39]
	v_mfma_f32_16x16x32_bf16 v[32:35], v[172:175], v[188:191], v[32:35]
	v_mfma_f32_16x16x32_bf16 v[20:23], v[164:167], v[196:199], v[20:23]
	v_mfma_f32_16x16x32_bf16 v[16:19], v[172:175], v[196:199], v[16:19]
	v_mfma_f32_16x16x32_bf16 v[4:7], v[164:167], v[204:207], v[4:7]
	v_mfma_f32_16x16x32_bf16 v[0:3], v[172:175], v[204:207], v[0:3]
	v_mfma_f32_16x16x32_bf16 v[52:55], v[168:171], v[184:187], v[52:55]
	v_mfma_f32_16x16x32_bf16 v[48:51], v[176:179], v[184:187], v[48:51]
	v_mfma_f32_16x16x32_bf16 v[36:39], v[168:171], v[192:195], v[36:39]
	v_mfma_f32_16x16x32_bf16 v[32:35], v[176:179], v[192:195], v[32:35]
	v_mfma_f32_16x16x32_bf16 v[20:23], v[168:171], v[200:203], v[20:23]
	v_mfma_f32_16x16x32_bf16 v[16:19], v[176:179], v[200:203], v[16:19]
	v_mfma_f32_16x16x32_bf16 v[4:7], v[168:171], v[208:211], v[4:7]
	v_mfma_f32_16x16x32_bf16 v[0:3], v[176:179], v[208:211], v[0:3]
	s_barrier
	s_add_u32 s68, s68, 0x100
	s_addc_u32 s69, s69, 0
	s_add_u32 s40, s40, 0x100
	s_addc_u32 s41, s41, 0
	s_cmp_ge_i32 s70, s52
	s_mov_b32 s42, s70
	s_cbranch_scc0 .LBB0_254
	s_setprio 0

; #define RT_(aw, pw, lo) ((lo ? bf_lo(aw) : bf_hi(aw)) * __builtin_amdgcn_rcpf(fmaxf(lo ? bf_lo(pw) : bf_hi(pw), 1e-30f)))
;     __device__ __forceinline__ void mid(f32x4 (&acc)[2][2][4][2], const Unit& u, int wr, int wc, int fr, int fq) const {
;         const int col0 = u.pn * BM + wc * 32 + 8 * fq, row0 = u.pm * BM + wr * 64 + fr;
;         unsigned long long ro_ = ((unsigned long long)row0 * 2048 + col0) * 2; asm volatile("" : "+v"(ro_));
;         const bf16_t* ga = (const bf16_t*)((const char*)GA + ro_); const bf16_t* gp = (const bf16_t*)((const char*)GP + ro_);
; #pragma unroll
;         for (int ai = 0; ai < 2; ++ai)
; #pragma unroll
;             for (int m = 0; m < 4; ++m)
; #pragma unroll
;                 for (int bj = 0; bj < 2; ++bj) { const size_t o_ = (size_t)(ai * HALF + m * 16) * 2048 + bj * HALF;
;                     const u32x4 a = *(const u32x4*)(ga + o_), p = *(const u32x4*)(gp + o_);
;     ...
;                     acc[ai][bj][m][0][0] *= RT_(a.x, p.x, 1); acc[ai][bj][m][0][1] *= RT_(a.x, p.x, 0); acc[ai][bj][m][0][2] *= RT_(a.y, p.y, 1); acc[ai][bj][m][0][3] *= RT_(a.y, p.y, 0);
;                     acc[ai][bj][m][1][0] *= RT_(a.z, p.z, 1); acc[ai][bj][m][1][1] *= RT_(a.z, p.z, 0); acc[ai][bj][m][1][2] *= RT_(a.w, p.w, 1); acc[ai][bj][m][1][3] *= RT_(a.w, p.w, 0);
;     ...
;                     asm volatile("" ::: "memory"); }
.LBB0_672:
	v_mov_b64_e32 v[128:129], v[180:181]
	s_waitcnt vmcnt(0)
	s_nop 0
	v_lshl_add_u64 v[182:183], s[12:13], 0, v[128:129]
	v_lshl_add_u64 v[184:185], s[10:11], 0, v[128:129]
	flat_load_dwordx4 v[136:139], v[182:183]
	flat_load_dwordx4 v[140:143], v[184:185]
	flat_load_dwordx4 v[150:153], v[182:183] offset:256
	flat_load_dwordx4 v[154:157], v[184:185] offset:256
	v_add_co_u32_e32 v144, vcc, s56, v184
	s_waitcnt vmcnt(0) lgkmcnt(0)
	v_lshlrev_b32_e32 v158, 16, v136
	v_addc_co_u32_e32 v145, vcc, 0, v185, vcc
	v_add_co_u32_e32 v148, vcc, s56, v182
	v_and_b32_e32 v159, 0xffff0000, v136
	s_nop 0
	v_addc_co_u32_e32 v149, vcc, 0, v183, vcc
	flat_load_dwordx4 v[128:131], v[144:145]
	flat_load_dwordx4 v[132:135], v[148:149]
	v_lshlrev_b32_e32 v146, 16, v140
	v_and_b32_e32 v147, 0xffff0000, v140
	v_lshlrev_b32_e32 v177, 16, v137
	v_and_b32_e32 v179, 0xffff0000, v137
	v_lshlrev_b32_e32 v136, 16, v141
	v_and_b32_e32 v137, 0xffff0000, v141
	v_lshlrev_b32_e32 v140, 16, v142
	v_and_b32_e32 v141, 0xffff0000, v142
	v_lshlrev_b32_e32 v142, 16, v139
	v_and_b32_e32 v194, 0xffff0000, v139
	v_lshlrev_b32_e32 v192, 16, v138
	v_and_b32_e32 v193, 0xffff0000, v138
	v_lshlrev_b32_e32 v138, 16, v143
	v_and_b32_e32 v139, 0xffff0000, v143
	v_max_f32_e32 v158, v158, v158
	v_max_f32_e32 v159, v159, v159
	v_max_f32_e32 v195, v142, v142
	v_max_f32_e32 v194, v194, v194
	v_lshlrev_b32_e32 v142, 16, v154
	v_and_b32_e32 v143, 0xffff0000, v154
	v_lshlrev_b32_e32 v154, 16, v151
	v_and_b32_e32 v198, 0xffff0000, v151
	v_lshlrev_b32_e32 v196, 16, v150
	v_and_b32_e32 v197, 0xffff0000, v150
	v_lshlrev_b32_e32 v150, 16, v155
	v_and_b32_e32 v151, 0xffff0000, v155
	v_max_f32_e32 v155, 0xda24260, v158
	v_max_f32_e32 v158, 0xda24260, v159
	v_max_f32_e32 v195, 0xda24260, v195
	v_max_f32_e32 v199, 0xda24260, v194
	v_max_f32_e32 v201, v154, v154
	v_max_f32_e32 v198, v198, v198
	v_rcp_f32_e32 v154, v155
	v_rcp_f32_e32 v155, v158
	v_rcp_f32_e32 v194, v195
	v_rcp_f32_e32 v195, v199
	v_max_f32_e32 v199, 0xda24260, v201
	v_max_f32_e32 v201, 0xda24260, v198
	v_rcp_f32_e32 v198, v199
	v_rcp_f32_e32 v199, v201
	v_max_f32_e32 v177, v177, v177
	v_max_f32_e32 v179, v179, v179
	v_max_f32_e32 v192, v192, v192
	v_pk_mul_f32 v[146:147], v[154:155], v[146:147]
	v_pk_mul_f32 v[138:139], v[194:195], v[138:139]
	v_max_f32_e32 v159, 0xda24260, v177
	v_max_f32_e32 v177, 0xda24260, v179
	v_max_f32_e32 v179, 0xda24260, v192
	v_max_f32_e32 v196, v196, v196
	v_max_f32_e32 v197, v197, v197
	v_pk_mul_f32 v[124:125], v[124:125], v[146:147]
	v_pk_mul_f32 v[122:123], v[122:123], v[138:139]
	v_pk_mul_f32 v[138:139], v[198:199], v[150:151]
	flat_load_dwordx4 v[144:147], v[144:145] offset:256
	s_nop 0
	flat_load_dwordx4 v[148:151], v[148:149] offset:256
	v_rcp_f32_e32 v158, v159
	v_rcp_f32_e32 v159, v177
	v_rcp_f32_e32 v192, v179
	v_max_f32_e32 v177, 0xda24260, v196
	v_max_f32_e32 v179, 0xda24260, v197
	v_rcp_f32_e32 v196, v177
	v_rcp_f32_e32 v197, v179
	v_pk_mul_f32 v[136:137], v[158:159], v[136:137]
	v_lshlrev_b32_e32 v200, 16, v152
	v_pk_mul_f32 v[126:127], v[126:127], v[136:137]
	v_pk_mul_f32 v[136:137], v[196:197], v[142:143]
	v_pk_mul_f32 v[118:119], v[118:119], v[138:139]
	v_pk_mul_f32 v[116:117], v[116:117], v[136:137]
	v_and_b32_e32 v137, 0xffff0000, v152
	v_max_f32_e32 v136, v200, v200
	v_max_f32_e32 v137, v137, v137
	v_max_f32_e32 v136, 0xda24260, v136
	v_max_f32_e32 v137, 0xda24260, v137
	v_rcp_f32_e32 v136, v136
	v_rcp_f32_e32 v137, v137
	v_lshlrev_b32_e32 v138, 16, v156
	v_and_b32_e32 v139, 0xffff0000, v156
	v_max_f32_e32 v193, v193, v193
	v_pk_mul_f32 v[136:137], v[136:137], v[138:139]
	v_lshlrev_b32_e32 v138, 16, v153
	v_and_b32_e32 v139, 0xffff0000, v153
	v_max_f32_e32 v138, v138, v138
	v_max_f32_e32 v139, v139, v139
	v_max_f32_e32 v138, 0xda24260, v138
	v_max_f32_e32 v139, 0xda24260, v139
	v_rcp_f32_e32 v138, v138
	v_rcp_f32_e32 v139, v139
	v_pk_mul_f32 v[112:113], v[112:113], v[136:137]
	v_lshlrev_b32_e32 v136, 16, v157
	v_and_b32_e32 v137, 0xffff0000, v157
	v_pk_mul_f32 v[136:137], v[138:139], v[136:137]
	s_waitcnt vmcnt(0) lgkmcnt(0)
	v_lshlrev_b32_e32 v138, 16, v132
	v_and_b32_e32 v132, 0xffff0000, v132
	v_max_f32_e32 v193, 0xda24260, v193
	v_max_f32_e32 v138, v138, v138
	v_max_f32_e32 v132, v132, v132
	v_rcp_f32_e32 v193, v193
	v_max_f32_e32 v138, 0xda24260, v138
	v_max_f32_e32 v132, 0xda24260, v132
	v_rcp_f32_e32 v138, v138
	v_rcp_f32_e32 v139, v132
	v_add_co_u32_e32 v154, vcc, s63, v184
	v_pk_mul_f32 v[140:141], v[192:193], v[140:141]
	s_nop 0
	v_addc_co_u32_e32 v155, vcc, 0, v185, vcc
	v_pk_mul_f32 v[114:115], v[114:115], v[136:137]
	v_lshlrev_b32_e32 v136, 16, v128
	v_and_b32_e32 v137, 0xffff0000, v128
	v_add_co_u32_e32 v156, vcc, s63, v182
	v_pk_mul_f32 v[120:121], v[120:121], v[140:141]
	v_pk_mul_f32 v[152:153], v[138:139], v[136:137]
	v_addc_co_u32_e32 v157, vcc, 0, v183, vcc
	flat_load_dwordx4 v[136:139], v[154:155]
	flat_load_dwordx4 v[140:143], v[156:157]
	v_lshlrev_b32_e32 v128, 16, v133
	v_max_f32_e32 v128, v128, v128
	v_max_f32_e32 v128, 0xda24260, v128
	v_rcp_f32_e32 v132, v128
	v_and_b32_e32 v128, 0xffff0000, v133
	v_max_f32_e32 v128, v128, v128
	v_max_f32_e32 v128, 0xda24260, v128
	v_rcp_f32_e32 v133, v128
	v_lshlrev_b32_e32 v128, 16, v129
	v_and_b32_e32 v129, 0xffff0000, v129
	v_pk_mul_f32 v[128:129], v[132:133], v[128:129]
	v_lshlrev_b32_e32 v132, 16, v134
	v_and_b32_e32 v133, 0xffff0000, v134
	v_max_f32_e32 v132, v132, v132
	v_max_f32_e32 v133, v133, v133
	v_max_f32_e32 v132, 0xda24260, v132
	v_max_f32_e32 v133, 0xda24260, v133
	v_rcp_f32_e32 v132, v132
	v_rcp_f32_e32 v133, v133
	v_pk_mul_f32 v[110:111], v[110:111], v[128:129]
	v_lshlrev_b32_e32 v128, 16, v130
; #define RT_(aw, pw, lo) ((lo ? bf_lo(aw) : bf_hi(aw)) * __builtin_amdgcn_rcpf(fmaxf(lo ? bf_lo(pw) : bf_hi(pw), 1e-30f)))
;     __device__ __forceinline__ void mid(f32x4 (&acc)[2][2][4][2], const Unit& u, int wr, int wc, int fr, int fq) const {
;         const int col0 = u.pn * BM + wc * 32 + 8 * fq, row0 = u.pm * BM + wr * 64 + fr;
;         unsigned long long ro_ = ((unsigned long long)row0 * 2048 + col0) * 2; asm volatile("" : "+v"(ro_));
;         const bf16_t* ga = (const bf16_t*)((const char*)GA + ro_); const bf16_t* gp = (const bf16_t*)((const char*)GP + ro_);
; #pragma unroll
;         for (int ai = 0; ai < 2; ++ai)
; #pragma unroll
;             for (int m = 0; m < 4; ++m)
; #pragma unroll
;                 for (int bj = 0; bj < 2; ++bj) { const size_t o_ = (size_t)(ai * HALF + m * 16) * 2048 + bj * HALF;
;                     const u32x4 a = *(const u32x4*)(ga + o_), p = *(const u32x4*)(gp + o_);
;     ...
;                     acc[ai][bj][m][0][0] *= RT_(a.x, p.x, 1); acc[ai][bj][m][0][1] *= RT_(a.x, p.x, 0); acc[ai][bj][m][0][2] *= RT_(a.y, p.y, 1); acc[ai][bj][m][0][3] *= RT_(a.y, p.y, 0);
;                     acc[ai][bj][m][1][0] *= RT_(a.z, p.z, 1); acc[ai][bj][m][1][1] *= RT_(a.z, p.z, 0); acc[ai][bj][m][1][2] *= RT_(a.w, p.w, 1); acc[ai][bj][m][1][3] *= RT_(a.w, p.w, 0);
;     ...
;                     asm volatile("" ::: "memory"); }
	v_and_b32_e32 v129, 0xffff0000, v130
	v_lshlrev_b32_e32 v130, 16, v135
	v_max_f32_e32 v130, v130, v130
	v_max_f32_e32 v130, 0xda24260, v130
	v_pk_mul_f32 v[128:129], v[132:133], v[128:129]
	v_rcp_f32_e32 v132, v130
	v_and_b32_e32 v130, 0xffff0000, v135
	v_max_f32_e32 v130, v130, v130
	v_max_f32_e32 v130, 0xda24260, v130
	v_rcp_f32_e32 v133, v130
	v_pk_mul_f32 v[104:105], v[104:105], v[128:129]
	v_lshlrev_b32_e32 v128, 16, v131
	v_and_b32_e32 v129, 0xffff0000, v131
	v_lshlrev_b32_e32 v130, 16, v148
	v_and_b32_e32 v131, 0xffff0000, v148
	v_max_f32_e32 v130, v130, v130
	v_max_f32_e32 v131, v131, v131
	v_max_f32_e32 v130, 0xda24260, v130
	v_max_f32_e32 v131, 0xda24260, v131
	v_rcp_f32_e32 v130, v130
	v_rcp_f32_e32 v131, v131
	v_pk_mul_f32 v[128:129], v[132:133], v[128:129]
	v_pk_mul_f32 v[108:109], v[108:109], v[152:153]
	v_pk_mul_f32 v[106:107], v[106:107], v[128:129]
	v_lshlrev_b32_e32 v128, 16, v144
	v_and_b32_e32 v129, 0xffff0000, v144
	v_pk_mul_f32 v[128:129], v[130:131], v[128:129]
	v_lshlrev_b32_e32 v130, 16, v149
	v_and_b32_e32 v131, 0xffff0000, v149
	v_max_f32_e32 v130, v130, v130
	v_max_f32_e32 v131, v131, v131
	v_max_f32_e32 v130, 0xda24260, v130
	v_max_f32_e32 v131, 0xda24260, v131
	v_rcp_f32_e32 v130, v130
	v_rcp_f32_e32 v131, v131
	v_pk_mul_f32 v[100:101], v[100:101], v[128:129]
	v_lshlrev_b32_e32 v128, 16, v145
	v_and_b32_e32 v129, 0xffff0000, v145
	v_pk_mul_f32 v[128:129], v[130:131], v[128:129]
	v_lshlrev_b32_e32 v130, 16, v150
	v_and_b32_e32 v131, 0xffff0000, v150
	v_max_f32_e32 v130, v130, v130
	v_max_f32_e32 v131, v131, v131
	v_max_f32_e32 v130, 0xda24260, v130
	v_max_f32_e32 v131, 0xda24260, v131
	v_rcp_f32_e32 v130, v130
	v_rcp_f32_e32 v131, v131
	flat_load_dwordx4 v[132:135], v[154:155] offset:256
	s_nop 0
	flat_load_dwordx4 v[152:155], v[156:157] offset:256
	v_pk_mul_f32 v[102:103], v[102:103], v[128:129]
	v_lshlrev_b32_e32 v128, 16, v146
	v_and_b32_e32 v129, 0xffff0000, v146
	v_pk_mul_f32 v[128:129], v[130:131], v[128:129]
	v_lshlrev_b32_e32 v130, 16, v151
	v_and_b32_e32 v131, 0xffff0000, v151
	v_max_f32_e32 v130, v130, v130
	v_max_f32_e32 v131, v131, v131
	v_max_f32_e32 v130, 0xda24260, v130
	v_max_f32_e32 v131, 0xda24260, v131
	v_rcp_f32_e32 v130, v130
	v_rcp_f32_e32 v131, v131
	v_pk_mul_f32 v[96:97], v[96:97], v[128:129]
	v_lshlrev_b32_e32 v128, 16, v147
	v_and_b32_e32 v129, 0xffff0000, v147
	v_pk_mul_f32 v[128:129], v[130:131], v[128:129]
	s_waitcnt vmcnt(0) lgkmcnt(0)
	v_lshlrev_b32_e32 v130, 16, v140
	v_and_b32_e32 v131, 0xffff0000, v140
	v_max_f32_e32 v130, v130, v130
	v_max_f32_e32 v131, v131, v131
	v_max_f32_e32 v130, 0xda24260, v130
	v_max_f32_e32 v131, 0xda24260, v131
	v_rcp_f32_e32 v130, v130
	v_rcp_f32_e32 v131, v131
	v_pk_mul_f32 v[98:99], v[98:99], v[128:129]
	v_lshlrev_b32_e32 v128, 16, v136
	v_and_b32_e32 v129, 0xffff0000, v136
	v_pk_mul_f32 v[148:149], v[130:131], v[128:129]
	v_lshlrev_b32_e32 v128, 16, v141
	v_max_f32_e32 v128, v128, v128
	v_max_f32_e32 v128, 0xda24260, v128
	v_rcp_f32_e32 v140, v128
	v_and_b32_e32 v128, 0xffff0000, v141
	v_add_co_u32_e32 v150, vcc, s64, v184
	v_max_f32_e32 v128, v128, v128
	s_nop 0
	v_addc_co_u32_e32 v151, vcc, 0, v185, vcc
	v_max_f32_e32 v128, 0xda24260, v128
	v_add_co_u32_e32 v156, vcc, s64, v182
	v_rcp_f32_e32 v141, v128
	s_nop 0
	v_addc_co_u32_e32 v157, vcc, 0, v183, vcc
	flat_load_dwordx4 v[128:131], v[150:151]
	flat_load_dwordx4 v[144:147], v[156:157]
	v_lshlrev_b32_e32 v136, 16, v137
	v_and_b32_e32 v137, 0xffff0000, v137
	v_pk_mul_f32 v[136:137], v[140:141], v[136:137]
	v_lshlrev_b32_e32 v140, 16, v142
	v_and_b32_e32 v141, 0xffff0000, v142
	v_max_f32_e32 v140, v140, v140
	v_max_f32_e32 v141, v141, v141
	v_max_f32_e32 v140, 0xda24260, v140
	v_max_f32_e32 v141, 0xda24260, v141
	v_rcp_f32_e32 v140, v140
	v_rcp_f32_e32 v141, v141
	v_pk_mul_f32 v[94:95], v[94:95], v[136:137]
	v_lshlrev_b32_e32 v136, 16, v138
	v_and_b32_e32 v137, 0xffff0000, v138
	v_lshlrev_b32_e32 v138, 16, v143
	v_max_f32_e32 v138, v138, v138
	v_max_f32_e32 v138, 0xda24260, v138
	v_pk_mul_f32 v[136:137], v[140:141], v[136:137]
	v_rcp_f32_e32 v140, v138
	v_and_b32_e32 v138, 0xffff0000, v143
	v_max_f32_e32 v138, v138, v138
	v_max_f32_e32 v138, 0xda24260, v138
	v_rcp_f32_e32 v141, v138
	v_pk_mul_f32 v[88:89], v[88:89], v[136:137]
	v_lshlrev_b32_e32 v136, 16, v139
	v_and_b32_e32 v137, 0xffff0000, v139
	v_pk_mul_f32 v[92:93], v[92:93], v[148:149]
	v_pk_mul_f32 v[136:137], v[140:141], v[136:137]
	flat_load_dwordx4 v[140:143], v[150:151] offset:256
	s_nop 0
	flat_load_dwordx4 v[148:151], v[156:157] offset:256
	v_pk_mul_f32 v[90:91], v[90:91], v[136:137]
	v_lshlrev_b32_e32 v136, 16, v132
	v_lshlrev_b32_e32 v138, 16, v152
	v_and_b32_e32 v139, 0xffff0000, v152
	v_max_f32_e32 v138, v138, v138
	v_max_f32_e32 v139, v139, v139
	v_max_f32_e32 v138, 0xda24260, v138
	v_max_f32_e32 v139, 0xda24260, v139
	v_rcp_f32_e32 v138, v138
	v_rcp_f32_e32 v139, v139
	v_and_b32_e32 v137, 0xffff0000, v132
	v_lshlrev_b32_e32 v132, 16, v153
	v_max_f32_e32 v132, v132, v132
	v_max_f32_e32 v132, 0xda24260, v132
	v_pk_mul_f32 v[136:137], v[138:139], v[136:137]
	v_rcp_f32_e32 v138, v132
	v_and_b32_e32 v132, 0xffff0000, v153
	v_max_f32_e32 v132, v132, v132
	v_max_f32_e32 v132, 0xda24260, v132
	v_rcp_f32_e32 v139, v132
	v_pk_mul_f32 v[84:85], v[84:85], v[136:137]
	v_lshlrev_b32_e32 v136, 16, v154
	v_and_b32_e32 v137, 0xffff0000, v154
	v_max_f32_e32 v136, v136, v136
	v_max_f32_e32 v137, v137, v137
	v_lshlrev_b32_e32 v132, 16, v133
	v_and_b32_e32 v133, 0xffff0000, v133
	v_max_f32_e32 v136, 0xda24260, v136
	v_max_f32_e32 v137, 0xda24260, v137
	v_pk_mul_f32 v[132:133], v[138:139], v[132:133]
	v_rcp_f32_e32 v136, v136
	v_rcp_f32_e32 v137, v137
	v_pk_mul_f32 v[86:87], v[86:87], v[132:133]
	v_lshlrev_b32_e32 v132, 16, v134
	v_and_b32_e32 v133, 0xffff0000, v134
	v_lshlrev_b32_e32 v134, 16, v155
	v_max_f32_e32 v134, v134, v134
	v_max_f32_e32 v134, 0xda24260, v134
	v_pk_mul_f32 v[132:133], v[136:137], v[132:133]
	v_rcp_f32_e32 v136, v134
	v_and_b32_e32 v134, 0xffff0000, v155
	v_max_f32_e32 v134, v134, v134
	v_max_f32_e32 v134, 0xda24260, v134
	v_rcp_f32_e32 v137, v134
	v_pk_mul_f32 v[80:81], v[80:81], v[132:133]
	v_lshlrev_b32_e32 v132, 16, v135
	v_and_b32_e32 v133, 0xffff0000, v135
	v_add_co_u32_e32 v154, vcc, s65, v184
	s_waitcnt vmcnt(0) lgkmcnt(0)
; #define RT_(aw, pw, lo) ((lo ? bf_lo(aw) : bf_hi(aw)) * __builtin_amdgcn_rcpf(fmaxf(lo ? bf_lo(pw) : bf_hi(pw), 1e-30f)))
;     __device__ __forceinline__ void mid(f32x4 (&acc)[2][2][4][2], const Unit& u, int wr, int wc, int fr, int fq) const {
;         const int col0 = u.pn * BM + wc * 32 + 8 * fq, row0 = u.pm * BM + wr * 64 + fr;
;         unsigned long long ro_ = ((unsigned long long)row0 * 2048 + col0) * 2; asm volatile("" : "+v"(ro_));
;         const bf16_t* ga = (const bf16_t*)((const char*)GA + ro_); const bf16_t* gp = (const bf16_t*)((const char*)GP + ro_);
; #pragma unroll
;         for (int ai = 0; ai < 2; ++ai)
; #pragma unroll
;             for (int m = 0; m < 4; ++m)
; #pragma unroll
;                 for (int bj = 0; bj < 2; ++bj) { const size_t o_ = (size_t)(ai * HALF + m * 16) * 2048 + bj * HALF;
;                     const u32x4 a = *(const u32x4*)(ga + o_), p = *(const u32x4*)(gp + o_);
;     ...
;                     acc[ai][bj][m][0][0] *= RT_(a.x, p.x, 1); acc[ai][bj][m][0][1] *= RT_(a.x, p.x, 0); acc[ai][bj][m][0][2] *= RT_(a.y, p.y, 1); acc[ai][bj][m][0][3] *= RT_(a.y, p.y, 0);
;                     acc[ai][bj][m][1][0] *= RT_(a.z, p.z, 1); acc[ai][bj][m][1][1] *= RT_(a.z, p.z, 0); acc[ai][bj][m][1][2] *= RT_(a.w, p.w, 1); acc[ai][bj][m][1][3] *= RT_(a.w, p.w, 0);
;     ...
;                     asm volatile("" ::: "memory"); }
	v_lshlrev_b32_e32 v134, 16, v144
	v_and_b32_e32 v135, 0xffff0000, v144
	v_max_f32_e32 v134, v134, v134
	v_max_f32_e32 v135, v135, v135
	v_max_f32_e32 v134, 0xda24260, v134
	v_max_f32_e32 v135, 0xda24260, v135
	v_rcp_f32_e32 v134, v134
	v_rcp_f32_e32 v135, v135
	v_pk_mul_f32 v[132:133], v[136:137], v[132:133]
	v_addc_co_u32_e32 v155, vcc, 0, v185, vcc
	v_pk_mul_f32 v[82:83], v[82:83], v[132:133]
	v_lshlrev_b32_e32 v132, 16, v128
	v_and_b32_e32 v133, 0xffff0000, v128
	v_add_co_u32_e32 v156, vcc, s65, v182
	v_pk_mul_f32 v[152:153], v[134:135], v[132:133]
	s_nop 0
	v_addc_co_u32_e32 v157, vcc, 0, v183, vcc
	flat_load_dwordx4 v[132:135], v[154:155]
	flat_load_dwordx4 v[136:139], v[156:157]
	v_lshlrev_b32_e32 v128, 16, v145
	v_max_f32_e32 v128, v128, v128
	v_max_f32_e32 v128, 0xda24260, v128
	v_rcp_f32_e32 v144, v128
	v_and_b32_e32 v128, 0xffff0000, v145
	v_max_f32_e32 v128, v128, v128
	v_max_f32_e32 v128, 0xda24260, v128
	v_rcp_f32_e32 v145, v128
	v_lshlrev_b32_e32 v128, 16, v129
	v_and_b32_e32 v129, 0xffff0000, v129
	v_pk_mul_f32 v[128:129], v[144:145], v[128:129]
	v_lshlrev_b32_e32 v144, 16, v146
	v_and_b32_e32 v145, 0xffff0000, v146
	v_max_f32_e32 v144, v144, v144
	v_max_f32_e32 v145, v145, v145
	v_max_f32_e32 v144, 0xda24260, v144
	v_max_f32_e32 v145, 0xda24260, v145
	v_rcp_f32_e32 v144, v144
	v_rcp_f32_e32 v145, v145
	v_pk_mul_f32 v[78:79], v[78:79], v[128:129]
	v_lshlrev_b32_e32 v128, 16, v130
	v_and_b32_e32 v129, 0xffff0000, v130
	v_lshlrev_b32_e32 v130, 16, v147
	v_max_f32_e32 v130, v130, v130
	v_max_f32_e32 v130, 0xda24260, v130
	v_pk_mul_f32 v[128:129], v[144:145], v[128:129]
	v_rcp_f32_e32 v144, v130
	v_and_b32_e32 v130, 0xffff0000, v147
	v_max_f32_e32 v130, v130, v130
	v_max_f32_e32 v130, 0xda24260, v130
	v_rcp_f32_e32 v145, v130
	v_pk_mul_f32 v[72:73], v[72:73], v[128:129]
	v_lshlrev_b32_e32 v128, 16, v131
	v_and_b32_e32 v129, 0xffff0000, v131
	v_lshlrev_b32_e32 v130, 16, v148
	v_and_b32_e32 v131, 0xffff0000, v148
	v_max_f32_e32 v130, v130, v130
	v_max_f32_e32 v131, v131, v131
	v_max_f32_e32 v130, 0xda24260, v130
	v_max_f32_e32 v131, 0xda24260, v131
	v_rcp_f32_e32 v130, v130
	v_rcp_f32_e32 v131, v131
	v_pk_mul_f32 v[128:129], v[144:145], v[128:129]
	v_pk_mul_f32 v[76:77], v[76:77], v[152:153]
	v_pk_mul_f32 v[74:75], v[74:75], v[128:129]
	v_lshlrev_b32_e32 v128, 16, v140
	v_and_b32_e32 v129, 0xffff0000, v140
	v_pk_mul_f32 v[128:129], v[130:131], v[128:129]
	v_lshlrev_b32_e32 v130, 16, v149
	v_and_b32_e32 v131, 0xffff0000, v149
	v_max_f32_e32 v130, v130, v130
	v_max_f32_e32 v131, v131, v131
	v_max_f32_e32 v130, 0xda24260, v130
	v_max_f32_e32 v131, 0xda24260, v131
	v_rcp_f32_e32 v130, v130
	v_rcp_f32_e32 v131, v131
	flat_load_dwordx4 v[144:147], v[154:155] offset:256
	s_nop 0
	flat_load_dwordx4 v[152:155], v[156:157] offset:256
	v_pk_mul_f32 v[68:69], v[68:69], v[128:129]
	v_lshlrev_b32_e32 v128, 16, v141
	v_and_b32_e32 v129, 0xffff0000, v141
	v_pk_mul_f32 v[128:129], v[130:131], v[128:129]
	v_lshlrev_b32_e32 v130, 16, v150
	v_and_b32_e32 v131, 0xffff0000, v150
	v_max_f32_e32 v130, v130, v130
	v_max_f32_e32 v131, v131, v131
	v_max_f32_e32 v130, 0xda24260, v130
	v_max_f32_e32 v131, 0xda24260, v131
	v_rcp_f32_e32 v130, v130
	v_rcp_f32_e32 v131, v131
	v_pk_mul_f32 v[70:71], v[70:71], v[128:129]
	v_lshlrev_b32_e32 v128, 16, v142
	v_and_b32_e32 v129, 0xffff0000, v142
	v_pk_mul_f32 v[128:129], v[130:131], v[128:129]
	v_lshlrev_b32_e32 v130, 16, v151
	v_and_b32_e32 v131, 0xffff0000, v151
	v_max_f32_e32 v130, v130, v130
	v_max_f32_e32 v131, v131, v131
	v_max_f32_e32 v130, 0xda24260, v130
	v_max_f32_e32 v131, 0xda24260, v131
	v_rcp_f32_e32 v130, v130
	v_rcp_f32_e32 v131, v131
	v_pk_mul_f32 v[64:65], v[64:65], v[128:129]
	v_lshlrev_b32_e32 v128, 16, v143
	v_and_b32_e32 v129, 0xffff0000, v143
	v_pk_mul_f32 v[128:129], v[130:131], v[128:129]
	s_waitcnt vmcnt(0) lgkmcnt(0)
	v_lshlrev_b32_e32 v130, 16, v136
	v_and_b32_e32 v131, 0xffff0000, v136
	v_max_f32_e32 v130, v130, v130
	v_max_f32_e32 v131, v131, v131
	v_max_f32_e32 v130, 0xda24260, v130
	v_max_f32_e32 v131, 0xda24260, v131
	v_rcp_f32_e32 v130, v130
	v_rcp_f32_e32 v131, v131
	v_pk_mul_f32 v[66:67], v[66:67], v[128:129]
	v_lshlrev_b32_e32 v128, 16, v132
	v_and_b32_e32 v129, 0xffff0000, v132
	v_pk_mul_f32 v[148:149], v[130:131], v[128:129]
	v_lshlrev_b32_e32 v128, 16, v137
	v_max_f32_e32 v128, v128, v128
	v_max_f32_e32 v128, 0xda24260, v128
	v_rcp_f32_e32 v136, v128
	v_and_b32_e32 v128, 0xffff0000, v137
	v_add_co_u32_e32 v150, vcc, s66, v184
	v_max_f32_e32 v128, v128, v128
	s_nop 0
	v_addc_co_u32_e32 v151, vcc, 0, v185, vcc
	v_max_f32_e32 v128, 0xda24260, v128
	v_add_co_u32_e32 v156, vcc, s66, v182
	v_rcp_f32_e32 v137, v128
	s_nop 0
	v_addc_co_u32_e32 v157, vcc, 0, v183, vcc
	flat_load_dwordx4 v[128:131], v[150:151]
	flat_load_dwordx4 v[140:143], v[156:157]
	v_pk_mul_f32 v[60:61], v[60:61], v[148:149]
	flat_load_dwordx4 v[148:151], v[150:151] offset:256
	s_nop 0
	flat_load_dwordx4 v[156:159], v[156:157] offset:256
	v_lshlrev_b32_e32 v132, 16, v133
	v_and_b32_e32 v133, 0xffff0000, v133
	v_pk_mul_f32 v[132:133], v[136:137], v[132:133]
	v_lshlrev_b32_e32 v136, 16, v138
	v_and_b32_e32 v137, 0xffff0000, v138
	v_max_f32_e32 v136, v136, v136
	v_max_f32_e32 v137, v137, v137
	v_max_f32_e32 v136, 0xda24260, v136
	v_max_f32_e32 v137, 0xda24260, v137
	v_rcp_f32_e32 v136, v136
	v_rcp_f32_e32 v137, v137
	v_pk_mul_f32 v[62:63], v[62:63], v[132:133]
	v_lshlrev_b32_e32 v132, 16, v134
	v_and_b32_e32 v133, 0xffff0000, v134
	v_lshlrev_b32_e32 v134, 16, v139
	v_max_f32_e32 v134, v134, v134
	v_max_f32_e32 v134, 0xda24260, v134
	v_pk_mul_f32 v[132:133], v[136:137], v[132:133]
	v_rcp_f32_e32 v136, v134
; #define RT_(aw, pw, lo) ((lo ? bf_lo(aw) : bf_hi(aw)) * __builtin_amdgcn_rcpf(fmaxf(lo ? bf_lo(pw) : bf_hi(pw), 1e-30f)))
;     __device__ __forceinline__ void mid(f32x4 (&acc)[2][2][4][2], const Unit& u, int wr, int wc, int fr, int fq) const {
;         const int col0 = u.pn * BM + wc * 32 + 8 * fq, row0 = u.pm * BM + wr * 64 + fr;
;         unsigned long long ro_ = ((unsigned long long)row0 * 2048 + col0) * 2; asm volatile("" : "+v"(ro_));
;         const bf16_t* ga = (const bf16_t*)((const char*)GA + ro_); const bf16_t* gp = (const bf16_t*)((const char*)GP + ro_);
; #pragma unroll
;         for (int ai = 0; ai < 2; ++ai)
; #pragma unroll
;             for (int m = 0; m < 4; ++m)
; #pragma unroll
;                 for (int bj = 0; bj < 2; ++bj) { const size_t o_ = (size_t)(ai * HALF + m * 16) * 2048 + bj * HALF;
;                     const u32x4 a = *(const u32x4*)(ga + o_), p = *(const u32x4*)(gp + o_);
;     ...
;                     acc[ai][bj][m][0][0] *= RT_(a.x, p.x, 1); acc[ai][bj][m][0][1] *= RT_(a.x, p.x, 0); acc[ai][bj][m][0][2] *= RT_(a.y, p.y, 1); acc[ai][bj][m][0][3] *= RT_(a.y, p.y, 0);
;                     acc[ai][bj][m][1][0] *= RT_(a.z, p.z, 1); acc[ai][bj][m][1][1] *= RT_(a.z, p.z, 0); acc[ai][bj][m][1][2] *= RT_(a.w, p.w, 1); acc[ai][bj][m][1][3] *= RT_(a.w, p.w, 0);
;     ...
;                     asm volatile("" ::: "memory"); }
	v_and_b32_e32 v134, 0xffff0000, v139
	v_max_f32_e32 v134, v134, v134
	v_max_f32_e32 v134, 0xda24260, v134
	v_rcp_f32_e32 v137, v134
	v_pk_mul_f32 v[56:57], v[56:57], v[132:133]
	v_lshlrev_b32_e32 v132, 16, v135
	v_and_b32_e32 v133, 0xffff0000, v135
	v_lshlrev_b32_e32 v134, 16, v152
	v_and_b32_e32 v135, 0xffff0000, v152
	v_max_f32_e32 v134, v134, v134
	v_max_f32_e32 v135, v135, v135
	v_max_f32_e32 v134, 0xda24260, v134
	v_max_f32_e32 v135, 0xda24260, v135
	v_rcp_f32_e32 v134, v134
	v_rcp_f32_e32 v135, v135
	v_pk_mul_f32 v[132:133], v[136:137], v[132:133]
	s_nop 0
	v_pk_mul_f32 v[58:59], v[58:59], v[132:133]
	v_lshlrev_b32_e32 v132, 16, v144
	v_and_b32_e32 v133, 0xffff0000, v144
	v_pk_mul_f32 v[132:133], v[134:135], v[132:133]
	v_lshlrev_b32_e32 v134, 16, v153
	v_and_b32_e32 v135, 0xffff0000, v153
	v_max_f32_e32 v134, v134, v134
	v_max_f32_e32 v135, v135, v135
	v_max_f32_e32 v134, 0xda24260, v134
	v_max_f32_e32 v135, 0xda24260, v135
	v_rcp_f32_e32 v134, v134
	v_rcp_f32_e32 v135, v135
	v_pk_mul_f32 v[52:53], v[52:53], v[132:133]
	v_lshlrev_b32_e32 v132, 16, v145
	v_and_b32_e32 v133, 0xffff0000, v145
	v_pk_mul_f32 v[132:133], v[134:135], v[132:133]
	v_lshlrev_b32_e32 v134, 16, v154
	v_and_b32_e32 v135, 0xffff0000, v154
	v_max_f32_e32 v134, v134, v134
	v_max_f32_e32 v135, v135, v135
	v_max_f32_e32 v134, 0xda24260, v134
	v_max_f32_e32 v135, 0xda24260, v135
	v_rcp_f32_e32 v134, v134
	v_rcp_f32_e32 v135, v135
	v_pk_mul_f32 v[54:55], v[54:55], v[132:133]
	v_lshlrev_b32_e32 v132, 16, v146
	v_and_b32_e32 v133, 0xffff0000, v146
	v_pk_mul_f32 v[132:133], v[134:135], v[132:133]
	v_lshlrev_b32_e32 v134, 16, v155
	v_and_b32_e32 v135, 0xffff0000, v155
	v_max_f32_e32 v134, v134, v134
	v_max_f32_e32 v135, v135, v135
	v_max_f32_e32 v134, 0xda24260, v134
	v_max_f32_e32 v135, 0xda24260, v135
	v_rcp_f32_e32 v134, v134
	v_rcp_f32_e32 v135, v135
	v_pk_mul_f32 v[48:49], v[48:49], v[132:133]
	v_lshlrev_b32_e32 v132, 16, v147
	v_and_b32_e32 v133, 0xffff0000, v147
	v_pk_mul_f32 v[132:133], v[134:135], v[132:133]
	s_waitcnt vmcnt(0) lgkmcnt(0)
	v_lshlrev_b32_e32 v134, 16, v140
	v_pk_mul_f32 v[50:51], v[50:51], v[132:133]
	v_lshlrev_b32_e32 v132, 16, v128
	v_and_b32_e32 v133, 0xffff0000, v128
	v_lshlrev_b32_e32 v128, 16, v141
	v_max_f32_e32 v128, v128, v128
	v_and_b32_e32 v135, 0xffff0000, v140
	v_max_f32_e32 v128, 0xda24260, v128
	v_max_f32_e32 v134, v134, v134
	v_max_f32_e32 v135, v135, v135
	v_rcp_f32_e32 v140, v128
	v_and_b32_e32 v128, 0xffff0000, v141
	v_max_f32_e32 v134, 0xda24260, v134
	v_max_f32_e32 v135, 0xda24260, v135
	v_max_f32_e32 v128, v128, v128
	v_rcp_f32_e32 v134, v134
	v_rcp_f32_e32 v135, v135
	v_max_f32_e32 v128, 0xda24260, v128
	v_rcp_f32_e32 v141, v128
	v_add_co_u32_e32 v146, vcc, s67, v184
	v_pk_mul_f32 v[144:145], v[134:135], v[132:133]
	s_nop 0
	v_addc_co_u32_e32 v147, vcc, 0, v185, vcc
	v_add_co_u32_e32 v152, vcc, s67, v182
	v_lshlrev_b32_e32 v128, 16, v129
	s_nop 0
	v_addc_co_u32_e32 v153, vcc, 0, v183, vcc
	flat_load_dwordx4 v[132:135], v[146:147]
	flat_load_dwordx4 v[136:139], v[152:153]
	v_and_b32_e32 v129, 0xffff0000, v129
	v_pk_mul_f32 v[128:129], v[140:141], v[128:129]
	v_lshlrev_b32_e32 v140, 16, v142
	v_and_b32_e32 v141, 0xffff0000, v142
	v_max_f32_e32 v140, v140, v140
	v_max_f32_e32 v141, v141, v141
	v_max_f32_e32 v140, 0xda24260, v140
	v_max_f32_e32 v141, 0xda24260, v141
	v_rcp_f32_e32 v140, v140
	v_rcp_f32_e32 v141, v141
	v_pk_mul_f32 v[46:47], v[46:47], v[128:129]
	v_lshlrev_b32_e32 v128, 16, v130
	v_and_b32_e32 v129, 0xffff0000, v130
	v_lshlrev_b32_e32 v130, 16, v143
	v_max_f32_e32 v130, v130, v130
	v_max_f32_e32 v130, 0xda24260, v130
	v_pk_mul_f32 v[128:129], v[140:141], v[128:129]
	v_rcp_f32_e32 v140, v130
	v_and_b32_e32 v130, 0xffff0000, v143
	v_max_f32_e32 v130, v130, v130
	v_max_f32_e32 v130, 0xda24260, v130
	v_rcp_f32_e32 v141, v130
	v_pk_mul_f32 v[40:41], v[40:41], v[128:129]
	v_lshlrev_b32_e32 v128, 16, v131
	v_and_b32_e32 v129, 0xffff0000, v131
	v_lshlrev_b32_e32 v130, 16, v156
	v_and_b32_e32 v131, 0xffff0000, v156
	v_max_f32_e32 v130, v130, v130
	v_max_f32_e32 v131, v131, v131
	v_max_f32_e32 v130, 0xda24260, v130
	v_max_f32_e32 v131, 0xda24260, v131
	v_rcp_f32_e32 v130, v130
	v_rcp_f32_e32 v131, v131
	v_pk_mul_f32 v[128:129], v[140:141], v[128:129]
	v_pk_mul_f32 v[44:45], v[44:45], v[144:145]
	v_pk_mul_f32 v[42:43], v[42:43], v[128:129]
	v_lshlrev_b32_e32 v128, 16, v148
	v_and_b32_e32 v129, 0xffff0000, v148
	v_pk_mul_f32 v[128:129], v[130:131], v[128:129]
	v_lshlrev_b32_e32 v130, 16, v157
	v_and_b32_e32 v131, 0xffff0000, v157
	v_max_f32_e32 v130, v130, v130
	v_max_f32_e32 v131, v131, v131
	v_max_f32_e32 v130, 0xda24260, v130
	v_max_f32_e32 v131, 0xda24260, v131
	v_rcp_f32_e32 v130, v130
	v_rcp_f32_e32 v131, v131
	v_pk_mul_f32 v[36:37], v[36:37], v[128:129]
	v_lshlrev_b32_e32 v128, 16, v149
	v_and_b32_e32 v129, 0xffff0000, v149
	v_pk_mul_f32 v[144:145], v[130:131], v[128:129]
	v_lshlrev_b32_e32 v128, 16, v158
	v_max_f32_e32 v128, v128, v128
	v_max_f32_e32 v128, 0xda24260, v128
	v_rcp_f32_e32 v148, v128
	flat_load_dwordx4 v[128:131], v[146:147] offset:256
	flat_load_dwordx4 v[140:143], v[152:153] offset:256
	v_and_b32_e32 v146, 0xffff0000, v158
	v_max_f32_e32 v146, v146, v146
	v_max_f32_e32 v146, 0xda24260, v146
	v_rcp_f32_e32 v149, v146
	v_lshlrev_b32_e32 v146, 16, v159
	v_and_b32_e32 v147, 0xffff0000, v159
	v_max_f32_e32 v146, v146, v146
	v_max_f32_e32 v147, v147, v147
	v_max_f32_e32 v146, 0xda24260, v146
	v_max_f32_e32 v147, 0xda24260, v147
	v_rcp_f32_e32 v146, v146
	v_rcp_f32_e32 v147, v147
	v_pk_mul_f32 v[38:39], v[38:39], v[144:145]
	v_lshlrev_b32_e32 v144, 16, v150
	v_and_b32_e32 v145, 0xffff0000, v150
	v_pk_mul_f32 v[144:145], v[148:149], v[144:145]
	v_add_co_u32_e32 v154, vcc, s68, v184
	v_pk_mul_f32 v[32:33], v[32:33], v[144:145]
	v_lshlrev_b32_e32 v144, 16, v151
	v_and_b32_e32 v145, 0xffff0000, v151
	v_pk_mul_f32 v[144:145], v[146:147], v[144:145]
	s_waitcnt vmcnt(0) lgkmcnt(0)
; #define RT_(aw, pw, lo) ((lo ? bf_lo(aw) : bf_hi(aw)) * __builtin_amdgcn_rcpf(fmaxf(lo ? bf_lo(pw) : bf_hi(pw), 1e-30f)))
;     __device__ __forceinline__ void mid(f32x4 (&acc)[2][2][4][2], const Unit& u, int wr, int wc, int fr, int fq) const {
;         const int col0 = u.pn * BM + wc * 32 + 8 * fq, row0 = u.pm * BM + wr * 64 + fr;
;         unsigned long long ro_ = ((unsigned long long)row0 * 2048 + col0) * 2; asm volatile("" : "+v"(ro_));
;         const bf16_t* ga = (const bf16_t*)((const char*)GA + ro_); const bf16_t* gp = (const bf16_t*)((const char*)GP + ro_);
; #pragma unroll
;         for (int ai = 0; ai < 2; ++ai)
; #pragma unroll
;             for (int m = 0; m < 4; ++m)
; #pragma unroll
;                 for (int bj = 0; bj < 2; ++bj) { const size_t o_ = (size_t)(ai * HALF + m * 16) * 2048 + bj * HALF;
;                     const u32x4 a = *(const u32x4*)(ga + o_), p = *(const u32x4*)(gp + o_);
;     ...
;                     acc[ai][bj][m][0][0] *= RT_(a.x, p.x, 1); acc[ai][bj][m][0][1] *= RT_(a.x, p.x, 0); acc[ai][bj][m][0][2] *= RT_(a.y, p.y, 1); acc[ai][bj][m][0][3] *= RT_(a.y, p.y, 0);
;                     acc[ai][bj][m][1][0] *= RT_(a.z, p.z, 1); acc[ai][bj][m][1][1] *= RT_(a.z, p.z, 0); acc[ai][bj][m][1][2] *= RT_(a.w, p.w, 1); acc[ai][bj][m][1][3] *= RT_(a.w, p.w, 0);
;     ...
;                     asm volatile("" ::: "memory"); }
	v_lshlrev_b32_e32 v146, 16, v136
	v_and_b32_e32 v136, 0xffff0000, v136
	v_max_f32_e32 v146, v146, v146
	v_max_f32_e32 v136, v136, v136
	v_max_f32_e32 v146, 0xda24260, v146
	v_max_f32_e32 v136, 0xda24260, v136
	v_rcp_f32_e32 v146, v146
	v_rcp_f32_e32 v147, v136
	v_addc_co_u32_e32 v155, vcc, 0, v185, vcc
	v_pk_mul_f32 v[34:35], v[34:35], v[144:145]
	v_lshlrev_b32_e32 v144, 16, v132
	v_and_b32_e32 v145, 0xffff0000, v132
	v_add_co_u32_e32 v156, vcc, s68, v182
	v_pk_mul_f32 v[152:153], v[146:147], v[144:145]
	s_nop 0
	v_addc_co_u32_e32 v157, vcc, 0, v183, vcc
	flat_load_dwordx4 v[144:147], v[154:155]
	flat_load_dwordx4 v[148:151], v[156:157]
	v_lshlrev_b32_e32 v132, 16, v137
	v_max_f32_e32 v132, v132, v132
	v_max_f32_e32 v132, 0xda24260, v132
	v_rcp_f32_e32 v136, v132
	v_and_b32_e32 v132, 0xffff0000, v137
	v_max_f32_e32 v132, v132, v132
	v_max_f32_e32 v132, 0xda24260, v132
	v_rcp_f32_e32 v137, v132
	v_lshlrev_b32_e32 v132, 16, v133
	v_and_b32_e32 v133, 0xffff0000, v133
	v_pk_mul_f32 v[132:133], v[136:137], v[132:133]
	v_lshlrev_b32_e32 v136, 16, v138
	v_and_b32_e32 v137, 0xffff0000, v138
	v_max_f32_e32 v136, v136, v136
	v_max_f32_e32 v137, v137, v137
	v_max_f32_e32 v136, 0xda24260, v136
	v_max_f32_e32 v137, 0xda24260, v137
	v_rcp_f32_e32 v136, v136
	v_rcp_f32_e32 v137, v137
	v_pk_mul_f32 v[30:31], v[30:31], v[132:133]
	v_lshlrev_b32_e32 v132, 16, v134
	v_and_b32_e32 v133, 0xffff0000, v134
	v_lshlrev_b32_e32 v134, 16, v139
	v_max_f32_e32 v134, v134, v134
	v_max_f32_e32 v134, 0xda24260, v134
	v_pk_mul_f32 v[132:133], v[136:137], v[132:133]
	v_rcp_f32_e32 v136, v134
	v_and_b32_e32 v134, 0xffff0000, v139
	v_max_f32_e32 v134, v134, v134
	v_max_f32_e32 v134, 0xda24260, v134
	v_rcp_f32_e32 v137, v134
	v_pk_mul_f32 v[24:25], v[24:25], v[132:133]
	v_lshlrev_b32_e32 v132, 16, v135
	v_and_b32_e32 v133, 0xffff0000, v135
	v_pk_mul_f32 v[132:133], v[136:137], v[132:133]
	v_pk_mul_f32 v[28:29], v[28:29], v[152:153]
	v_lshlrev_b32_e32 v134, 16, v140
	v_and_b32_e32 v135, 0xffff0000, v140
	v_max_f32_e32 v134, v134, v134
	v_max_f32_e32 v135, v135, v135
	v_max_f32_e32 v134, 0xda24260, v134
	v_max_f32_e32 v135, 0xda24260, v135
	v_rcp_f32_e32 v134, v134
	v_rcp_f32_e32 v135, v135
	v_pk_mul_f32 v[26:27], v[26:27], v[132:133]
	v_lshlrev_b32_e32 v132, 16, v128
	v_and_b32_e32 v133, 0xffff0000, v128
	v_pk_mul_f32 v[152:153], v[134:135], v[132:133]
	flat_load_dwordx4 v[132:135], v[154:155] offset:256
	flat_load_dwordx4 v[136:139], v[156:157] offset:256
	v_lshlrev_b32_e32 v128, 16, v141
	v_max_f32_e32 v128, v128, v128
	v_max_f32_e32 v128, 0xda24260, v128
	v_rcp_f32_e32 v140, v128
	v_and_b32_e32 v128, 0xffff0000, v141
	v_max_f32_e32 v128, v128, v128
	v_max_f32_e32 v128, 0xda24260, v128
	v_rcp_f32_e32 v141, v128
	v_lshlrev_b32_e32 v128, 16, v129
	v_and_b32_e32 v129, 0xffff0000, v129
	v_pk_mul_f32 v[128:129], v[140:141], v[128:129]
	v_lshlrev_b32_e32 v140, 16, v142
	v_and_b32_e32 v141, 0xffff0000, v142
	v_max_f32_e32 v140, v140, v140
	v_max_f32_e32 v141, v141, v141
	v_max_f32_e32 v140, 0xda24260, v140
	v_max_f32_e32 v141, 0xda24260, v141
	v_rcp_f32_e32 v140, v140
	v_rcp_f32_e32 v141, v141
	v_pk_mul_f32 v[22:23], v[22:23], v[128:129]
	v_lshlrev_b32_e32 v128, 16, v130
	v_and_b32_e32 v129, 0xffff0000, v130
	v_lshlrev_b32_e32 v130, 16, v143
	v_max_f32_e32 v130, v130, v130
	v_max_f32_e32 v130, 0xda24260, v130
	v_pk_mul_f32 v[128:129], v[140:141], v[128:129]
	v_rcp_f32_e32 v140, v130
	v_and_b32_e32 v130, 0xffff0000, v143
	v_max_f32_e32 v130, v130, v130
	v_max_f32_e32 v130, 0xda24260, v130
	v_rcp_f32_e32 v141, v130
	v_pk_mul_f32 v[16:17], v[16:17], v[128:129]
	v_lshlrev_b32_e32 v128, 16, v131
	v_and_b32_e32 v129, 0xffff0000, v131
	s_waitcnt vmcnt(0) lgkmcnt(0)
	v_lshlrev_b32_e32 v130, 16, v148
	v_and_b32_e32 v131, 0xffff0000, v148
	v_max_f32_e32 v130, v130, v130
	v_max_f32_e32 v131, v131, v131
	v_max_f32_e32 v130, 0xda24260, v130
	v_max_f32_e32 v131, 0xda24260, v131
	v_rcp_f32_e32 v130, v130
	v_rcp_f32_e32 v131, v131
	v_pk_mul_f32 v[128:129], v[140:141], v[128:129]
	s_waitcnt vmcnt(0)
	v_pk_mul_f32 v[20:21], v[20:21], v[152:153]
	v_pk_mul_f32 v[18:19], v[18:19], v[128:129]
	v_lshlrev_b32_e32 v128, 16, v144
	v_and_b32_e32 v129, 0xffff0000, v144
	v_pk_mul_f32 v[128:129], v[130:131], v[128:129]
	v_lshlrev_b32_e32 v130, 16, v149
	v_and_b32_e32 v131, 0xffff0000, v149
	v_max_f32_e32 v130, v130, v130
	v_max_f32_e32 v131, v131, v131
	v_max_f32_e32 v130, 0xda24260, v130
	v_max_f32_e32 v131, 0xda24260, v131
	v_rcp_f32_e32 v130, v130
	v_rcp_f32_e32 v131, v131
	v_pk_mul_f32 v[12:13], v[12:13], v[128:129]
	v_lshlrev_b32_e32 v128, 16, v145
	v_and_b32_e32 v129, 0xffff0000, v145
	v_pk_mul_f32 v[128:129], v[130:131], v[128:129]
	v_lshlrev_b32_e32 v130, 16, v150
	v_and_b32_e32 v131, 0xffff0000, v150
	v_max_f32_e32 v130, v130, v130
	v_max_f32_e32 v131, v131, v131
	v_max_f32_e32 v130, 0xda24260, v130
	v_max_f32_e32 v131, 0xda24260, v131
	v_rcp_f32_e32 v130, v130
	v_rcp_f32_e32 v131, v131
	v_pk_mul_f32 v[14:15], v[14:15], v[128:129]
	v_lshlrev_b32_e32 v128, 16, v146
	v_and_b32_e32 v129, 0xffff0000, v146
	v_pk_mul_f32 v[128:129], v[130:131], v[128:129]
	v_lshlrev_b32_e32 v130, 16, v151
	v_and_b32_e32 v131, 0xffff0000, v151
	v_max_f32_e32 v130, v130, v130
	v_max_f32_e32 v131, v131, v131
	v_max_f32_e32 v130, 0xda24260, v130
	v_max_f32_e32 v131, 0xda24260, v131
	v_rcp_f32_e32 v130, v130
	v_rcp_f32_e32 v131, v131
	v_pk_mul_f32 v[8:9], v[8:9], v[128:129]
	v_lshlrev_b32_e32 v128, 16, v147
	v_and_b32_e32 v129, 0xffff0000, v147
	v_pk_mul_f32 v[128:129], v[130:131], v[128:129]
	v_lshlrev_b32_e32 v130, 16, v136
	v_and_b32_e32 v131, 0xffff0000, v136
	v_max_f32_e32 v130, v130, v130
	v_max_f32_e32 v131, v131, v131
; #define PG8_STAGE(bufoff, gbase, voff) do { _Pragma("unroll") for (int _i = 0; _i < 2; ++_i) \
;         __builtin_amdgcn_global_load_lds((const unsigned*)((const char*)(gbase) + (voff)[_i]), (PG8_LAS unsigned*)(lds + (bufoff) + ldsw + _i * 8192), 16, 0, 0); } while (0)
; #define PG8_LDA(dst, b, h) do { _Pragma("unroll") for (int m = 0; m < 4; ++m) _Pragma("unroll") for (int k = 0; k < 2; ++k) dst[m][k] = *(const PG8_LAS bf16x8*)(lds + PG8_SA(b, h) + aoff + m * 2048 + k * 1024); } while (0)
; #define PG8_LDB(dst, b, h) do { _Pragma("unroll") for (int n = 0; n < 2; ++n) _Pragma("unroll") for (int k = 0; k < 2; ++k) dst[n][k] = *(const PG8_LAS bf16x8*)(lds + PG8_SB(b, h) + boff + n * 2048 + k * 1024); } while (0)
; #define PG8_MMA(ai, bj, At, Bt) do { __builtin_amdgcn_s_setprio(1); _Pragma("unroll") for (int m = 0; m < 4; ++m) _Pragma("unroll") for (int n = 0; n < 2; ++n) _Pragma("unroll") for (int k = 0; k < 2; ++k) \
;         acc[ai][bj][m][n] = __builtin_amdgcn_mfma_f32_16x16x32_bf16(Bt[n][k], At[m][k], acc[ai][bj][m][n], 0, 0, 0); __builtin_amdgcn_s_setprio(0); } while (0)
; #define PG8_WAIT_V(n) asm volatile("s_waitcnt vmcnt(" #n ")" ::: "memory")
; #define PG8_WAIT_L(n) asm volatile("s_waitcnt lgkmcnt(" #n ")" ::: "memory")
; #define PG8_BAR __builtin_amdgcn_s_barrier()
; #define PG8_SCHED __builtin_amdgcn_sched_barrier(0)
; template <class Epi, class Sched, bool ALIGN_EPI = false, bool SP2 = false>
; __device__ __forceinline__ void gemm_phase(PG8_LAS unsigned char* lds, const Gemm g, const Sched& S, const Epi& E) {
;     ...
;             if constexpr (Epi::MIDK) { if (t == (nt >> 1)) { asm volatile("s_waitcnt vmcnt(0)" ::: "memory"); E.mid(acc, cur, wr, wc, fr, fq); asm volatile("s_waitcnt vmcnt(0)" ::: "memory"); } }
;             const bool last = (t == nt - 2);
;             const char* a1 = cA + (size_t)(t + 1) * kstep;
;             const char* a2 = last ? nA : cA + (size_t)(t + 2) * kstep; const char* b2 = last ? nB : cB + (size_t)(t + 2) * kstep;
;             const char* a3 = a2 + kstep; const char* b3 = b2 + kstep;
;             if (last && has_next) S.a_ready(nxt);
;             if constexpr (SP2) {
;             PG8_LDB(B0, 0, 0); PG8_LDB(B1, 0, 1); PG8_SCHED; PG8_LDA(At, 0, 0); PG8_STAGE(PG8_SA(1, 1), a1 + hstepA, voffA);
;             PG8_WAIT_V(8); PG8_WAIT_L(0); PG8_BAR; PG8_MMA(0, 0, At, B0); PG8_MMA(0, 1, At, B1); PG8_BAR; PG8_SCHED;
	v_max_f32_e32 v130, 0xda24260, v130
	v_max_f32_e32 v131, 0xda24260, v131
	v_rcp_f32_e32 v130, v130
	v_rcp_f32_e32 v131, v131
	v_pk_mul_f32 v[10:11], v[10:11], v[128:129]
	v_lshlrev_b32_e32 v128, 16, v132
	v_and_b32_e32 v129, 0xffff0000, v132
	v_pk_mul_f32 v[128:129], v[130:131], v[128:129]
	v_lshlrev_b32_e32 v130, 16, v137
	v_and_b32_e32 v131, 0xffff0000, v137
	v_max_f32_e32 v130, v130, v130
	v_max_f32_e32 v131, v131, v131
	v_max_f32_e32 v130, 0xda24260, v130
	v_max_f32_e32 v131, 0xda24260, v131
	v_rcp_f32_e32 v130, v130
	v_rcp_f32_e32 v131, v131
	v_pk_mul_f32 v[4:5], v[4:5], v[128:129]
	v_lshlrev_b32_e32 v128, 16, v133
	v_and_b32_e32 v129, 0xffff0000, v133
	v_pk_mul_f32 v[128:129], v[130:131], v[128:129]
	v_lshlrev_b32_e32 v130, 16, v138
	v_and_b32_e32 v131, 0xffff0000, v138
	v_max_f32_e32 v130, v130, v130
	v_max_f32_e32 v131, v131, v131
	v_max_f32_e32 v130, 0xda24260, v130
	v_max_f32_e32 v131, 0xda24260, v131
	v_rcp_f32_e32 v130, v130
	v_rcp_f32_e32 v131, v131
	v_pk_mul_f32 v[6:7], v[6:7], v[128:129]
	v_lshlrev_b32_e32 v128, 16, v134
	v_and_b32_e32 v129, 0xffff0000, v134
	v_pk_mul_f32 v[128:129], v[130:131], v[128:129]
	v_lshlrev_b32_e32 v130, 16, v139
	v_and_b32_e32 v131, 0xffff0000, v139
	v_max_f32_e32 v130, v130, v130
	v_max_f32_e32 v131, v131, v131
	v_max_f32_e32 v130, 0xda24260, v130
	v_max_f32_e32 v131, 0xda24260, v131
	v_rcp_f32_e32 v130, v130
	v_rcp_f32_e32 v131, v131
	v_pk_mul_f32 v[0:1], v[0:1], v[128:129]
	v_lshlrev_b32_e32 v128, 16, v135
	v_and_b32_e32 v129, 0xffff0000, v135
	v_pk_mul_f32 v[128:129], v[130:131], v[128:129]
	s_nop 0
	v_pk_mul_f32 v[2:3], v[2:3], v[128:129]
	v_readfirstlane_b32 s32, v227
	s_nop 3
	s_lshr_b32 s32, s32, 6
	s_cmp_ge_u32 s32, 4
	s_cbranch_scc0 .Lprio_2
	s_setprio 1
.Lprio_2:
.LBB0_673:
	s_add_i32 s74, s44, 2
	s_add_u32 s45, s42, 0xfff80080
	s_addc_u32 s46, s43, -1
	s_add_i32 s75, 0, 0x10000
	v_add_u32_e32 v140, s75, v189
	v_add_u32_e32 v156, s69, v189
	ds_read_b128 v[128:131], v140
	ds_read_b128 v[132:135], v140 offset:1024
	ds_read_b128 v[136:139], v140 offset:2048
	ds_read_b128 v[140:143], v140 offset:3072
	ds_read_b128 v[144:147], v156
	ds_read_b128 v[148:151], v156 offset:1024
	ds_read_b128 v[152:155], v156 offset:2048
	ds_read_b128 v[156:159], v156 offset:3072
	s_cmp_eq_u32 s62, s44
	s_cselect_b32 s47, s29, s46
	s_cselect_b32 s46, s31, s45
	s_cselect_b32 s45, s70, s73
	s_cselect_b32 s44, s71, s72
	v_lshl_add_u64 v[220:221], s[42:43], 0, v[170:171]
	s_add_i32 m0, s52, 0xc000
	ds_read_b128 v[182:185], v191
	ds_read_b128 v[192:195], v191 offset:1024
	ds_read_b128 v[196:199], v191 offset:2048
	ds_read_b128 v[200:203], v191 offset:3072
	ds_read_b128 v[204:207], v191 offset:4096
	ds_read_b128 v[208:211], v191 offset:5120
	ds_read_b128 v[212:215], v191 offset:6144
	ds_read_b128 v[216:219], v191 offset:7168
	global_load_lds_dwordx4 v[220:221], off
	v_lshl_add_u64 v[220:221], s[42:43], 0, v[168:169]
	s_add_i32 m0, s52, 0xe000
	s_nop 0
	global_load_lds_dwordx4 v[220:221], off
	s_waitcnt vmcnt(8)
	s_waitcnt lgkmcnt(0)
	s_barrier
	s_waitcnt lgkmcnt(0)
	v_mfma_f32_16x16x32_bf16 v[124:127], v[128:131], v[182:185], v[124:127]
	v_mfma_f32_16x16x32_bf16 v[120:123], v[136:139], v[182:185], v[120:123]
	v_mfma_f32_16x16x32_bf16 v[108:111], v[128:131], v[196:199], v[108:111]
	v_mfma_f32_16x16x32_bf16 v[104:107], v[136:139], v[196:199], v[104:107]
	v_mfma_f32_16x16x32_bf16 v[92:95], v[128:131], v[204:207], v[92:95]
	v_mfma_f32_16x16x32_bf16 v[88:91], v[136:139], v[204:207], v[88:91]
	v_mfma_f32_16x16x32_bf16 v[76:79], v[128:131], v[212:215], v[76:79]
	v_mfma_f32_16x16x32_bf16 v[72:75], v[136:139], v[212:215], v[72:75]
	v_mfma_f32_16x16x32_bf16 v[124:127], v[132:135], v[192:195], v[124:127]
	v_mfma_f32_16x16x32_bf16 v[120:123], v[140:143], v[192:195], v[120:123]
	v_mfma_f32_16x16x32_bf16 v[108:111], v[132:135], v[200:203], v[108:111]
	v_mfma_f32_16x16x32_bf16 v[104:107], v[140:143], v[200:203], v[104:107]
	v_mfma_f32_16x16x32_bf16 v[92:95], v[132:135], v[208:211], v[92:95]
	v_mfma_f32_16x16x32_bf16 v[88:91], v[140:143], v[208:211], v[88:91]
	v_mfma_f32_16x16x32_bf16 v[76:79], v[132:135], v[216:219], v[76:79]
	v_mfma_f32_16x16x32_bf16 v[72:75], v[140:143], v[216:219], v[72:75]
	v_mfma_f32_16x16x32_bf16 v[116:119], v[144:147], v[182:185], v[116:119]
	v_mfma_f32_16x16x32_bf16 v[112:115], v[152:155], v[182:185], v[112:115]
	v_mfma_f32_16x16x32_bf16 v[100:103], v[144:147], v[196:199], v[100:103]
	v_mfma_f32_16x16x32_bf16 v[96:99], v[152:155], v[196:199], v[96:99]
	v_mfma_f32_16x16x32_bf16 v[84:87], v[144:147], v[204:207], v[84:87]
	v_mfma_f32_16x16x32_bf16 v[80:83], v[152:155], v[204:207], v[80:83]
	v_mfma_f32_16x16x32_bf16 v[68:71], v[144:147], v[212:215], v[68:71]
	v_mfma_f32_16x16x32_bf16 v[64:67], v[152:155], v[212:215], v[64:67]
	v_mfma_f32_16x16x32_bf16 v[116:119], v[148:151], v[192:195], v[116:119]
	v_mfma_f32_16x16x32_bf16 v[112:115], v[156:159], v[192:195], v[112:115]
	v_mfma_f32_16x16x32_bf16 v[100:103], v[148:151], v[200:203], v[100:103]
	v_mfma_f32_16x16x32_bf16 v[96:99], v[156:159], v[200:203], v[96:99]
	v_mfma_f32_16x16x32_bf16 v[84:87], v[148:151], v[208:211], v[84:87]
	v_mfma_f32_16x16x32_bf16 v[80:83], v[156:159], v[208:211], v[80:83]
	v_mfma_f32_16x16x32_bf16 v[68:71], v[148:151], v[216:219], v[68:71]
	v_mfma_f32_16x16x32_bf16 v[64:67], v[156:159], v[216:219], v[64:67]
	s_barrier
; #define PG8_STAGE(bufoff, gbase, voff) do { _Pragma("unroll") for (int _i = 0; _i < 2; ++_i) \
;         __builtin_amdgcn_global_load_lds((const unsigned*)((const char*)(gbase) + (voff)[_i]), (PG8_LAS unsigned*)(lds + (bufoff) + ldsw + _i * 8192), 16, 0, 0); } while (0)
; #define PG8_LDA(dst, b, h) do { _Pragma("unroll") for (int m = 0; m < 4; ++m) _Pragma("unroll") for (int k = 0; k < 2; ++k) dst[m][k] = *(const PG8_LAS bf16x8*)(lds + PG8_SA(b, h) + aoff + m * 2048 + k * 1024); } while (0)
; #define PG8_LDB(dst, b, h) do { _Pragma("unroll") for (int n = 0; n < 2; ++n) _Pragma("unroll") for (int k = 0; k < 2; ++k) dst[n][k] = *(const PG8_LAS bf16x8*)(lds + PG8_SB(b, h) + boff + n * 2048 + k * 1024); } while (0)
; #define PG8_MMA(ai, bj, At, Bt) do { __builtin_amdgcn_s_setprio(1); _Pragma("unroll") for (int m = 0; m < 4; ++m) _Pragma("unroll") for (int n = 0; n < 2; ++n) _Pragma("unroll") for (int k = 0; k < 2; ++k) \
;         acc[ai][bj][m][n] = __builtin_amdgcn_mfma_f32_16x16x32_bf16(Bt[n][k], At[m][k], acc[ai][bj][m][n], 0, 0, 0); __builtin_amdgcn_s_setprio(0); } while (0)
; #define PG8_WAIT_V(n) asm volatile("s_waitcnt vmcnt(" #n ")" ::: "memory")
; #define PG8_WAIT_L(n) asm volatile("s_waitcnt lgkmcnt(" #n ")" ::: "memory")
; #define PG8_BAR __builtin_amdgcn_s_barrier()
; #define PG8_SCHED __builtin_amdgcn_sched_barrier(0)
; template <class Epi, class Sched, bool ALIGN_EPI = false, bool SP2 = false>
; __device__ __forceinline__ void gemm_phase(PG8_LAS unsigned char* lds, const Gemm g, const Sched& S, const Epi& E) {
;     ...
;             PG8_LDA(At, 0, 1); PG8_STAGE(PG8_SB(0, 0), b2, voffB); PG8_STAGE(PG8_SB(0, 1), b2 + hstepB, voffB); PG8_STAGE(PG8_SA(0, 0), a2, voffA);
;             PG8_WAIT_V(8); PG8_WAIT_L(0); PG8_BAR; PG8_MMA(1, 0, At, B0); PG8_MMA(1, 1, At, B1); PG8_BAR; PG8_SCHED;
;             PG8_LDB(B0, 1, 0); PG8_LDB(B1, 1, 1); PG8_SCHED; PG8_LDA(At, 1, 0); PG8_STAGE(PG8_SA(0, 1), a2 + hstepA, voffA);
	s_add_i32 s75, s75, s51
	v_lshl_add_u64 v[220:221], s[44:45], 0, v[164:165]
	s_mov_b32 m0, s75
	ds_read_b128 v[182:185], v191 offset:16384
	ds_read_b128 v[192:195], v191 offset:17408
	ds_read_b128 v[196:199], v191 offset:18432
	ds_read_b128 v[200:203], v191 offset:19456
	ds_read_b128 v[204:207], v191 offset:20480
	ds_read_b128 v[208:211], v191 offset:21504
	ds_read_b128 v[212:215], v191 offset:22528
	ds_read_b128 v[216:219], v191 offset:23552
	global_load_lds_dwordx4 v[220:221], off
	s_add_i32 m0, s75, 0x2000
	s_add_u32 s76, s44, 0x80000
	v_lshl_add_u64 v[222:223], s[44:45], 0, v[160:161]
	s_addc_u32 s77, s45, 0
	s_add_i32 s75, s69, s51
	global_load_lds_dwordx4 v[222:223], off
	v_lshl_add_u64 v[224:225], s[76:77], 0, v[164:165]
	s_mov_b32 m0, s75
	v_lshl_add_u64 v[228:229], s[46:47], 0, v[162:163]
	global_load_lds_dwordx4 v[224:225], off
	v_lshl_add_u64 v[224:225], s[76:77], 0, v[160:161]
	s_add_i32 m0, s75, 0x2000
	s_nop 0
	global_load_lds_dwordx4 v[224:225], off
	v_lshl_add_u64 v[224:225], s[46:47], 0, v[166:167]
	s_mov_b32 m0, s52
	s_nop 0
	global_load_lds_dwordx4 v[224:225], off
	s_mov_b32 m0, s53
	s_nop 0
	global_load_lds_dwordx4 v[228:229], off
	s_waitcnt vmcnt(8)
	s_waitcnt lgkmcnt(0)
	s_barrier
	s_waitcnt lgkmcnt(0)
	v_mfma_f32_16x16x32_bf16 v[60:63], v[128:131], v[182:185], v[60:63]
	v_mfma_f32_16x16x32_bf16 v[56:59], v[136:139], v[182:185], v[56:59]
	v_mfma_f32_16x16x32_bf16 v[44:47], v[128:131], v[196:199], v[44:47]
	v_mfma_f32_16x16x32_bf16 v[40:43], v[136:139], v[196:199], v[40:43]
	v_mfma_f32_16x16x32_bf16 v[28:31], v[128:131], v[204:207], v[28:31]
	v_mfma_f32_16x16x32_bf16 v[24:27], v[136:139], v[204:207], v[24:27]
	v_mfma_f32_16x16x32_bf16 v[12:15], v[128:131], v[212:215], v[12:15]
	v_mfma_f32_16x16x32_bf16 v[8:11], v[136:139], v[212:215], v[8:11]
	v_mfma_f32_16x16x32_bf16 v[60:63], v[132:135], v[192:195], v[60:63]
	v_mfma_f32_16x16x32_bf16 v[56:59], v[140:143], v[192:195], v[56:59]
	v_mfma_f32_16x16x32_bf16 v[44:47], v[132:135], v[200:203], v[44:47]
	v_mfma_f32_16x16x32_bf16 v[40:43], v[140:143], v[200:203], v[40:43]
	v_mfma_f32_16x16x32_bf16 v[28:31], v[132:135], v[208:211], v[28:31]
	v_mfma_f32_16x16x32_bf16 v[24:27], v[140:143], v[208:211], v[24:27]
	v_mfma_f32_16x16x32_bf16 v[12:15], v[132:135], v[216:219], v[12:15]
	v_mfma_f32_16x16x32_bf16 v[8:11], v[140:143], v[216:219], v[8:11]
	v_mfma_f32_16x16x32_bf16 v[52:55], v[144:147], v[182:185], v[52:55]
	v_mfma_f32_16x16x32_bf16 v[48:51], v[152:155], v[182:185], v[48:51]
	v_mfma_f32_16x16x32_bf16 v[36:39], v[144:147], v[196:199], v[36:39]
	v_mfma_f32_16x16x32_bf16 v[32:35], v[152:155], v[196:199], v[32:35]
	v_mfma_f32_16x16x32_bf16 v[20:23], v[144:147], v[204:207], v[20:23]
	v_mfma_f32_16x16x32_bf16 v[16:19], v[152:155], v[204:207], v[16:19]
	v_mfma_f32_16x16x32_bf16 v[4:7], v[144:147], v[212:215], v[4:7]
	v_mfma_f32_16x16x32_bf16 v[0:3], v[152:155], v[212:215], v[0:3]
	v_mfma_f32_16x16x32_bf16 v[52:55], v[148:151], v[192:195], v[52:55]
	v_mfma_f32_16x16x32_bf16 v[48:51], v[156:159], v[192:195], v[48:51]
	v_mfma_f32_16x16x32_bf16 v[36:39], v[148:151], v[200:203], v[36:39]
	v_mfma_f32_16x16x32_bf16 v[32:35], v[156:159], v[200:203], v[32:35]
	v_mfma_f32_16x16x32_bf16 v[20:23], v[148:151], v[208:211], v[20:23]
	v_mfma_f32_16x16x32_bf16 v[16:19], v[156:159], v[208:211], v[16:19]
	v_mfma_f32_16x16x32_bf16 v[4:7], v[148:151], v[216:219], v[4:7]
	v_mfma_f32_16x16x32_bf16 v[0:3], v[156:159], v[216:219], v[0:3]
	s_barrier
	s_add_i32 s75, 0, 0x18000
	s_add_i32 s76, 0, 0x1c000
	v_add_u32_e32 v140, s75, v189
	v_add_u32_e32 v156, s76, v189
	ds_read_b128 v[128:131], v140
	ds_read_b128 v[132:135], v140 offset:1024
	ds_read_b128 v[136:139], v140 offset:2048
	ds_read_b128 v[140:143], v140 offset:3072
	ds_read_b128 v[144:147], v156
	ds_read_b128 v[148:151], v156 offset:1024
	ds_read_b128 v[152:155], v156 offset:2048
	ds_read_b128 v[156:159], v156 offset:3072
	s_add_u32 s46, s46, 0x80000
	s_addc_u32 s47, s47, 0
	s_mov_b32 m0, s54
	v_lshl_add_u64 v[230:231], s[46:47], 0, v[166:167]
	ds_read_b128 v[182:185], v191 offset:32768
	ds_read_b128 v[192:195], v191 offset:33792
	ds_read_b128 v[196:199], v191 offset:34816
	ds_read_b128 v[200:203], v191 offset:35840
	ds_read_b128 v[204:207], v191 offset:36864
	ds_read_b128 v[208:211], v191 offset:37888
	ds_read_b128 v[212:215], v191 offset:38912
	ds_read_b128 v[216:219], v191 offset:39936
	global_load_lds_dwordx4 v[230:231], off
	v_lshl_add_u64 v[230:231], s[46:47], 0, v[162:163]
	s_mov_b32 m0, s55
	s_nop 0
	global_load_lds_dwordx4 v[230:231], off
	s_waitcnt vmcnt(8)
	s_waitcnt lgkmcnt(0)
	s_barrier
; #define PG8_STAGE(bufoff, gbase, voff) do { _Pragma("unroll") for (int _i = 0; _i < 2; ++_i) \
;         __builtin_amdgcn_global_load_lds((const unsigned*)((const char*)(gbase) + (voff)[_i]), (PG8_LAS unsigned*)(lds + (bufoff) + ldsw + _i * 8192), 16, 0, 0); } while (0)
; #define PG8_LDA(dst, b, h) do { _Pragma("unroll") for (int m = 0; m < 4; ++m) _Pragma("unroll") for (int k = 0; k < 2; ++k) dst[m][k] = *(const PG8_LAS bf16x8*)(lds + PG8_SA(b, h) + aoff + m * 2048 + k * 1024); } while (0)
; #define PG8_LDB(dst, b, h) do { _Pragma("unroll") for (int n = 0; n < 2; ++n) _Pragma("unroll") for (int k = 0; k < 2; ++k) dst[n][k] = *(const PG8_LAS bf16x8*)(lds + PG8_SB(b, h) + boff + n * 2048 + k * 1024); } while (0)
; #define PG8_MMA(ai, bj, At, Bt) do { __builtin_amdgcn_s_setprio(1); _Pragma("unroll") for (int m = 0; m < 4; ++m) _Pragma("unroll") for (int n = 0; n < 2; ++n) _Pragma("unroll") for (int k = 0; k < 2; ++k) \
;         acc[ai][bj][m][n] = __builtin_amdgcn_mfma_f32_16x16x32_bf16(Bt[n][k], At[m][k], acc[ai][bj][m][n], 0, 0, 0); __builtin_amdgcn_s_setprio(0); } while (0)
; #define PG8_WAIT_V(n) asm volatile("s_waitcnt vmcnt(" #n ")" ::: "memory")
; #define PG8_WAIT_L(n) asm volatile("s_waitcnt lgkmcnt(" #n ")" ::: "memory")
; #define PG8_BAR __builtin_amdgcn_s_barrier()
; #define PG8_SCHED __builtin_amdgcn_sched_barrier(0)
; template <class Epi, class Sched, bool ALIGN_EPI = false, bool SP2 = false>
; __device__ __forceinline__ void gemm_phase(PG8_LAS unsigned char* lds, const Gemm g, const Sched& S, const Epi& E) {
;     ...
;         for (int t = 0; t < nt; t += 2) {
;             if constexpr (Epi::MIDK) { if (t == (nt >> 1)) { asm volatile("s_waitcnt vmcnt(0)" ::: "memory"); E.mid(acc, cur, wr, wc, fr, fq); asm volatile("s_waitcnt vmcnt(0)" ::: "memory"); } }
;     ...
;             PG8_LDB(B0, 1, 0); PG8_LDB(B1, 1, 1); PG8_SCHED; PG8_LDA(At, 1, 0); PG8_STAGE(PG8_SA(0, 1), a2 + hstepA, voffA);
;             PG8_WAIT_V(8); PG8_WAIT_L(0); PG8_BAR; PG8_MMA(0, 0, At, B0); PG8_MMA(0, 1, At, B1); PG8_BAR; PG8_SCHED;
;             PG8_LDA(At, 1, 1); PG8_STAGE(PG8_SB(1, 0), b3, voffB); PG8_STAGE(PG8_SB(1, 1), b3 + hstepB, voffB); PG8_STAGE(PG8_SA(1, 0), a3, voffA);
;             PG8_WAIT_V(8); PG8_WAIT_L(0); PG8_BAR; PG8_MMA(1, 0, At, B0); PG8_MMA(1, 1, At, B1); PG8_BAR; PG8_SCHED;
	s_waitcnt lgkmcnt(0)
	v_mfma_f32_16x16x32_bf16 v[124:127], v[128:131], v[182:185], v[124:127]
	v_mfma_f32_16x16x32_bf16 v[120:123], v[136:139], v[182:185], v[120:123]
	v_mfma_f32_16x16x32_bf16 v[108:111], v[128:131], v[196:199], v[108:111]
	v_mfma_f32_16x16x32_bf16 v[104:107], v[136:139], v[196:199], v[104:107]
	v_mfma_f32_16x16x32_bf16 v[92:95], v[128:131], v[204:207], v[92:95]
	v_mfma_f32_16x16x32_bf16 v[88:91], v[136:139], v[204:207], v[88:91]
	v_mfma_f32_16x16x32_bf16 v[76:79], v[128:131], v[212:215], v[76:79]
	v_mfma_f32_16x16x32_bf16 v[72:75], v[136:139], v[212:215], v[72:75]
	v_mfma_f32_16x16x32_bf16 v[124:127], v[132:135], v[192:195], v[124:127]
	v_mfma_f32_16x16x32_bf16 v[120:123], v[140:143], v[192:195], v[120:123]
	v_mfma_f32_16x16x32_bf16 v[108:111], v[132:135], v[200:203], v[108:111]
	v_mfma_f32_16x16x32_bf16 v[104:107], v[140:143], v[200:203], v[104:107]
	v_mfma_f32_16x16x32_bf16 v[92:95], v[132:135], v[208:211], v[92:95]
	v_mfma_f32_16x16x32_bf16 v[88:91], v[140:143], v[208:211], v[88:91]
	v_mfma_f32_16x16x32_bf16 v[76:79], v[132:135], v[216:219], v[76:79]
	v_mfma_f32_16x16x32_bf16 v[72:75], v[140:143], v[216:219], v[72:75]
	v_mfma_f32_16x16x32_bf16 v[116:119], v[144:147], v[182:185], v[116:119]
	v_mfma_f32_16x16x32_bf16 v[112:115], v[152:155], v[182:185], v[112:115]
	v_mfma_f32_16x16x32_bf16 v[100:103], v[144:147], v[196:199], v[100:103]
	v_mfma_f32_16x16x32_bf16 v[96:99], v[152:155], v[196:199], v[96:99]
	v_mfma_f32_16x16x32_bf16 v[84:87], v[144:147], v[204:207], v[84:87]
	v_mfma_f32_16x16x32_bf16 v[80:83], v[152:155], v[204:207], v[80:83]
	v_mfma_f32_16x16x32_bf16 v[68:71], v[144:147], v[212:215], v[68:71]
	v_mfma_f32_16x16x32_bf16 v[64:67], v[152:155], v[212:215], v[64:67]
	v_mfma_f32_16x16x32_bf16 v[116:119], v[148:151], v[192:195], v[116:119]
	v_mfma_f32_16x16x32_bf16 v[112:115], v[156:159], v[192:195], v[112:115]
	v_mfma_f32_16x16x32_bf16 v[100:103], v[148:151], v[200:203], v[100:103]
	v_mfma_f32_16x16x32_bf16 v[96:99], v[156:159], v[200:203], v[96:99]
	v_mfma_f32_16x16x32_bf16 v[84:87], v[148:151], v[208:211], v[84:87]
	v_mfma_f32_16x16x32_bf16 v[80:83], v[156:159], v[208:211], v[80:83]
	v_mfma_f32_16x16x32_bf16 v[68:71], v[148:151], v[216:219], v[68:71]
	v_mfma_f32_16x16x32_bf16 v[64:67], v[156:159], v[216:219], v[64:67]
	s_barrier
	s_add_i32 s46, s75, s51
	v_lshl_add_u64 v[220:221], v[220:221], 0, s[16:17]
	s_mov_b32 m0, s46
	ds_read_b128 v[182:185], v191 offset:49152
	ds_read_b128 v[192:195], v191 offset:50176
	ds_read_b128 v[196:199], v191 offset:51200
	ds_read_b128 v[200:203], v191 offset:52224
	ds_read_b128 v[204:207], v191 offset:53248
	ds_read_b128 v[208:211], v191 offset:54272
	ds_read_b128 v[212:215], v191 offset:55296
	ds_read_b128 v[216:219], v191 offset:56320
	global_load_lds_dwordx4 v[220:221], off
	s_add_i32 m0, s46, 0x2000
	s_add_u32 s44, s44, 0x80080
	v_lshl_add_u64 v[220:221], v[222:223], 0, s[16:17]
	s_addc_u32 s45, s45, 0
	s_add_i32 s46, s76, s51
	global_load_lds_dwordx4 v[220:221], off
	v_lshl_add_u64 v[220:221], s[44:45], 0, v[164:165]
	s_mov_b32 m0, s46
	s_nop 0
	global_load_lds_dwordx4 v[220:221], off
	v_lshl_add_u64 v[220:221], s[44:45], 0, v[160:161]
	s_add_i32 m0, s46, 0x2000
	s_nop 0
	global_load_lds_dwordx4 v[220:221], off
	v_lshl_add_u64 v[220:221], v[224:225], 0, s[16:17]
	s_mov_b32 m0, s58
	s_nop 0
	global_load_lds_dwordx4 v[220:221], off
	v_lshl_add_u64 v[220:221], v[228:229], 0, s[16:17]
	s_mov_b32 m0, s59
	s_nop 0
	global_load_lds_dwordx4 v[220:221], off
	s_waitcnt vmcnt(8)
	s_waitcnt lgkmcnt(0)
	s_barrier
	s_waitcnt lgkmcnt(0)
	v_mfma_f32_16x16x32_bf16 v[60:63], v[128:131], v[182:185], v[60:63]
	v_mfma_f32_16x16x32_bf16 v[56:59], v[136:139], v[182:185], v[56:59]
	v_mfma_f32_16x16x32_bf16 v[44:47], v[128:131], v[196:199], v[44:47]
	v_mfma_f32_16x16x32_bf16 v[40:43], v[136:139], v[196:199], v[40:43]
	v_mfma_f32_16x16x32_bf16 v[28:31], v[128:131], v[204:207], v[28:31]
	v_mfma_f32_16x16x32_bf16 v[24:27], v[136:139], v[204:207], v[24:27]
	v_mfma_f32_16x16x32_bf16 v[12:15], v[128:131], v[212:215], v[12:15]
	v_mfma_f32_16x16x32_bf16 v[8:11], v[136:139], v[212:215], v[8:11]
	v_mfma_f32_16x16x32_bf16 v[60:63], v[132:135], v[192:195], v[60:63]
	v_mfma_f32_16x16x32_bf16 v[56:59], v[140:143], v[192:195], v[56:59]
	v_mfma_f32_16x16x32_bf16 v[44:47], v[132:135], v[200:203], v[44:47]
	v_mfma_f32_16x16x32_bf16 v[40:43], v[140:143], v[200:203], v[40:43]
	v_mfma_f32_16x16x32_bf16 v[28:31], v[132:135], v[208:211], v[28:31]
	v_mfma_f32_16x16x32_bf16 v[24:27], v[140:143], v[208:211], v[24:27]
	v_mfma_f32_16x16x32_bf16 v[12:15], v[132:135], v[216:219], v[12:15]
	v_mfma_f32_16x16x32_bf16 v[8:11], v[140:143], v[216:219], v[8:11]
	v_mfma_f32_16x16x32_bf16 v[52:55], v[144:147], v[182:185], v[52:55]
	v_mfma_f32_16x16x32_bf16 v[48:51], v[152:155], v[182:185], v[48:51]
	v_mfma_f32_16x16x32_bf16 v[36:39], v[144:147], v[196:199], v[36:39]
	v_mfma_f32_16x16x32_bf16 v[32:35], v[152:155], v[196:199], v[32:35]
	v_mfma_f32_16x16x32_bf16 v[20:23], v[144:147], v[204:207], v[20:23]
	v_mfma_f32_16x16x32_bf16 v[16:19], v[152:155], v[204:207], v[16:19]
	v_mfma_f32_16x16x32_bf16 v[4:7], v[144:147], v[212:215], v[4:7]
	v_mfma_f32_16x16x32_bf16 v[0:3], v[152:155], v[212:215], v[0:3]
	v_mfma_f32_16x16x32_bf16 v[52:55], v[148:151], v[192:195], v[52:55]
	v_mfma_f32_16x16x32_bf16 v[48:51], v[156:159], v[192:195], v[48:51]
	v_mfma_f32_16x16x32_bf16 v[36:39], v[148:151], v[200:203], v[36:39]
	v_mfma_f32_16x16x32_bf16 v[32:35], v[156:159], v[200:203], v[32:35]
	v_mfma_f32_16x16x32_bf16 v[20:23], v[148:151], v[208:211], v[20:23]
	v_mfma_f32_16x16x32_bf16 v[16:19], v[156:159], v[208:211], v[16:19]
	v_mfma_f32_16x16x32_bf16 v[4:7], v[148:151], v[216:219], v[4:7]
	v_mfma_f32_16x16x32_bf16 v[0:3], v[156:159], v[216:219], v[0:3]
	s_barrier
	s_add_u32 s72, s72, 0x100
	s_addc_u32 s73, s73, 0
	s_add_u32 s42, s42, 0x100
	s_addc_u32 s43, s43, 0
	s_cmp_ge_i32 s74, s57
	s_cbranch_scc1 .LBB0_675
	s_mov_b32 s44, s74
	s_cmp_lg_u32 s61, s44
	s_cbranch_scc0 .LBB0_672
	s_branch .LBB0_673
	s_setprio 0

; #define PG8_STAGE(bufoff, gbase, voff) do { _Pragma("unroll") for (int _i = 0; _i < 2; ++_i) \
;         __builtin_amdgcn_global_load_lds((const unsigned*)((const char*)(gbase) + (voff)[_i]), (PG8_LAS unsigned*)(lds + (bufoff) + ldsw + _i * 8192), 16, 0, 0); } while (0)
; #define PG8_LDA(dst, b, h) do { _Pragma("unroll") for (int m = 0; m < 4; ++m) _Pragma("unroll") for (int k = 0; k < 2; ++k) dst[m][k] = *(const PG8_LAS bf16x8*)(lds + PG8_SA(b, h) + aoff + m * 2048 + k * 1024); } while (0)
; #define PG8_LDB(dst, b, h) do { _Pragma("unroll") for (int n = 0; n < 2; ++n) _Pragma("unroll") for (int k = 0; k < 2; ++k) dst[n][k] = *(const PG8_LAS bf16x8*)(lds + PG8_SB(b, h) + boff + n * 2048 + k * 1024); } while (0)
; #define PG8_MMA(ai, bj, At, Bt) do { __builtin_amdgcn_s_setprio(1); _Pragma("unroll") for (int m = 0; m < 4; ++m) _Pragma("unroll") for (int n = 0; n < 2; ++n) _Pragma("unroll") for (int k = 0; k < 2; ++k) \
;         acc[ai][bj][m][n] = __builtin_amdgcn_mfma_f32_16x16x32_bf16(Bt[n][k], At[m][k], acc[ai][bj][m][n], 0, 0, 0); __builtin_amdgcn_s_setprio(0); } while (0)
; #define PG8_WAIT_V(n) asm volatile("s_waitcnt vmcnt(" #n ")" ::: "memory")
; #define PG8_WAIT_L(n) asm volatile("s_waitcnt lgkmcnt(" #n ")" ::: "memory")
; #define PG8_BAR __builtin_amdgcn_s_barrier()
; #define PG8_SCHED __builtin_amdgcn_sched_barrier(0)
; template <class Epi, class Sched, bool ALIGN_EPI = false, bool SP2 = false>
; __device__ __forceinline__ void gemm_phase(PG8_LAS unsigned char* lds, const Gemm g, const Sched& S, const Epi& E) {
;     ...
;             PG8_LDB(B0, 0, 0); PG8_LDB(B1, 0, 1); PG8_SCHED; PG8_LDA(At, 0, 0); PG8_STAGE(PG8_SA(1, 1), a1 + hstepA, voffA);
;             PG8_WAIT_V(8); PG8_WAIT_L(0); PG8_BAR; PG8_MMA(0, 0, At, B0); PG8_MMA(0, 1, At, B1); PG8_BAR; PG8_SCHED;
;     ...
;         for (int a = 0; a < 2; ++a)
; #pragma unroll
;             for (int b = 0; b < 2; ++b)
; #pragma unroll
;                 for (int m = 0; m < 4; ++m)
; #pragma unroll
;                     for (int n = 0; n < 2; ++n) acc[a][b][m][n] = (f32x4){0.f, 0.f, 0.f, 0.f};
;         cur = nxt; cA = nA; cB = nB; ++ui;
.LBB0_742:
	s_ashr_i32 s31, s30, 31
	s_lshl_b64 s[34:35], s[30:31], 20
	s_add_u32 s34, s39, s34
	s_addc_u32 s35, s48, s35
	s_ashr_i32 s29, s28, 31
	s_lshl_b64 s[36:37], s[28:29], 20
	s_add_u32 s36, s49, s36
	v_mov_b32_e32 v123, 0
	s_addc_u32 s37, s50, s37
	s_andn2_b64 vcc, exec, s[16:17]
	v_mov_b32_e32 v122, v123
	v_mov_b32_e32 v121, v123
	v_mov_b32_e32 v120, v123
	v_mov_b32_e32 v127, v123
	v_mov_b32_e32 v126, v123
	v_mov_b32_e32 v125, v123
	v_mov_b32_e32 v124, v123
	v_mov_b32_e32 v111, v123
	v_mov_b32_e32 v110, v123
	v_mov_b32_e32 v109, v123
	v_mov_b32_e32 v108, v123
	v_mov_b32_e32 v107, v123
	v_mov_b32_e32 v106, v123
	v_mov_b32_e32 v105, v123
	v_mov_b32_e32 v104, v123
	v_mov_b32_e32 v95, v123
	v_mov_b32_e32 v94, v123
	v_mov_b32_e32 v93, v123
	v_mov_b32_e32 v92, v123
	v_mov_b32_e32 v91, v123
	v_mov_b32_e32 v90, v123
	v_mov_b32_e32 v89, v123
	v_mov_b32_e32 v88, v123
	v_mov_b32_e32 v79, v123
	v_mov_b32_e32 v78, v123
	v_mov_b32_e32 v77, v123
	v_mov_b32_e32 v76, v123
	v_mov_b32_e32 v75, v123
	v_mov_b32_e32 v74, v123
	v_mov_b32_e32 v73, v123
	v_mov_b32_e32 v72, v123
	v_mov_b32_e32 v119, v123
	v_mov_b32_e32 v118, v123
	v_mov_b32_e32 v117, v123
	v_mov_b32_e32 v116, v123
	v_mov_b32_e32 v115, v123
	v_mov_b32_e32 v114, v123
	v_mov_b32_e32 v113, v123
	v_mov_b32_e32 v112, v123
	v_mov_b32_e32 v103, v123
	v_mov_b32_e32 v102, v123
	v_mov_b32_e32 v101, v123
	v_mov_b32_e32 v100, v123
	v_mov_b32_e32 v99, v123
	v_mov_b32_e32 v98, v123
	v_mov_b32_e32 v97, v123
	v_mov_b32_e32 v96, v123
	v_mov_b32_e32 v87, v123
	v_mov_b32_e32 v86, v123
	v_mov_b32_e32 v85, v123
	v_mov_b32_e32 v84, v123
	v_mov_b32_e32 v83, v123
	v_mov_b32_e32 v82, v123
	v_mov_b32_e32 v81, v123
	v_mov_b32_e32 v80, v123
	v_mov_b32_e32 v71, v123
	v_mov_b32_e32 v70, v123
	v_mov_b32_e32 v69, v123
	v_mov_b32_e32 v68, v123
	v_mov_b32_e32 v67, v123
	v_mov_b32_e32 v66, v123
	v_mov_b32_e32 v65, v123
	v_mov_b32_e32 v64, v123
	v_mov_b32_e32 v63, v123
	v_mov_b32_e32 v62, v123
	v_mov_b32_e32 v61, v123
	v_mov_b32_e32 v60, v123
	v_mov_b32_e32 v59, v123
	v_mov_b32_e32 v58, v123
	v_mov_b32_e32 v57, v123
	v_mov_b32_e32 v56, v123
	v_mov_b32_e32 v47, v123
	v_mov_b32_e32 v46, v123
	v_mov_b32_e32 v45, v123
	v_mov_b32_e32 v44, v123
	v_mov_b32_e32 v43, v123
	v_mov_b32_e32 v42, v123
	v_mov_b32_e32 v41, v123
	v_mov_b32_e32 v40, v123
	v_mov_b32_e32 v31, v123
	v_mov_b32_e32 v30, v123
	v_mov_b32_e32 v29, v123
	v_mov_b32_e32 v28, v123
	v_mov_b32_e32 v27, v123
	v_mov_b32_e32 v26, v123
	v_mov_b32_e32 v25, v123
	v_mov_b32_e32 v24, v123
	v_mov_b32_e32 v15, v123
	v_mov_b32_e32 v14, v123
	v_mov_b32_e32 v13, v123
	v_mov_b32_e32 v12, v123
	v_mov_b32_e32 v11, v123
	v_mov_b32_e32 v10, v123
	v_mov_b32_e32 v9, v123
	v_mov_b32_e32 v8, v123
	v_mov_b32_e32 v55, v123
	v_mov_b32_e32 v54, v123
	v_mov_b32_e32 v53, v123
	v_mov_b32_e32 v52, v123
	v_mov_b32_e32 v51, v123
	v_mov_b32_e32 v50, v123
	v_mov_b32_e32 v49, v123
	v_mov_b32_e32 v48, v123
	v_mov_b32_e32 v39, v123
	v_mov_b32_e32 v38, v123
	v_mov_b32_e32 v37, v123
	v_mov_b32_e32 v36, v123
	v_mov_b32_e32 v35, v123
	v_mov_b32_e32 v34, v123
	v_mov_b32_e32 v33, v123
	v_mov_b32_e32 v32, v123
	v_mov_b32_e32 v23, v123
	v_mov_b32_e32 v22, v123
	v_mov_b32_e32 v21, v123
	v_mov_b32_e32 v20, v123
	v_mov_b32_e32 v19, v123
	v_mov_b32_e32 v18, v123
	v_mov_b32_e32 v17, v123
	v_mov_b32_e32 v16, v123
	v_mov_b32_e32 v7, v123
	v_mov_b32_e32 v6, v123
	v_mov_b32_e32 v5, v123
	v_mov_b32_e32 v4, v123
	s_waitcnt lgkmcnt(0)
	v_mov_b32_e32 v3, v123
	v_mov_b32_e32 v2, v123
	v_mov_b32_e32 v1, v123
	v_mov_b32_e32 v0, v123
	s_cbranch_vccnz .LBB0_745
	s_and_b64 s[46:47], s[6:7], exec
	s_cselect_b32 s29, s35, s45
	s_cselect_b32 s31, s34, s44
	s_cselect_b32 s63, s37, s43
	s_cselect_b32 s64, s36, s42
	s_add_u32 s65, s42, 0x100
	s_addc_u32 s66, s43, 0
	s_add_u32 s42, s44, 0x80080
	s_addc_u32 s43, s45, 0
	s_mov_b32 s44, 0
	v_readfirstlane_b32 s32, v227
	s_nop 3
	s_lshr_b32 s32, s32, 6
	s_cmp_ge_u32 s32, 4
	s_cbranch_scc0 .Lprio_3
	s_setprio 1
.Lprio_3:
.LBB0_744:
	ds_read_b128 v[146:149], v158
	ds_read_b128 v[150:153], v158 offset:1024
	ds_read_b128 v[162:165], v158 offset:2048
	ds_read_b128 v[166:169], v158 offset:3072
	ds_read_b128 v[170:173], v159
	ds_read_b128 v[174:177], v159 offset:1024
	ds_read_b128 v[178:181], v159 offset:2048
	ds_read_b128 v[182:185], v159 offset:3072
	s_add_i32 s67, s44, 2
	s_add_u32 s45, s42, 0xfff80080
	s_addc_u32 s46, s43, -1
	s_cmp_eq_u32 s60, s44
	s_cselect_b32 s44, s64, s65
	s_cselect_b32 s47, s29, s46
	s_cselect_b32 s46, s31, s45
	s_cselect_b32 s45, s63, s66
	v_lshl_add_u64 v[220:221], s[42:43], 0, v[140:141]
	s_add_i32 m0, s52, 0xc000
	ds_read_b128 v[188:191], v160
	ds_read_b128 v[192:195], v160 offset:1024
	ds_read_b128 v[196:199], v160 offset:2048
	ds_read_b128 v[200:203], v160 offset:3072
	ds_read_b128 v[204:207], v160 offset:4096
	ds_read_b128 v[208:211], v160 offset:5120
	ds_read_b128 v[212:215], v160 offset:6144
	ds_read_b128 v[216:219], v160 offset:7168
	global_load_lds_dwordx4 v[220:221], off
	v_lshl_add_u64 v[220:221], s[42:43], 0, v[138:139]
	s_add_i32 m0, s52, 0xe000
	s_nop 0
	global_load_lds_dwordx4 v[220:221], off
	s_waitcnt vmcnt(8)
	s_waitcnt lgkmcnt(0)
	s_barrier
; #define PG8_STAGE(bufoff, gbase, voff) do { _Pragma("unroll") for (int _i = 0; _i < 2; ++_i) \
;         __builtin_amdgcn_global_load_lds((const unsigned*)((const char*)(gbase) + (voff)[_i]), (PG8_LAS unsigned*)(lds + (bufoff) + ldsw + _i * 8192), 16, 0, 0); } while (0)
; #define PG8_LDA(dst, b, h) do { _Pragma("unroll") for (int m = 0; m < 4; ++m) _Pragma("unroll") for (int k = 0; k < 2; ++k) dst[m][k] = *(const PG8_LAS bf16x8*)(lds + PG8_SA(b, h) + aoff + m * 2048 + k * 1024); } while (0)
; #define PG8_MMA(ai, bj, At, Bt) do { __builtin_amdgcn_s_setprio(1); _Pragma("unroll") for (int m = 0; m < 4; ++m) _Pragma("unroll") for (int n = 0; n < 2; ++n) _Pragma("unroll") for (int k = 0; k < 2; ++k) \
;         acc[ai][bj][m][n] = __builtin_amdgcn_mfma_f32_16x16x32_bf16(Bt[n][k], At[m][k], acc[ai][bj][m][n], 0, 0, 0); __builtin_amdgcn_s_setprio(0); } while (0)
; #define PG8_WAIT_V(n) asm volatile("s_waitcnt vmcnt(" #n ")" ::: "memory")
; #define PG8_WAIT_L(n) asm volatile("s_waitcnt lgkmcnt(" #n ")" ::: "memory")
; #define PG8_BAR __builtin_amdgcn_s_barrier()
; #define PG8_SCHED __builtin_amdgcn_sched_barrier(0)
; template <class Epi, class Sched, bool ALIGN_EPI = false, bool SP2 = false>
; __device__ __forceinline__ void gemm_phase(PG8_LAS unsigned char* lds, const Gemm g, const Sched& S, const Epi& E) {
;     ...
;             PG8_WAIT_V(8); PG8_WAIT_L(0); PG8_BAR; PG8_MMA(0, 0, At, B0); PG8_MMA(0, 1, At, B1); PG8_BAR; PG8_SCHED;
;             PG8_LDA(At, 0, 1); PG8_STAGE(PG8_SB(0, 0), b2, voffB); PG8_STAGE(PG8_SB(0, 1), b2 + hstepB, voffB); PG8_STAGE(PG8_SA(0, 0), a2, voffA);
;             PG8_WAIT_V(8); PG8_WAIT_L(0); PG8_BAR; PG8_MMA(1, 0, At, B0); PG8_MMA(1, 1, At, B1); PG8_BAR; PG8_SCHED;
	s_waitcnt lgkmcnt(0)
	v_mfma_f32_16x16x32_bf16 v[120:123], v[146:149], v[188:191], v[120:123]
	v_mfma_f32_16x16x32_bf16 v[124:127], v[162:165], v[188:191], v[124:127]
	v_mfma_f32_16x16x32_bf16 v[108:111], v[146:149], v[196:199], v[108:111]
	v_mfma_f32_16x16x32_bf16 v[104:107], v[162:165], v[196:199], v[104:107]
	v_mfma_f32_16x16x32_bf16 v[92:95], v[146:149], v[204:207], v[92:95]
	v_mfma_f32_16x16x32_bf16 v[88:91], v[162:165], v[204:207], v[88:91]
	v_mfma_f32_16x16x32_bf16 v[76:79], v[146:149], v[212:215], v[76:79]
	v_mfma_f32_16x16x32_bf16 v[72:75], v[162:165], v[212:215], v[72:75]
	v_mfma_f32_16x16x32_bf16 v[120:123], v[150:153], v[192:195], v[120:123]
	v_mfma_f32_16x16x32_bf16 v[124:127], v[166:169], v[192:195], v[124:127]
	v_mfma_f32_16x16x32_bf16 v[108:111], v[150:153], v[200:203], v[108:111]
	v_mfma_f32_16x16x32_bf16 v[104:107], v[166:169], v[200:203], v[104:107]
	v_mfma_f32_16x16x32_bf16 v[92:95], v[150:153], v[208:211], v[92:95]
	v_mfma_f32_16x16x32_bf16 v[88:91], v[166:169], v[208:211], v[88:91]
	v_mfma_f32_16x16x32_bf16 v[76:79], v[150:153], v[216:219], v[76:79]
	v_mfma_f32_16x16x32_bf16 v[72:75], v[166:169], v[216:219], v[72:75]
	v_mfma_f32_16x16x32_bf16 v[116:119], v[170:173], v[188:191], v[116:119]
	v_mfma_f32_16x16x32_bf16 v[112:115], v[178:181], v[188:191], v[112:115]
	v_mfma_f32_16x16x32_bf16 v[100:103], v[170:173], v[196:199], v[100:103]
	v_mfma_f32_16x16x32_bf16 v[96:99], v[178:181], v[196:199], v[96:99]
	v_mfma_f32_16x16x32_bf16 v[84:87], v[170:173], v[204:207], v[84:87]
	v_mfma_f32_16x16x32_bf16 v[80:83], v[178:181], v[204:207], v[80:83]
	v_mfma_f32_16x16x32_bf16 v[68:71], v[170:173], v[212:215], v[68:71]
	v_mfma_f32_16x16x32_bf16 v[64:67], v[178:181], v[212:215], v[64:67]
	v_mfma_f32_16x16x32_bf16 v[116:119], v[174:177], v[192:195], v[116:119]
	v_mfma_f32_16x16x32_bf16 v[112:115], v[182:185], v[192:195], v[112:115]
	v_mfma_f32_16x16x32_bf16 v[100:103], v[174:177], v[200:203], v[100:103]
	v_mfma_f32_16x16x32_bf16 v[96:99], v[182:185], v[200:203], v[96:99]
	v_mfma_f32_16x16x32_bf16 v[84:87], v[174:177], v[208:211], v[84:87]
	v_mfma_f32_16x16x32_bf16 v[80:83], v[182:185], v[208:211], v[80:83]
	v_mfma_f32_16x16x32_bf16 v[68:71], v[174:177], v[216:219], v[68:71]
	v_mfma_f32_16x16x32_bf16 v[64:67], v[182:185], v[216:219], v[64:67]
	s_barrier
	s_add_i32 s68, s61, s51
	v_lshl_add_u64 v[220:221], s[44:45], 0, v[130:131]
	s_mov_b32 m0, s68
	ds_read_b128 v[188:191], v160 offset:16384
	ds_read_b128 v[192:195], v160 offset:17408
	ds_read_b128 v[196:199], v160 offset:18432
	ds_read_b128 v[200:203], v160 offset:19456
	ds_read_b128 v[204:207], v160 offset:20480
	ds_read_b128 v[208:211], v160 offset:21504
	ds_read_b128 v[212:215], v160 offset:22528
	ds_read_b128 v[216:219], v160 offset:23552
	global_load_lds_dwordx4 v[220:221], off
	s_add_i32 m0, s68, 0x2000
	s_add_u32 s68, s44, 0x80000
	v_lshl_add_u64 v[222:223], s[44:45], 0, v[134:135]
	s_addc_u32 s69, s45, 0
	s_add_i32 s70, s62, s51
	global_load_lds_dwordx4 v[222:223], off
	v_lshl_add_u64 v[224:225], s[68:69], 0, v[130:131]
	s_mov_b32 m0, s70
	v_lshl_add_u64 v[228:229], s[46:47], 0, v[132:133]
	global_load_lds_dwordx4 v[224:225], off
	v_lshl_add_u64 v[224:225], s[68:69], 0, v[134:135]
	s_add_i32 m0, s70, 0x2000
	s_nop 0
	global_load_lds_dwordx4 v[224:225], off
	v_lshl_add_u64 v[224:225], s[46:47], 0, v[128:129]
	s_mov_b32 m0, s52
	s_nop 0
	global_load_lds_dwordx4 v[224:225], off
	s_mov_b32 m0, s53
	s_nop 0
	global_load_lds_dwordx4 v[228:229], off
	s_waitcnt vmcnt(8)
	s_waitcnt lgkmcnt(0)
	s_barrier
	s_waitcnt lgkmcnt(0)
	v_mfma_f32_16x16x32_bf16 v[60:63], v[146:149], v[188:191], v[60:63]
	v_mfma_f32_16x16x32_bf16 v[56:59], v[162:165], v[188:191], v[56:59]
	v_mfma_f32_16x16x32_bf16 v[44:47], v[146:149], v[196:199], v[44:47]
	v_mfma_f32_16x16x32_bf16 v[40:43], v[162:165], v[196:199], v[40:43]
	v_mfma_f32_16x16x32_bf16 v[28:31], v[146:149], v[204:207], v[28:31]
	v_mfma_f32_16x16x32_bf16 v[24:27], v[162:165], v[204:207], v[24:27]
	v_mfma_f32_16x16x32_bf16 v[12:15], v[146:149], v[212:215], v[12:15]
	v_mfma_f32_16x16x32_bf16 v[8:11], v[162:165], v[212:215], v[8:11]
	v_mfma_f32_16x16x32_bf16 v[60:63], v[150:153], v[192:195], v[60:63]
	v_mfma_f32_16x16x32_bf16 v[56:59], v[166:169], v[192:195], v[56:59]
	v_mfma_f32_16x16x32_bf16 v[44:47], v[150:153], v[200:203], v[44:47]
	v_mfma_f32_16x16x32_bf16 v[40:43], v[166:169], v[200:203], v[40:43]
	v_mfma_f32_16x16x32_bf16 v[28:31], v[150:153], v[208:211], v[28:31]
	v_mfma_f32_16x16x32_bf16 v[24:27], v[166:169], v[208:211], v[24:27]
	v_mfma_f32_16x16x32_bf16 v[12:15], v[150:153], v[216:219], v[12:15]
	v_mfma_f32_16x16x32_bf16 v[8:11], v[166:169], v[216:219], v[8:11]
	v_mfma_f32_16x16x32_bf16 v[52:55], v[170:173], v[188:191], v[52:55]
	v_mfma_f32_16x16x32_bf16 v[48:51], v[178:181], v[188:191], v[48:51]
	v_mfma_f32_16x16x32_bf16 v[36:39], v[170:173], v[196:199], v[36:39]
	v_mfma_f32_16x16x32_bf16 v[32:35], v[178:181], v[196:199], v[32:35]
	v_mfma_f32_16x16x32_bf16 v[20:23], v[170:173], v[204:207], v[20:23]
	v_mfma_f32_16x16x32_bf16 v[16:19], v[178:181], v[204:207], v[16:19]
	v_mfma_f32_16x16x32_bf16 v[4:7], v[170:173], v[212:215], v[4:7]
	v_mfma_f32_16x16x32_bf16 v[0:3], v[178:181], v[212:215], v[0:3]
	v_mfma_f32_16x16x32_bf16 v[52:55], v[174:177], v[192:195], v[52:55]
	v_mfma_f32_16x16x32_bf16 v[48:51], v[182:185], v[192:195], v[48:51]
	v_mfma_f32_16x16x32_bf16 v[36:39], v[174:177], v[200:203], v[36:39]
	v_mfma_f32_16x16x32_bf16 v[32:35], v[182:185], v[200:203], v[32:35]
	v_mfma_f32_16x16x32_bf16 v[20:23], v[174:177], v[208:211], v[20:23]
	v_mfma_f32_16x16x32_bf16 v[16:19], v[182:185], v[208:211], v[16:19]
	v_mfma_f32_16x16x32_bf16 v[4:7], v[174:177], v[216:219], v[4:7]
	v_mfma_f32_16x16x32_bf16 v[0:3], v[182:185], v[216:219], v[0:3]
	s_barrier
; #define PG8_STAGE(bufoff, gbase, voff) do { _Pragma("unroll") for (int _i = 0; _i < 2; ++_i) \
;         __builtin_amdgcn_global_load_lds((const unsigned*)((const char*)(gbase) + (voff)[_i]), (PG8_LAS unsigned*)(lds + (bufoff) + ldsw + _i * 8192), 16, 0, 0); } while (0)
; #define PG8_LDA(dst, b, h) do { _Pragma("unroll") for (int m = 0; m < 4; ++m) _Pragma("unroll") for (int k = 0; k < 2; ++k) dst[m][k] = *(const PG8_LAS bf16x8*)(lds + PG8_SA(b, h) + aoff + m * 2048 + k * 1024); } while (0)
; #define PG8_LDB(dst, b, h) do { _Pragma("unroll") for (int n = 0; n < 2; ++n) _Pragma("unroll") for (int k = 0; k < 2; ++k) dst[n][k] = *(const PG8_LAS bf16x8*)(lds + PG8_SB(b, h) + boff + n * 2048 + k * 1024); } while (0)
; #define PG8_MMA(ai, bj, At, Bt) do { __builtin_amdgcn_s_setprio(1); _Pragma("unroll") for (int m = 0; m < 4; ++m) _Pragma("unroll") for (int n = 0; n < 2; ++n) _Pragma("unroll") for (int k = 0; k < 2; ++k) \
;         acc[ai][bj][m][n] = __builtin_amdgcn_mfma_f32_16x16x32_bf16(Bt[n][k], At[m][k], acc[ai][bj][m][n], 0, 0, 0); __builtin_amdgcn_s_setprio(0); } while (0)
; #define PG8_WAIT_V(n) asm volatile("s_waitcnt vmcnt(" #n ")" ::: "memory")
; #define PG8_WAIT_L(n) asm volatile("s_waitcnt lgkmcnt(" #n ")" ::: "memory")
; #define PG8_BAR __builtin_amdgcn_s_barrier()
; #define PG8_SCHED __builtin_amdgcn_sched_barrier(0)
; template <class Epi, class Sched, bool ALIGN_EPI = false, bool SP2 = false>
; __device__ __forceinline__ void gemm_phase(PG8_LAS unsigned char* lds, const Gemm g, const Sched& S, const Epi& E) {
;     ...
;             PG8_LDB(B0, 1, 0); PG8_LDB(B1, 1, 1); PG8_SCHED; PG8_LDA(At, 1, 0); PG8_STAGE(PG8_SA(0, 1), a2 + hstepA, voffA);
;             PG8_WAIT_V(8); PG8_WAIT_L(0); PG8_BAR; PG8_MMA(0, 0, At, B0); PG8_MMA(0, 1, At, B1); PG8_BAR; PG8_SCHED;
	s_add_i32 s68, 0, 0x18000
	v_add_u32_e32 v161, s68, v156
	s_add_i32 s69, 0, 0x1c000
	ds_read_b128 v[146:149], v161
	ds_read_b128 v[150:153], v161 offset:1024
	ds_read_b128 v[162:165], v161 offset:2048
	ds_read_b128 v[166:169], v161 offset:3072
	v_add_u32_e32 v161, s69, v156
	ds_read_b128 v[170:173], v161
	ds_read_b128 v[174:177], v161 offset:1024
	ds_read_b128 v[178:181], v161 offset:2048
	ds_read_b128 v[182:185], v161 offset:3072
	s_add_u32 s46, s46, 0x80000
	s_addc_u32 s47, s47, 0
	s_mov_b32 m0, s54
	v_lshl_add_u64 v[230:231], s[46:47], 0, v[128:129]
	ds_read_b128 v[188:191], v160 offset:32768
	ds_read_b128 v[192:195], v160 offset:33792
	ds_read_b128 v[196:199], v160 offset:34816
	ds_read_b128 v[200:203], v160 offset:35840
	ds_read_b128 v[204:207], v160 offset:36864
	ds_read_b128 v[208:211], v160 offset:37888
	ds_read_b128 v[212:215], v160 offset:38912
	ds_read_b128 v[216:219], v160 offset:39936
	global_load_lds_dwordx4 v[230:231], off
	v_lshl_add_u64 v[230:231], s[46:47], 0, v[132:133]
	s_mov_b32 m0, s55
	s_nop 0
	global_load_lds_dwordx4 v[230:231], off
	s_waitcnt vmcnt(8)
	s_waitcnt lgkmcnt(0)
	s_barrier
	s_waitcnt lgkmcnt(0)
	v_mfma_f32_16x16x32_bf16 v[120:123], v[146:149], v[188:191], v[120:123]
	v_mfma_f32_16x16x32_bf16 v[124:127], v[162:165], v[188:191], v[124:127]
	v_mfma_f32_16x16x32_bf16 v[108:111], v[146:149], v[196:199], v[108:111]
	v_mfma_f32_16x16x32_bf16 v[104:107], v[162:165], v[196:199], v[104:107]
	v_mfma_f32_16x16x32_bf16 v[92:95], v[146:149], v[204:207], v[92:95]
	v_mfma_f32_16x16x32_bf16 v[88:91], v[162:165], v[204:207], v[88:91]
	v_mfma_f32_16x16x32_bf16 v[76:79], v[146:149], v[212:215], v[76:79]
	v_mfma_f32_16x16x32_bf16 v[72:75], v[162:165], v[212:215], v[72:75]
	v_mfma_f32_16x16x32_bf16 v[120:123], v[150:153], v[192:195], v[120:123]
	v_mfma_f32_16x16x32_bf16 v[124:127], v[166:169], v[192:195], v[124:127]
	v_mfma_f32_16x16x32_bf16 v[108:111], v[150:153], v[200:203], v[108:111]
	v_mfma_f32_16x16x32_bf16 v[104:107], v[166:169], v[200:203], v[104:107]
	v_mfma_f32_16x16x32_bf16 v[92:95], v[150:153], v[208:211], v[92:95]
	v_mfma_f32_16x16x32_bf16 v[88:91], v[166:169], v[208:211], v[88:91]
	v_mfma_f32_16x16x32_bf16 v[76:79], v[150:153], v[216:219], v[76:79]
	v_mfma_f32_16x16x32_bf16 v[72:75], v[166:169], v[216:219], v[72:75]
	v_mfma_f32_16x16x32_bf16 v[116:119], v[170:173], v[188:191], v[116:119]
	v_mfma_f32_16x16x32_bf16 v[112:115], v[178:181], v[188:191], v[112:115]
	v_mfma_f32_16x16x32_bf16 v[100:103], v[170:173], v[196:199], v[100:103]
	v_mfma_f32_16x16x32_bf16 v[96:99], v[178:181], v[196:199], v[96:99]
	v_mfma_f32_16x16x32_bf16 v[84:87], v[170:173], v[204:207], v[84:87]
	v_mfma_f32_16x16x32_bf16 v[80:83], v[178:181], v[204:207], v[80:83]
	v_mfma_f32_16x16x32_bf16 v[68:71], v[170:173], v[212:215], v[68:71]
	v_mfma_f32_16x16x32_bf16 v[64:67], v[178:181], v[212:215], v[64:67]
	v_mfma_f32_16x16x32_bf16 v[116:119], v[174:177], v[192:195], v[116:119]
	v_mfma_f32_16x16x32_bf16 v[112:115], v[182:185], v[192:195], v[112:115]
	v_mfma_f32_16x16x32_bf16 v[100:103], v[174:177], v[200:203], v[100:103]
	v_mfma_f32_16x16x32_bf16 v[96:99], v[182:185], v[200:203], v[96:99]
	v_mfma_f32_16x16x32_bf16 v[84:87], v[174:177], v[208:211], v[84:87]
	v_mfma_f32_16x16x32_bf16 v[80:83], v[182:185], v[208:211], v[80:83]
	v_mfma_f32_16x16x32_bf16 v[68:71], v[174:177], v[216:219], v[68:71]
	v_mfma_f32_16x16x32_bf16 v[64:67], v[182:185], v[216:219], v[64:67]
	s_barrier
; #define PG8_STAGE(bufoff, gbase, voff) do { _Pragma("unroll") for (int _i = 0; _i < 2; ++_i) \
;         __builtin_amdgcn_global_load_lds((const unsigned*)((const char*)(gbase) + (voff)[_i]), (PG8_LAS unsigned*)(lds + (bufoff) + ldsw + _i * 8192), 16, 0, 0); } while (0)
; #define PG8_LDA(dst, b, h) do { _Pragma("unroll") for (int m = 0; m < 4; ++m) _Pragma("unroll") for (int k = 0; k < 2; ++k) dst[m][k] = *(const PG8_LAS bf16x8*)(lds + PG8_SA(b, h) + aoff + m * 2048 + k * 1024); } while (0)
; #define PG8_MMA(ai, bj, At, Bt) do { __builtin_amdgcn_s_setprio(1); _Pragma("unroll") for (int m = 0; m < 4; ++m) _Pragma("unroll") for (int n = 0; n < 2; ++n) _Pragma("unroll") for (int k = 0; k < 2; ++k) \
;         acc[ai][bj][m][n] = __builtin_amdgcn_mfma_f32_16x16x32_bf16(Bt[n][k], At[m][k], acc[ai][bj][m][n], 0, 0, 0); __builtin_amdgcn_s_setprio(0); } while (0)
; #define PG8_WAIT_V(n) asm volatile("s_waitcnt vmcnt(" #n ")" ::: "memory")
; #define PG8_WAIT_L(n) asm volatile("s_waitcnt lgkmcnt(" #n ")" ::: "memory")
; #define PG8_BAR __builtin_amdgcn_s_barrier()
; #define PG8_SCHED __builtin_amdgcn_sched_barrier(0)
; template <class Epi, class Sched, bool ALIGN_EPI = false, bool SP2 = false>
; __device__ __forceinline__ void gemm_phase(PG8_LAS unsigned char* lds, const Gemm g, const Sched& S, const Epi& E) {
;     ...
;         for (int t = 0; t < nt; t += 2) {
;     ...
;             PG8_LDA(At, 1, 1); PG8_STAGE(PG8_SB(1, 0), b3, voffB); PG8_STAGE(PG8_SB(1, 1), b3 + hstepB, voffB); PG8_STAGE(PG8_SA(1, 0), a3, voffA);
;             PG8_WAIT_V(8); PG8_WAIT_L(0); PG8_BAR; PG8_MMA(1, 0, At, B0); PG8_MMA(1, 1, At, B1); PG8_BAR; PG8_SCHED;
	s_add_i32 s46, s68, s51
	v_lshl_add_u64 v[220:221], v[220:221], 0, s[12:13]
	s_mov_b32 m0, s46
	ds_read_b128 v[188:191], v160 offset:49152
	ds_read_b128 v[192:195], v160 offset:50176
	ds_read_b128 v[196:199], v160 offset:51200
	ds_read_b128 v[200:203], v160 offset:52224
	ds_read_b128 v[204:207], v160 offset:53248
	ds_read_b128 v[208:211], v160 offset:54272
	ds_read_b128 v[212:215], v160 offset:55296
	ds_read_b128 v[216:219], v160 offset:56320
	global_load_lds_dwordx4 v[220:221], off
	s_add_i32 m0, s46, 0x2000
	s_add_u32 s44, s44, 0x80080
	v_lshl_add_u64 v[220:221], v[222:223], 0, s[12:13]
	s_addc_u32 s45, s45, 0
	s_add_i32 s46, s69, s51
	global_load_lds_dwordx4 v[220:221], off
	v_lshl_add_u64 v[220:221], s[44:45], 0, v[130:131]
	s_mov_b32 m0, s46
	s_nop 0
	global_load_lds_dwordx4 v[220:221], off
	v_lshl_add_u64 v[220:221], s[44:45], 0, v[134:135]
	s_add_i32 m0, s46, 0x2000
	s_nop 0
	global_load_lds_dwordx4 v[220:221], off
	v_lshl_add_u64 v[220:221], v[224:225], 0, s[12:13]
	s_mov_b32 m0, s58
	s_nop 0
	global_load_lds_dwordx4 v[220:221], off
	v_lshl_add_u64 v[220:221], v[228:229], 0, s[12:13]
	s_mov_b32 m0, s59
	s_nop 0
	global_load_lds_dwordx4 v[220:221], off
	s_waitcnt vmcnt(8)
	s_waitcnt lgkmcnt(0)
	s_barrier
	s_waitcnt lgkmcnt(0)
	v_mfma_f32_16x16x32_bf16 v[60:63], v[146:149], v[188:191], v[60:63]
	v_mfma_f32_16x16x32_bf16 v[56:59], v[162:165], v[188:191], v[56:59]
	v_mfma_f32_16x16x32_bf16 v[44:47], v[146:149], v[196:199], v[44:47]
	v_mfma_f32_16x16x32_bf16 v[40:43], v[162:165], v[196:199], v[40:43]
	v_mfma_f32_16x16x32_bf16 v[28:31], v[146:149], v[204:207], v[28:31]
	v_mfma_f32_16x16x32_bf16 v[24:27], v[162:165], v[204:207], v[24:27]
	v_mfma_f32_16x16x32_bf16 v[12:15], v[146:149], v[212:215], v[12:15]
	v_mfma_f32_16x16x32_bf16 v[8:11], v[162:165], v[212:215], v[8:11]
	v_mfma_f32_16x16x32_bf16 v[60:63], v[150:153], v[192:195], v[60:63]
	v_mfma_f32_16x16x32_bf16 v[56:59], v[166:169], v[192:195], v[56:59]
	v_mfma_f32_16x16x32_bf16 v[44:47], v[150:153], v[200:203], v[44:47]
	v_mfma_f32_16x16x32_bf16 v[40:43], v[166:169], v[200:203], v[40:43]
	v_mfma_f32_16x16x32_bf16 v[28:31], v[150:153], v[208:211], v[28:31]
	v_mfma_f32_16x16x32_bf16 v[24:27], v[166:169], v[208:211], v[24:27]
	v_mfma_f32_16x16x32_bf16 v[12:15], v[150:153], v[216:219], v[12:15]
	v_mfma_f32_16x16x32_bf16 v[8:11], v[166:169], v[216:219], v[8:11]
	v_mfma_f32_16x16x32_bf16 v[52:55], v[170:173], v[188:191], v[52:55]
	v_mfma_f32_16x16x32_bf16 v[48:51], v[178:181], v[188:191], v[48:51]
	v_mfma_f32_16x16x32_bf16 v[36:39], v[170:173], v[196:199], v[36:39]
	v_mfma_f32_16x16x32_bf16 v[32:35], v[178:181], v[196:199], v[32:35]
	v_mfma_f32_16x16x32_bf16 v[20:23], v[170:173], v[204:207], v[20:23]
	v_mfma_f32_16x16x32_bf16 v[16:19], v[178:181], v[204:207], v[16:19]
	v_mfma_f32_16x16x32_bf16 v[4:7], v[170:173], v[212:215], v[4:7]
	v_mfma_f32_16x16x32_bf16 v[0:3], v[178:181], v[212:215], v[0:3]
	v_mfma_f32_16x16x32_bf16 v[52:55], v[174:177], v[192:195], v[52:55]
	v_mfma_f32_16x16x32_bf16 v[48:51], v[182:185], v[192:195], v[48:51]
	v_mfma_f32_16x16x32_bf16 v[36:39], v[174:177], v[200:203], v[36:39]
	v_mfma_f32_16x16x32_bf16 v[32:35], v[182:185], v[200:203], v[32:35]
	v_mfma_f32_16x16x32_bf16 v[20:23], v[174:177], v[208:211], v[20:23]
	v_mfma_f32_16x16x32_bf16 v[16:19], v[182:185], v[208:211], v[16:19]
	v_mfma_f32_16x16x32_bf16 v[4:7], v[174:177], v[216:219], v[4:7]
	v_mfma_f32_16x16x32_bf16 v[0:3], v[182:185], v[216:219], v[0:3]
	s_barrier
	s_add_u32 s65, s65, 0x100
	s_addc_u32 s66, s66, 0
	s_add_u32 s42, s42, 0x100
	s_addc_u32 s43, s43, 0
	s_cmp_ge_i32 s67, s57
	s_mov_b32 s44, s67
	s_cbranch_scc0 .LBB0_744
	s_setprio 0

; #define PG8_STAGE(bufoff, gbase, voff) do { _Pragma("unroll") for (int _i = 0; _i < 2; ++_i) \
;         __builtin_amdgcn_global_load_lds((const unsigned*)((const char*)(gbase) + (voff)[_i]), (PG8_LAS unsigned*)(lds + (bufoff) + ldsw + _i * 8192), 16, 0, 0); } while (0)
; #define PG8_LDA(dst, b, h) do { _Pragma("unroll") for (int m = 0; m < 4; ++m) _Pragma("unroll") for (int k = 0; k < 2; ++k) dst[m][k] = *(const PG8_LAS bf16x8*)(lds + PG8_SA(b, h) + aoff + m * 2048 + k * 1024); } while (0)
; #define PG8_LDB(dst, b, h) do { _Pragma("unroll") for (int n = 0; n < 2; ++n) _Pragma("unroll") for (int k = 0; k < 2; ++k) dst[n][k] = *(const PG8_LAS bf16x8*)(lds + PG8_SB(b, h) + boff + n * 2048 + k * 1024); } while (0)
; #define PG8_MMA(ai, bj, At, Bt) do { __builtin_amdgcn_s_setprio(1); _Pragma("unroll") for (int m = 0; m < 4; ++m) _Pragma("unroll") for (int n = 0; n < 2; ++n) _Pragma("unroll") for (int k = 0; k < 2; ++k) \
;         acc[ai][bj][m][n] = __builtin_amdgcn_mfma_f32_16x16x32_bf16(Bt[n][k], At[m][k], acc[ai][bj][m][n], 0, 0, 0); __builtin_amdgcn_s_setprio(0); } while (0)
; #define PG8_WAIT_V(n) asm volatile("s_waitcnt vmcnt(" #n ")" ::: "memory")
; #define PG8_WAIT_L(n) asm volatile("s_waitcnt lgkmcnt(" #n ")" ::: "memory")
; #define PG8_BAR __builtin_amdgcn_s_barrier()
; #define PG8_SCHED __builtin_amdgcn_sched_barrier(0)
; template <class Epi, class Sched, bool ALIGN_EPI = false, bool SP2 = false>
; __device__ __forceinline__ void gemm_phase(PG8_LAS unsigned char* lds, const Gemm g, const Sched& S, const Epi& E) {
;     ...
;             PG8_LDB(B0, 0, 0); PG8_LDB(B1, 0, 1); PG8_SCHED; PG8_LDA(At, 0, 0); PG8_STAGE(PG8_SA(1, 1), a1 + hstepA, voffA);
;             PG8_WAIT_V(8); PG8_WAIT_L(0); PG8_BAR; PG8_MMA(0, 0, At, B0); PG8_MMA(0, 1, At, B1); PG8_BAR; PG8_SCHED;
;     ...
;         for (int a = 0; a < 2; ++a)
; #pragma unroll
;             for (int b = 0; b < 2; ++b)
; #pragma unroll
;                 for (int m = 0; m < 4; ++m)
; #pragma unroll
;                     for (int n = 0; n < 2; ++n) acc[a][b][m][n] = (f32x4){0.f, 0.f, 0.f, 0.f};
;         cur = nxt; cA = nA; cB = nB; ++ui;
.LBB0_827:
	s_ashr_i32 s35, s34, 31
	s_lshl_b64 s[36:37], s[34:35], 20
	s_add_u32 s36, s47, s36
	s_addc_u32 s37, s48, s37
	s_ashr_i32 s31, s30, 31
	s_lshl_b64 s[38:39], s[30:31], 20
	s_add_u32 s38, s49, s38
	v_mov_b32_e32 v123, 0
	s_addc_u32 s39, s50, s39
	s_andn2_b64 vcc, exec, s[18:19]
	v_mov_b32_e32 v122, v123
	v_mov_b32_e32 v121, v123
	v_mov_b32_e32 v120, v123
	v_mov_b32_e32 v127, v123
	v_mov_b32_e32 v126, v123
	v_mov_b32_e32 v125, v123
	v_mov_b32_e32 v124, v123
	v_mov_b32_e32 v111, v123
	v_mov_b32_e32 v110, v123
	v_mov_b32_e32 v109, v123
	v_mov_b32_e32 v108, v123
	v_mov_b32_e32 v107, v123
	v_mov_b32_e32 v106, v123
	v_mov_b32_e32 v105, v123
	v_mov_b32_e32 v104, v123
	v_mov_b32_e32 v95, v123
	v_mov_b32_e32 v94, v123
	v_mov_b32_e32 v93, v123
	v_mov_b32_e32 v92, v123
	v_mov_b32_e32 v91, v123
	v_mov_b32_e32 v90, v123
	v_mov_b32_e32 v89, v123
	v_mov_b32_e32 v88, v123
	v_mov_b32_e32 v79, v123
	v_mov_b32_e32 v78, v123
	v_mov_b32_e32 v77, v123
	v_mov_b32_e32 v76, v123
	v_mov_b32_e32 v75, v123
	v_mov_b32_e32 v74, v123
	v_mov_b32_e32 v73, v123
	v_mov_b32_e32 v72, v123
	v_mov_b32_e32 v119, v123
	v_mov_b32_e32 v118, v123
	v_mov_b32_e32 v117, v123
	v_mov_b32_e32 v116, v123
	v_mov_b32_e32 v115, v123
	v_mov_b32_e32 v114, v123
	v_mov_b32_e32 v113, v123
	v_mov_b32_e32 v112, v123
	v_mov_b32_e32 v103, v123
	v_mov_b32_e32 v102, v123
	v_mov_b32_e32 v101, v123
	v_mov_b32_e32 v100, v123
	v_mov_b32_e32 v99, v123
	v_mov_b32_e32 v98, v123
	v_mov_b32_e32 v97, v123
	v_mov_b32_e32 v96, v123
	v_mov_b32_e32 v87, v123
	v_mov_b32_e32 v86, v123
	v_mov_b32_e32 v85, v123
	v_mov_b32_e32 v84, v123
	v_mov_b32_e32 v83, v123
	v_mov_b32_e32 v82, v123
	v_mov_b32_e32 v81, v123
	v_mov_b32_e32 v80, v123
	v_mov_b32_e32 v71, v123
	v_mov_b32_e32 v70, v123
	v_mov_b32_e32 v69, v123
	v_mov_b32_e32 v68, v123
	v_mov_b32_e32 v67, v123
	v_mov_b32_e32 v66, v123
	v_mov_b32_e32 v65, v123
	v_mov_b32_e32 v64, v123
	v_mov_b32_e32 v63, v123
	v_mov_b32_e32 v62, v123
	v_mov_b32_e32 v61, v123
	v_mov_b32_e32 v60, v123
	v_mov_b32_e32 v59, v123
	v_mov_b32_e32 v58, v123
	v_mov_b32_e32 v57, v123
	v_mov_b32_e32 v56, v123
	v_mov_b32_e32 v47, v123
	v_mov_b32_e32 v46, v123
	v_mov_b32_e32 v45, v123
	v_mov_b32_e32 v44, v123
	v_mov_b32_e32 v43, v123
	v_mov_b32_e32 v42, v123
	v_mov_b32_e32 v41, v123
	v_mov_b32_e32 v40, v123
	v_mov_b32_e32 v31, v123
	v_mov_b32_e32 v30, v123
	v_mov_b32_e32 v29, v123
	v_mov_b32_e32 v28, v123
	v_mov_b32_e32 v27, v123
	v_mov_b32_e32 v26, v123
	v_mov_b32_e32 v25, v123
	v_mov_b32_e32 v24, v123
	v_mov_b32_e32 v15, v123
	v_mov_b32_e32 v14, v123
	v_mov_b32_e32 v13, v123
	v_mov_b32_e32 v12, v123
	v_mov_b32_e32 v11, v123
	v_mov_b32_e32 v10, v123
	v_mov_b32_e32 v9, v123
	v_mov_b32_e32 v8, v123
	v_mov_b32_e32 v55, v123
	v_mov_b32_e32 v54, v123
	v_mov_b32_e32 v53, v123
	v_mov_b32_e32 v52, v123
	v_mov_b32_e32 v51, v123
	v_mov_b32_e32 v50, v123
	v_mov_b32_e32 v49, v123
	v_mov_b32_e32 v48, v123
	v_mov_b32_e32 v39, v123
	v_mov_b32_e32 v38, v123
	v_mov_b32_e32 v37, v123
	v_mov_b32_e32 v36, v123
	v_mov_b32_e32 v35, v123
	v_mov_b32_e32 v34, v123
	v_mov_b32_e32 v33, v123
	v_mov_b32_e32 v32, v123
	v_mov_b32_e32 v23, v123
	v_mov_b32_e32 v22, v123
	v_mov_b32_e32 v21, v123
	v_mov_b32_e32 v20, v123
	v_mov_b32_e32 v19, v123
	v_mov_b32_e32 v18, v123
	v_mov_b32_e32 v17, v123
	v_mov_b32_e32 v16, v123
	v_mov_b32_e32 v7, v123
	v_mov_b32_e32 v6, v123
	v_mov_b32_e32 v5, v123
	v_mov_b32_e32 v4, v123
	v_mov_b32_e32 v3, v123
	v_mov_b32_e32 v2, v123
	v_mov_b32_e32 v1, v123
	v_mov_b32_e32 v0, v123
	s_cbranch_vccnz .LBB0_830
	s_and_b64 s[44:45], s[6:7], exec
	s_cselect_b32 s31, s37, s43
	s_cselect_b32 s35, s36, s42
	s_cselect_b32 s67, s39, s41
	s_cselect_b32 s68, s38, s40
	s_add_u32 s69, s40, 0x100
	s_addc_u32 s70, s41, 0
	s_add_u32 s40, s42, 0x80080
	s_addc_u32 s41, s43, 0
	s_mov_b32 s42, 0
	v_readfirstlane_b32 s32, v227
	s_nop 3
	s_lshr_b32 s32, s32, 6
	s_cmp_ge_u32 s32, 4
	s_cbranch_scc0 .Lprio_4
	s_setprio 1
.Lprio_4:
.LBB0_829:
	ds_read_b128 v[144:147], v155
	ds_read_b128 v[148:151], v155 offset:1024
	ds_read_b128 v[160:163], v155 offset:2048
	ds_read_b128 v[164:167], v155 offset:3072
	ds_read_b128 v[168:171], v156
	ds_read_b128 v[172:175], v156 offset:1024
	ds_read_b128 v[176:179], v156 offset:2048
	ds_read_b128 v[180:183], v156 offset:3072
	s_add_i32 s71, s42, 2
	s_add_u32 s43, s40, 0xfff80080
	s_addc_u32 s44, s41, -1
	s_cmp_eq_u32 s60, s42
	s_cselect_b32 s42, s68, s69
	s_cselect_b32 s45, s31, s44
	s_cselect_b32 s44, s35, s43
	s_cselect_b32 s43, s67, s70
	v_lshl_add_u64 v[184:185], s[40:41], 0, v[138:139]
	s_add_i32 m0, s52, 0xc000
	ds_read_b128 v[188:191], v157
	ds_read_b128 v[192:195], v157 offset:1024
	ds_read_b128 v[196:199], v157 offset:2048
	ds_read_b128 v[200:203], v157 offset:3072
	ds_read_b128 v[204:207], v157 offset:4096
	ds_read_b128 v[208:211], v157 offset:5120
	ds_read_b128 v[212:215], v157 offset:6144
	ds_read_b128 v[216:219], v157 offset:7168
	global_load_lds_dwordx4 v[184:185], off
	v_lshl_add_u64 v[184:185], s[40:41], 0, v[136:137]
	s_add_i32 m0, s52, 0xe000
	s_nop 0
	global_load_lds_dwordx4 v[184:185], off
	s_waitcnt vmcnt(8)
	s_waitcnt lgkmcnt(0)
	s_barrier
; #define PG8_STAGE(bufoff, gbase, voff) do { _Pragma("unroll") for (int _i = 0; _i < 2; ++_i) \
;         __builtin_amdgcn_global_load_lds((const unsigned*)((const char*)(gbase) + (voff)[_i]), (PG8_LAS unsigned*)(lds + (bufoff) + ldsw + _i * 8192), 16, 0, 0); } while (0)
; #define PG8_LDA(dst, b, h) do { _Pragma("unroll") for (int m = 0; m < 4; ++m) _Pragma("unroll") for (int k = 0; k < 2; ++k) dst[m][k] = *(const PG8_LAS bf16x8*)(lds + PG8_SA(b, h) + aoff + m * 2048 + k * 1024); } while (0)
; #define PG8_MMA(ai, bj, At, Bt) do { __builtin_amdgcn_s_setprio(1); _Pragma("unroll") for (int m = 0; m < 4; ++m) _Pragma("unroll") for (int n = 0; n < 2; ++n) _Pragma("unroll") for (int k = 0; k < 2; ++k) \
;         acc[ai][bj][m][n] = __builtin_amdgcn_mfma_f32_16x16x32_bf16(Bt[n][k], At[m][k], acc[ai][bj][m][n], 0, 0, 0); __builtin_amdgcn_s_setprio(0); } while (0)
; #define PG8_WAIT_V(n) asm volatile("s_waitcnt vmcnt(" #n ")" ::: "memory")
; #define PG8_WAIT_L(n) asm volatile("s_waitcnt lgkmcnt(" #n ")" ::: "memory")
; #define PG8_BAR __builtin_amdgcn_s_barrier()
; #define PG8_SCHED __builtin_amdgcn_sched_barrier(0)
; template <class Epi, class Sched, bool ALIGN_EPI = false, bool SP2 = false>
; __device__ __forceinline__ void gemm_phase(PG8_LAS unsigned char* lds, const Gemm g, const Sched& S, const Epi& E) {
;     ...
;             PG8_WAIT_V(8); PG8_WAIT_L(0); PG8_BAR; PG8_MMA(0, 0, At, B0); PG8_MMA(0, 1, At, B1); PG8_BAR; PG8_SCHED;
;             PG8_LDA(At, 0, 1); PG8_STAGE(PG8_SB(0, 0), b2, voffB); PG8_STAGE(PG8_SB(0, 1), b2 + hstepB, voffB); PG8_STAGE(PG8_SA(0, 0), a2, voffA);
;             PG8_WAIT_V(8); PG8_WAIT_L(0); PG8_BAR; PG8_MMA(1, 0, At, B0); PG8_MMA(1, 1, At, B1); PG8_BAR; PG8_SCHED;
	s_waitcnt lgkmcnt(0)
	v_mfma_f32_16x16x32_bf16 v[120:123], v[144:147], v[188:191], v[120:123]
	v_mfma_f32_16x16x32_bf16 v[124:127], v[160:163], v[188:191], v[124:127]
	v_mfma_f32_16x16x32_bf16 v[108:111], v[144:147], v[196:199], v[108:111]
	v_mfma_f32_16x16x32_bf16 v[104:107], v[160:163], v[196:199], v[104:107]
	v_mfma_f32_16x16x32_bf16 v[92:95], v[144:147], v[204:207], v[92:95]
	v_mfma_f32_16x16x32_bf16 v[88:91], v[160:163], v[204:207], v[88:91]
	v_mfma_f32_16x16x32_bf16 v[76:79], v[144:147], v[212:215], v[76:79]
	v_mfma_f32_16x16x32_bf16 v[72:75], v[160:163], v[212:215], v[72:75]
	v_mfma_f32_16x16x32_bf16 v[120:123], v[148:151], v[192:195], v[120:123]
	v_mfma_f32_16x16x32_bf16 v[124:127], v[164:167], v[192:195], v[124:127]
	v_mfma_f32_16x16x32_bf16 v[108:111], v[148:151], v[200:203], v[108:111]
	v_mfma_f32_16x16x32_bf16 v[104:107], v[164:167], v[200:203], v[104:107]
	v_mfma_f32_16x16x32_bf16 v[92:95], v[148:151], v[208:211], v[92:95]
	v_mfma_f32_16x16x32_bf16 v[88:91], v[164:167], v[208:211], v[88:91]
	v_mfma_f32_16x16x32_bf16 v[76:79], v[148:151], v[216:219], v[76:79]
	v_mfma_f32_16x16x32_bf16 v[72:75], v[164:167], v[216:219], v[72:75]
	v_mfma_f32_16x16x32_bf16 v[116:119], v[168:171], v[188:191], v[116:119]
	v_mfma_f32_16x16x32_bf16 v[112:115], v[176:179], v[188:191], v[112:115]
	v_mfma_f32_16x16x32_bf16 v[100:103], v[168:171], v[196:199], v[100:103]
	v_mfma_f32_16x16x32_bf16 v[96:99], v[176:179], v[196:199], v[96:99]
	v_mfma_f32_16x16x32_bf16 v[84:87], v[168:171], v[204:207], v[84:87]
	v_mfma_f32_16x16x32_bf16 v[80:83], v[176:179], v[204:207], v[80:83]
	v_mfma_f32_16x16x32_bf16 v[68:71], v[168:171], v[212:215], v[68:71]
	v_mfma_f32_16x16x32_bf16 v[64:67], v[176:179], v[212:215], v[64:67]
	v_mfma_f32_16x16x32_bf16 v[116:119], v[172:175], v[192:195], v[116:119]
	v_mfma_f32_16x16x32_bf16 v[112:115], v[180:183], v[192:195], v[112:115]
	v_mfma_f32_16x16x32_bf16 v[100:103], v[172:175], v[200:203], v[100:103]
	v_mfma_f32_16x16x32_bf16 v[96:99], v[180:183], v[200:203], v[96:99]
	v_mfma_f32_16x16x32_bf16 v[84:87], v[172:175], v[208:211], v[84:87]
	v_mfma_f32_16x16x32_bf16 v[80:83], v[180:183], v[208:211], v[80:83]
	v_mfma_f32_16x16x32_bf16 v[68:71], v[172:175], v[216:219], v[68:71]
	v_mfma_f32_16x16x32_bf16 v[64:67], v[180:183], v[216:219], v[64:67]
	s_barrier
	s_add_i32 s72, s61, s51
	v_lshl_add_u64 v[184:185], s[42:43], 0, v[132:133]
	s_mov_b32 m0, s72
	ds_read_b128 v[188:191], v157 offset:16384
	ds_read_b128 v[192:195], v157 offset:17408
	ds_read_b128 v[196:199], v157 offset:18432
	ds_read_b128 v[200:203], v157 offset:19456
	ds_read_b128 v[204:207], v157 offset:20480
	ds_read_b128 v[208:211], v157 offset:21504
	ds_read_b128 v[212:215], v157 offset:22528
	ds_read_b128 v[216:219], v157 offset:23552
	global_load_lds_dwordx4 v[184:185], off
	s_add_i32 m0, s72, 0x2000
	s_add_u32 s72, s42, 0x80000
	v_lshl_add_u64 v[220:221], s[42:43], 0, v[128:129]
	s_addc_u32 s73, s43, 0
	s_add_i32 s74, s62, s51
	global_load_lds_dwordx4 v[220:221], off
	v_lshl_add_u64 v[222:223], s[72:73], 0, v[132:133]
	s_mov_b32 m0, s74
	v_lshl_add_u64 v[224:225], s[44:45], 0, v[130:131]
	global_load_lds_dwordx4 v[222:223], off
	v_lshl_add_u64 v[222:223], s[72:73], 0, v[128:129]
	s_add_i32 m0, s74, 0x2000
	s_nop 0
	global_load_lds_dwordx4 v[222:223], off
	v_lshl_add_u64 v[222:223], s[44:45], 0, v[134:135]
	s_mov_b32 m0, s52
	s_nop 0
	global_load_lds_dwordx4 v[222:223], off
	s_mov_b32 m0, s53
	s_nop 0
	global_load_lds_dwordx4 v[224:225], off
	s_waitcnt vmcnt(8)
	s_waitcnt lgkmcnt(0)
	s_barrier
	s_waitcnt lgkmcnt(0)
	v_mfma_f32_16x16x32_bf16 v[60:63], v[144:147], v[188:191], v[60:63]
	v_mfma_f32_16x16x32_bf16 v[56:59], v[160:163], v[188:191], v[56:59]
	v_mfma_f32_16x16x32_bf16 v[44:47], v[144:147], v[196:199], v[44:47]
	v_mfma_f32_16x16x32_bf16 v[40:43], v[160:163], v[196:199], v[40:43]
	v_mfma_f32_16x16x32_bf16 v[28:31], v[144:147], v[204:207], v[28:31]
	v_mfma_f32_16x16x32_bf16 v[24:27], v[160:163], v[204:207], v[24:27]
	v_mfma_f32_16x16x32_bf16 v[12:15], v[144:147], v[212:215], v[12:15]
	v_mfma_f32_16x16x32_bf16 v[8:11], v[160:163], v[212:215], v[8:11]
	v_mfma_f32_16x16x32_bf16 v[60:63], v[148:151], v[192:195], v[60:63]
	v_mfma_f32_16x16x32_bf16 v[56:59], v[164:167], v[192:195], v[56:59]
	v_mfma_f32_16x16x32_bf16 v[44:47], v[148:151], v[200:203], v[44:47]
	v_mfma_f32_16x16x32_bf16 v[40:43], v[164:167], v[200:203], v[40:43]
	v_mfma_f32_16x16x32_bf16 v[28:31], v[148:151], v[208:211], v[28:31]
	v_mfma_f32_16x16x32_bf16 v[24:27], v[164:167], v[208:211], v[24:27]
	v_mfma_f32_16x16x32_bf16 v[12:15], v[148:151], v[216:219], v[12:15]
	v_mfma_f32_16x16x32_bf16 v[8:11], v[164:167], v[216:219], v[8:11]
	v_mfma_f32_16x16x32_bf16 v[52:55], v[168:171], v[188:191], v[52:55]
	v_mfma_f32_16x16x32_bf16 v[48:51], v[176:179], v[188:191], v[48:51]
	v_mfma_f32_16x16x32_bf16 v[36:39], v[168:171], v[196:199], v[36:39]
	v_mfma_f32_16x16x32_bf16 v[32:35], v[176:179], v[196:199], v[32:35]
	v_mfma_f32_16x16x32_bf16 v[20:23], v[168:171], v[204:207], v[20:23]
	v_mfma_f32_16x16x32_bf16 v[16:19], v[176:179], v[204:207], v[16:19]
	v_mfma_f32_16x16x32_bf16 v[4:7], v[168:171], v[212:215], v[4:7]
	v_mfma_f32_16x16x32_bf16 v[0:3], v[176:179], v[212:215], v[0:3]
	v_mfma_f32_16x16x32_bf16 v[52:55], v[172:175], v[192:195], v[52:55]
	v_mfma_f32_16x16x32_bf16 v[48:51], v[180:183], v[192:195], v[48:51]
	v_mfma_f32_16x16x32_bf16 v[36:39], v[172:175], v[200:203], v[36:39]
	v_mfma_f32_16x16x32_bf16 v[32:35], v[180:183], v[200:203], v[32:35]
	v_mfma_f32_16x16x32_bf16 v[20:23], v[172:175], v[208:211], v[20:23]
	v_mfma_f32_16x16x32_bf16 v[16:19], v[180:183], v[208:211], v[16:19]
	v_mfma_f32_16x16x32_bf16 v[4:7], v[172:175], v[216:219], v[4:7]
	v_mfma_f32_16x16x32_bf16 v[0:3], v[180:183], v[216:219], v[0:3]
	s_barrier
; #define PG8_STAGE(bufoff, gbase, voff) do { _Pragma("unroll") for (int _i = 0; _i < 2; ++_i) \
;         __builtin_amdgcn_global_load_lds((const unsigned*)((const char*)(gbase) + (voff)[_i]), (PG8_LAS unsigned*)(lds + (bufoff) + ldsw + _i * 8192), 16, 0, 0); } while (0)
; #define PG8_LDA(dst, b, h) do { _Pragma("unroll") for (int m = 0; m < 4; ++m) _Pragma("unroll") for (int k = 0; k < 2; ++k) dst[m][k] = *(const PG8_LAS bf16x8*)(lds + PG8_SA(b, h) + aoff + m * 2048 + k * 1024); } while (0)
; #define PG8_LDB(dst, b, h) do { _Pragma("unroll") for (int n = 0; n < 2; ++n) _Pragma("unroll") for (int k = 0; k < 2; ++k) dst[n][k] = *(const PG8_LAS bf16x8*)(lds + PG8_SB(b, h) + boff + n * 2048 + k * 1024); } while (0)
; #define PG8_MMA(ai, bj, At, Bt) do { __builtin_amdgcn_s_setprio(1); _Pragma("unroll") for (int m = 0; m < 4; ++m) _Pragma("unroll") for (int n = 0; n < 2; ++n) _Pragma("unroll") for (int k = 0; k < 2; ++k) \
;         acc[ai][bj][m][n] = __builtin_amdgcn_mfma_f32_16x16x32_bf16(Bt[n][k], At[m][k], acc[ai][bj][m][n], 0, 0, 0); __builtin_amdgcn_s_setprio(0); } while (0)
; #define PG8_WAIT_V(n) asm volatile("s_waitcnt vmcnt(" #n ")" ::: "memory")
; #define PG8_WAIT_L(n) asm volatile("s_waitcnt lgkmcnt(" #n ")" ::: "memory")
; #define PG8_BAR __builtin_amdgcn_s_barrier()
; #define PG8_SCHED __builtin_amdgcn_sched_barrier(0)
; template <class Epi, class Sched, bool ALIGN_EPI = false, bool SP2 = false>
; __device__ __forceinline__ void gemm_phase(PG8_LAS unsigned char* lds, const Gemm g, const Sched& S, const Epi& E) {
;     ...
;             PG8_LDB(B0, 1, 0); PG8_LDB(B1, 1, 1); PG8_SCHED; PG8_LDA(At, 1, 0); PG8_STAGE(PG8_SA(0, 1), a2 + hstepA, voffA);
;             PG8_WAIT_V(8); PG8_WAIT_L(0); PG8_BAR; PG8_MMA(0, 0, At, B0); PG8_MMA(0, 1, At, B1); PG8_BAR; PG8_SCHED;
	s_add_i32 s72, 0, 0x18000
	v_add_u32_e32 v159, s72, v153
	s_add_i32 s73, 0, 0x1c000
	ds_read_b128 v[144:147], v159
	ds_read_b128 v[148:151], v159 offset:1024
	ds_read_b128 v[160:163], v159 offset:2048
	ds_read_b128 v[164:167], v159 offset:3072
	v_add_u32_e32 v159, s73, v153
	ds_read_b128 v[168:171], v159
	ds_read_b128 v[172:175], v159 offset:1024
	ds_read_b128 v[176:179], v159 offset:2048
	ds_read_b128 v[180:183], v159 offset:3072
	s_add_u32 s44, s44, 0x80000
	s_addc_u32 s45, s45, 0
	s_mov_b32 m0, s54
	v_lshl_add_u64 v[228:229], s[44:45], 0, v[134:135]
	ds_read_b128 v[188:191], v157 offset:32768
	ds_read_b128 v[192:195], v157 offset:33792
	ds_read_b128 v[196:199], v157 offset:34816
	ds_read_b128 v[200:203], v157 offset:35840
	ds_read_b128 v[204:207], v157 offset:36864
	ds_read_b128 v[208:211], v157 offset:37888
	ds_read_b128 v[212:215], v157 offset:38912
	ds_read_b128 v[216:219], v157 offset:39936
	global_load_lds_dwordx4 v[228:229], off
	v_lshl_add_u64 v[228:229], s[44:45], 0, v[130:131]
	s_mov_b32 m0, s55
	s_nop 0
	global_load_lds_dwordx4 v[228:229], off
	s_waitcnt vmcnt(8)
	s_waitcnt lgkmcnt(0)
	s_barrier
	s_waitcnt lgkmcnt(0)
	v_mfma_f32_16x16x32_bf16 v[120:123], v[144:147], v[188:191], v[120:123]
	v_mfma_f32_16x16x32_bf16 v[124:127], v[160:163], v[188:191], v[124:127]
	v_mfma_f32_16x16x32_bf16 v[108:111], v[144:147], v[196:199], v[108:111]
	v_mfma_f32_16x16x32_bf16 v[104:107], v[160:163], v[196:199], v[104:107]
	v_mfma_f32_16x16x32_bf16 v[92:95], v[144:147], v[204:207], v[92:95]
	v_mfma_f32_16x16x32_bf16 v[88:91], v[160:163], v[204:207], v[88:91]
	v_mfma_f32_16x16x32_bf16 v[76:79], v[144:147], v[212:215], v[76:79]
	v_mfma_f32_16x16x32_bf16 v[72:75], v[160:163], v[212:215], v[72:75]
	v_mfma_f32_16x16x32_bf16 v[120:123], v[148:151], v[192:195], v[120:123]
	v_mfma_f32_16x16x32_bf16 v[124:127], v[164:167], v[192:195], v[124:127]
	v_mfma_f32_16x16x32_bf16 v[108:111], v[148:151], v[200:203], v[108:111]
	v_mfma_f32_16x16x32_bf16 v[104:107], v[164:167], v[200:203], v[104:107]
	v_mfma_f32_16x16x32_bf16 v[92:95], v[148:151], v[208:211], v[92:95]
	v_mfma_f32_16x16x32_bf16 v[88:91], v[164:167], v[208:211], v[88:91]
	v_mfma_f32_16x16x32_bf16 v[76:79], v[148:151], v[216:219], v[76:79]
	v_mfma_f32_16x16x32_bf16 v[72:75], v[164:167], v[216:219], v[72:75]
	v_mfma_f32_16x16x32_bf16 v[116:119], v[168:171], v[188:191], v[116:119]
	v_mfma_f32_16x16x32_bf16 v[112:115], v[176:179], v[188:191], v[112:115]
	v_mfma_f32_16x16x32_bf16 v[100:103], v[168:171], v[196:199], v[100:103]
	v_mfma_f32_16x16x32_bf16 v[96:99], v[176:179], v[196:199], v[96:99]
	v_mfma_f32_16x16x32_bf16 v[84:87], v[168:171], v[204:207], v[84:87]
	v_mfma_f32_16x16x32_bf16 v[80:83], v[176:179], v[204:207], v[80:83]
	v_mfma_f32_16x16x32_bf16 v[68:71], v[168:171], v[212:215], v[68:71]
	v_mfma_f32_16x16x32_bf16 v[64:67], v[176:179], v[212:215], v[64:67]
	v_mfma_f32_16x16x32_bf16 v[116:119], v[172:175], v[192:195], v[116:119]
	v_mfma_f32_16x16x32_bf16 v[112:115], v[180:183], v[192:195], v[112:115]
	v_mfma_f32_16x16x32_bf16 v[100:103], v[172:175], v[200:203], v[100:103]
	v_mfma_f32_16x16x32_bf16 v[96:99], v[180:183], v[200:203], v[96:99]
	v_mfma_f32_16x16x32_bf16 v[84:87], v[172:175], v[208:211], v[84:87]
	v_mfma_f32_16x16x32_bf16 v[80:83], v[180:183], v[208:211], v[80:83]
	v_mfma_f32_16x16x32_bf16 v[68:71], v[172:175], v[216:219], v[68:71]
	v_mfma_f32_16x16x32_bf16 v[64:67], v[180:183], v[216:219], v[64:67]
	s_barrier
; #define PG8_STAGE(bufoff, gbase, voff) do { _Pragma("unroll") for (int _i = 0; _i < 2; ++_i) \
;         __builtin_amdgcn_global_load_lds((const unsigned*)((const char*)(gbase) + (voff)[_i]), (PG8_LAS unsigned*)(lds + (bufoff) + ldsw + _i * 8192), 16, 0, 0); } while (0)
; #define PG8_LDA(dst, b, h) do { _Pragma("unroll") for (int m = 0; m < 4; ++m) _Pragma("unroll") for (int k = 0; k < 2; ++k) dst[m][k] = *(const PG8_LAS bf16x8*)(lds + PG8_SA(b, h) + aoff + m * 2048 + k * 1024); } while (0)
; #define PG8_MMA(ai, bj, At, Bt) do { __builtin_amdgcn_s_setprio(1); _Pragma("unroll") for (int m = 0; m < 4; ++m) _Pragma("unroll") for (int n = 0; n < 2; ++n) _Pragma("unroll") for (int k = 0; k < 2; ++k) \
;         acc[ai][bj][m][n] = __builtin_amdgcn_mfma_f32_16x16x32_bf16(Bt[n][k], At[m][k], acc[ai][bj][m][n], 0, 0, 0); __builtin_amdgcn_s_setprio(0); } while (0)
; #define PG8_WAIT_V(n) asm volatile("s_waitcnt vmcnt(" #n ")" ::: "memory")
; #define PG8_WAIT_L(n) asm volatile("s_waitcnt lgkmcnt(" #n ")" ::: "memory")
; #define PG8_BAR __builtin_amdgcn_s_barrier()
; #define PG8_SCHED __builtin_amdgcn_sched_barrier(0)
; template <class Epi, class Sched, bool ALIGN_EPI = false, bool SP2 = false>
; __device__ __forceinline__ void gemm_phase(PG8_LAS unsigned char* lds, const Gemm g, const Sched& S, const Epi& E) {
;     ...
;         for (int t = 0; t < nt; t += 2) {
;     ...
;             PG8_LDA(At, 1, 1); PG8_STAGE(PG8_SB(1, 0), b3, voffB); PG8_STAGE(PG8_SB(1, 1), b3 + hstepB, voffB); PG8_STAGE(PG8_SA(1, 0), a3, voffA);
;             PG8_WAIT_V(8); PG8_WAIT_L(0); PG8_BAR; PG8_MMA(1, 0, At, B0); PG8_MMA(1, 1, At, B1); PG8_BAR; PG8_SCHED;
	s_add_i32 s44, s72, s51
	v_lshl_add_u64 v[184:185], v[184:185], 0, s[16:17]
	s_mov_b32 m0, s44
	ds_read_b128 v[188:191], v157 offset:49152
	ds_read_b128 v[192:195], v157 offset:50176
	ds_read_b128 v[196:199], v157 offset:51200
	ds_read_b128 v[200:203], v157 offset:52224
	ds_read_b128 v[204:207], v157 offset:53248
	ds_read_b128 v[208:211], v157 offset:54272
	ds_read_b128 v[212:215], v157 offset:55296
	ds_read_b128 v[216:219], v157 offset:56320
	global_load_lds_dwordx4 v[184:185], off
	s_add_i32 m0, s44, 0x2000
	s_add_u32 s42, s42, 0x80080
	v_lshl_add_u64 v[184:185], v[220:221], 0, s[16:17]
	s_addc_u32 s43, s43, 0
	s_add_i32 s44, s73, s51
	global_load_lds_dwordx4 v[184:185], off
	v_lshl_add_u64 v[184:185], s[42:43], 0, v[132:133]
	s_mov_b32 m0, s44
	s_nop 0
	global_load_lds_dwordx4 v[184:185], off
	v_lshl_add_u64 v[184:185], s[42:43], 0, v[128:129]
	s_add_i32 m0, s44, 0x2000
	s_nop 0
	global_load_lds_dwordx4 v[184:185], off
	v_lshl_add_u64 v[184:185], v[222:223], 0, s[16:17]
	s_mov_b32 m0, s57
	s_nop 0
	global_load_lds_dwordx4 v[184:185], off
	v_lshl_add_u64 v[184:185], v[224:225], 0, s[16:17]
	s_mov_b32 m0, s58
	s_nop 0
	global_load_lds_dwordx4 v[184:185], off
	s_waitcnt vmcnt(8)
	s_waitcnt lgkmcnt(0)
	s_barrier
	s_waitcnt lgkmcnt(0)
	v_mfma_f32_16x16x32_bf16 v[60:63], v[144:147], v[188:191], v[60:63]
	v_mfma_f32_16x16x32_bf16 v[56:59], v[160:163], v[188:191], v[56:59]
	v_mfma_f32_16x16x32_bf16 v[44:47], v[144:147], v[196:199], v[44:47]
	v_mfma_f32_16x16x32_bf16 v[40:43], v[160:163], v[196:199], v[40:43]
	v_mfma_f32_16x16x32_bf16 v[28:31], v[144:147], v[204:207], v[28:31]
	v_mfma_f32_16x16x32_bf16 v[24:27], v[160:163], v[204:207], v[24:27]
	v_mfma_f32_16x16x32_bf16 v[12:15], v[144:147], v[212:215], v[12:15]
	v_mfma_f32_16x16x32_bf16 v[8:11], v[160:163], v[212:215], v[8:11]
	v_mfma_f32_16x16x32_bf16 v[60:63], v[148:151], v[192:195], v[60:63]
	v_mfma_f32_16x16x32_bf16 v[56:59], v[164:167], v[192:195], v[56:59]
	v_mfma_f32_16x16x32_bf16 v[44:47], v[148:151], v[200:203], v[44:47]
	v_mfma_f32_16x16x32_bf16 v[40:43], v[164:167], v[200:203], v[40:43]
	v_mfma_f32_16x16x32_bf16 v[28:31], v[148:151], v[208:211], v[28:31]
	v_mfma_f32_16x16x32_bf16 v[24:27], v[164:167], v[208:211], v[24:27]
	v_mfma_f32_16x16x32_bf16 v[12:15], v[148:151], v[216:219], v[12:15]
	v_mfma_f32_16x16x32_bf16 v[8:11], v[164:167], v[216:219], v[8:11]
	v_mfma_f32_16x16x32_bf16 v[52:55], v[168:171], v[188:191], v[52:55]
	v_mfma_f32_16x16x32_bf16 v[48:51], v[176:179], v[188:191], v[48:51]
	v_mfma_f32_16x16x32_bf16 v[36:39], v[168:171], v[196:199], v[36:39]
	v_mfma_f32_16x16x32_bf16 v[32:35], v[176:179], v[196:199], v[32:35]
	v_mfma_f32_16x16x32_bf16 v[20:23], v[168:171], v[204:207], v[20:23]
	v_mfma_f32_16x16x32_bf16 v[16:19], v[176:179], v[204:207], v[16:19]
	v_mfma_f32_16x16x32_bf16 v[4:7], v[168:171], v[212:215], v[4:7]
	v_mfma_f32_16x16x32_bf16 v[0:3], v[176:179], v[212:215], v[0:3]
	v_mfma_f32_16x16x32_bf16 v[52:55], v[172:175], v[192:195], v[52:55]
	v_mfma_f32_16x16x32_bf16 v[48:51], v[180:183], v[192:195], v[48:51]
	v_mfma_f32_16x16x32_bf16 v[36:39], v[172:175], v[200:203], v[36:39]
	v_mfma_f32_16x16x32_bf16 v[32:35], v[180:183], v[200:203], v[32:35]
	v_mfma_f32_16x16x32_bf16 v[20:23], v[172:175], v[208:211], v[20:23]
	v_mfma_f32_16x16x32_bf16 v[16:19], v[180:183], v[208:211], v[16:19]
	v_mfma_f32_16x16x32_bf16 v[4:7], v[172:175], v[216:219], v[4:7]
	v_mfma_f32_16x16x32_bf16 v[0:3], v[180:183], v[216:219], v[0:3]
	s_barrier
	s_add_u32 s69, s69, 0x100
	s_addc_u32 s70, s70, 0
	s_add_u32 s40, s40, 0x100
	s_addc_u32 s41, s41, 0
	s_cmp_ge_i32 s71, s56
	s_mov_b32 s42, s71
	s_cbranch_scc0 .LBB0_829
	s_setprio 0

; #define PG8_STAGE(bufoff, gbase, voff) do { _Pragma("unroll") for (int _i = 0; _i < 2; ++_i) \
;         __builtin_amdgcn_global_load_lds((const unsigned*)((const char*)(gbase) + (voff)[_i]), (PG8_LAS unsigned*)(lds + (bufoff) + ldsw + _i * 8192), 16, 0, 0); } while (0)
; #define PG8_LDA(dst, b, h) do { _Pragma("unroll") for (int m = 0; m < 4; ++m) _Pragma("unroll") for (int k = 0; k < 2; ++k) dst[m][k] = *(const PG8_LAS bf16x8*)(lds + PG8_SA(b, h) + aoff + m * 2048 + k * 1024); } while (0)
; #define PG8_LDB(dst, b, h) do { _Pragma("unroll") for (int n = 0; n < 2; ++n) _Pragma("unroll") for (int k = 0; k < 2; ++k) dst[n][k] = *(const PG8_LAS bf16x8*)(lds + PG8_SB(b, h) + boff + n * 2048 + k * 1024); } while (0)
; #define PG8_MMA(ai, bj, At, Bt) do { __builtin_amdgcn_s_setprio(1); _Pragma("unroll") for (int m = 0; m < 4; ++m) _Pragma("unroll") for (int n = 0; n < 2; ++n) _Pragma("unroll") for (int k = 0; k < 2; ++k) \
;         acc[ai][bj][m][n] = __builtin_amdgcn_mfma_f32_16x16x32_bf16(Bt[n][k], At[m][k], acc[ai][bj][m][n], 0, 0, 0); __builtin_amdgcn_s_setprio(0); } while (0)
; #define PG8_WAIT_V(n) asm volatile("s_waitcnt vmcnt(" #n ")" ::: "memory")
; #define PG8_WAIT_L(n) asm volatile("s_waitcnt lgkmcnt(" #n ")" ::: "memory")
; #define PG8_BAR __builtin_amdgcn_s_barrier()
; #define PG8_SCHED __builtin_amdgcn_sched_barrier(0)
; template <class Epi, class Sched, bool ALIGN_EPI = false, bool SP2 = false>
; __device__ __forceinline__ void gemm_phase(PG8_LAS unsigned char* lds, const Gemm g, const Sched& S, const Epi& E) {
;     ...
;             PG8_LDB(B0, 0, 0); PG8_LDB(B1, 0, 1); PG8_SCHED; PG8_LDA(At, 0, 0); PG8_STAGE(PG8_SA(1, 1), a1 + hstepA, voffA);
;             PG8_WAIT_V(8); PG8_WAIT_L(0); PG8_BAR; PG8_MMA(0, 0, At, B0); PG8_MMA(0, 1, At, B1); PG8_BAR; PG8_SCHED;
;     ...
;         for (int a = 0; a < 2; ++a)
; #pragma unroll
;             for (int b = 0; b < 2; ++b)
; #pragma unroll
;                 for (int m = 0; m < 4; ++m)
; #pragma unroll
;                     for (int n = 0; n < 2; ++n) acc[a][b][m][n] = (f32x4){0.f, 0.f, 0.f, 0.f};
;         cur = nxt; cA = nA; cB = nB; ++ui;
.LBB0_897:
	s_ashr_i32 s29, s28, 31
	s_lshl_b64 s[30:31], s[28:29], 22
	s_add_u32 s30, s45, s30
	s_addc_u32 s31, s46, s31
	s_ashr_i32 s27, s26, 31
	s_lshl_b64 s[34:35], s[26:27], 22
	s_add_u32 s34, s47, s34
	v_mov_b32_e32 v127, 0
	s_addc_u32 s35, s48, s35
	s_andn2_b64 vcc, exec, s[12:13]
	v_mov_b32_e32 v126, v127
	v_mov_b32_e32 v125, v127
	v_mov_b32_e32 v124, v127
	v_mov_b32_e32 v123, v127
	v_mov_b32_e32 v122, v127
	v_mov_b32_e32 v121, v127
	v_mov_b32_e32 v120, v127
	v_mov_b32_e32 v111, v127
	v_mov_b32_e32 v110, v127
	v_mov_b32_e32 v109, v127
	v_mov_b32_e32 v108, v127
	v_mov_b32_e32 v107, v127
	v_mov_b32_e32 v106, v127
	v_mov_b32_e32 v105, v127
	v_mov_b32_e32 v104, v127
	v_mov_b32_e32 v95, v127
	v_mov_b32_e32 v94, v127
	v_mov_b32_e32 v93, v127
	v_mov_b32_e32 v92, v127
	v_mov_b32_e32 v91, v127
	v_mov_b32_e32 v90, v127
	v_mov_b32_e32 v89, v127
	v_mov_b32_e32 v88, v127
	v_mov_b32_e32 v79, v127
	v_mov_b32_e32 v78, v127
	v_mov_b32_e32 v77, v127
	v_mov_b32_e32 v76, v127
	v_mov_b32_e32 v75, v127
	v_mov_b32_e32 v74, v127
	v_mov_b32_e32 v73, v127
	v_mov_b32_e32 v72, v127
	v_mov_b32_e32 v119, v127
	v_mov_b32_e32 v118, v127
	v_mov_b32_e32 v117, v127
	v_mov_b32_e32 v116, v127
	v_mov_b32_e32 v115, v127
	v_mov_b32_e32 v114, v127
	v_mov_b32_e32 v113, v127
	v_mov_b32_e32 v112, v127
	v_mov_b32_e32 v103, v127
	v_mov_b32_e32 v102, v127
	v_mov_b32_e32 v101, v127
	v_mov_b32_e32 v100, v127
	v_mov_b32_e32 v99, v127
	v_mov_b32_e32 v98, v127
	v_mov_b32_e32 v97, v127
	v_mov_b32_e32 v96, v127
	v_mov_b32_e32 v87, v127
	v_mov_b32_e32 v86, v127
	v_mov_b32_e32 v85, v127
	v_mov_b32_e32 v84, v127
	v_mov_b32_e32 v83, v127
	v_mov_b32_e32 v82, v127
	v_mov_b32_e32 v81, v127
	v_mov_b32_e32 v80, v127
	v_mov_b32_e32 v71, v127
	v_mov_b32_e32 v70, v127
	v_mov_b32_e32 v69, v127
	v_mov_b32_e32 v68, v127
	v_mov_b32_e32 v67, v127
	v_mov_b32_e32 v66, v127
	v_mov_b32_e32 v65, v127
	v_mov_b32_e32 v64, v127
	v_mov_b32_e32 v63, v127
	v_mov_b32_e32 v62, v127
	v_mov_b32_e32 v61, v127
	v_mov_b32_e32 v60, v127
	v_mov_b32_e32 v59, v127
	v_mov_b32_e32 v58, v127
	v_mov_b32_e32 v57, v127
	v_mov_b32_e32 v56, v127
	v_mov_b32_e32 v47, v127
	v_mov_b32_e32 v46, v127
	v_mov_b32_e32 v45, v127
	v_mov_b32_e32 v44, v127
	v_mov_b32_e32 v43, v127
	v_mov_b32_e32 v42, v127
	v_mov_b32_e32 v41, v127
	v_mov_b32_e32 v40, v127
	v_mov_b32_e32 v31, v127
	v_mov_b32_e32 v30, v127
	v_mov_b32_e32 v29, v127
	v_mov_b32_e32 v28, v127
	v_mov_b32_e32 v27, v127
	v_mov_b32_e32 v26, v127
	v_mov_b32_e32 v25, v127
	v_mov_b32_e32 v24, v127
	v_mov_b32_e32 v15, v127
	v_mov_b32_e32 v14, v127
	v_mov_b32_e32 v13, v127
	v_mov_b32_e32 v12, v127
	v_mov_b32_e32 v11, v127
	v_mov_b32_e32 v10, v127
	v_mov_b32_e32 v9, v127
	v_mov_b32_e32 v8, v127
	v_mov_b32_e32 v55, v127
	v_mov_b32_e32 v54, v127
	v_mov_b32_e32 v53, v127
	v_mov_b32_e32 v52, v127
	v_mov_b32_e32 v51, v127
	v_mov_b32_e32 v50, v127
	v_mov_b32_e32 v49, v127
	v_mov_b32_e32 v48, v127
	v_mov_b32_e32 v39, v127
	v_mov_b32_e32 v38, v127
	v_mov_b32_e32 v37, v127
	v_mov_b32_e32 v36, v127
	v_mov_b32_e32 v35, v127
	v_mov_b32_e32 v34, v127
	v_mov_b32_e32 v33, v127
	v_mov_b32_e32 v32, v127
	v_mov_b32_e32 v23, v127
	v_mov_b32_e32 v22, v127
	v_mov_b32_e32 v21, v127
	v_mov_b32_e32 v20, v127
	v_mov_b32_e32 v19, v127
	v_mov_b32_e32 v18, v127
	v_mov_b32_e32 v17, v127
	v_mov_b32_e32 v16, v127
	v_mov_b32_e32 v7, v127
	v_mov_b32_e32 v6, v127
	v_mov_b32_e32 v5, v127
	v_mov_b32_e32 v4, v127
	s_waitcnt lgkmcnt(0)
	v_mov_b32_e32 v3, v127
	v_mov_b32_e32 v2, v127
	v_mov_b32_e32 v1, v127
	v_mov_b32_e32 v0, v127
	s_cbranch_vccnz .LBB0_900
	s_and_b64 s[42:43], s[6:7], exec
	s_cselect_b32 s27, s31, s41
	s_cselect_b32 s29, s30, s40
	s_cselect_b32 s65, s35, s39
	s_cselect_b32 s66, s34, s38
	s_add_u32 s67, s38, 0x100
	s_addc_u32 s68, s39, 0
	s_add_u32 s38, s40, 0x200080
	s_addc_u32 s39, s41, 0
	s_mov_b32 s40, 0
	v_readfirstlane_b32 s32, v227
	s_nop 3
	s_lshr_b32 s32, s32, 6
	s_cmp_ge_u32 s32, 4
	s_cbranch_scc0 .Lprio_5
	s_setprio 1
.Lprio_5:
.LBB0_899:
	ds_read_b128 v[146:149], v156
	ds_read_b128 v[160:163], v156 offset:1024
	ds_read_b128 v[164:167], v156 offset:2048
	ds_read_b128 v[168:171], v156 offset:3072
	ds_read_b128 v[172:175], v157
	ds_read_b128 v[176:179], v157 offset:1024
	ds_read_b128 v[180:183], v157 offset:2048
	ds_read_b128 v[188:191], v157 offset:3072
	s_add_i32 s69, s40, 2
	s_add_u32 s41, s38, 0xffe00080
	s_addc_u32 s42, s39, -1
	s_cmp_eq_u32 s58, s40
	s_cselect_b32 s40, s66, s67
	s_cselect_b32 s43, s27, s42
	s_cselect_b32 s42, s29, s41
	s_cselect_b32 s41, s65, s68
	v_lshl_add_u64 v[150:151], s[38:39], 0, v[140:141]
	s_add_i32 m0, s50, 0xc000
	ds_read_b128 v[192:195], v158
	ds_read_b128 v[196:199], v158 offset:1024
	ds_read_b128 v[200:203], v158 offset:2048
	ds_read_b128 v[204:207], v158 offset:3072
	ds_read_b128 v[208:211], v158 offset:4096
	ds_read_b128 v[212:215], v158 offset:5120
	ds_read_b128 v[216:219], v158 offset:6144
	ds_read_b128 v[220:223], v158 offset:7168
	global_load_lds_dwordx4 v[150:151], off
	v_lshl_add_u64 v[150:151], s[38:39], 0, v[138:139]
	s_add_i32 m0, s50, 0xe000
	s_nop 0
	global_load_lds_dwordx4 v[150:151], off
	s_waitcnt vmcnt(8)
	s_waitcnt lgkmcnt(0)
	s_barrier
; #define PG8_STAGE(bufoff, gbase, voff) do { _Pragma("unroll") for (int _i = 0; _i < 2; ++_i) \
;         __builtin_amdgcn_global_load_lds((const unsigned*)((const char*)(gbase) + (voff)[_i]), (PG8_LAS unsigned*)(lds + (bufoff) + ldsw + _i * 8192), 16, 0, 0); } while (0)
; #define PG8_LDA(dst, b, h) do { _Pragma("unroll") for (int m = 0; m < 4; ++m) _Pragma("unroll") for (int k = 0; k < 2; ++k) dst[m][k] = *(const PG8_LAS bf16x8*)(lds + PG8_SA(b, h) + aoff + m * 2048 + k * 1024); } while (0)
; #define PG8_MMA(ai, bj, At, Bt) do { __builtin_amdgcn_s_setprio(1); _Pragma("unroll") for (int m = 0; m < 4; ++m) _Pragma("unroll") for (int n = 0; n < 2; ++n) _Pragma("unroll") for (int k = 0; k < 2; ++k) \
;         acc[ai][bj][m][n] = __builtin_amdgcn_mfma_f32_16x16x32_bf16(Bt[n][k], At[m][k], acc[ai][bj][m][n], 0, 0, 0); __builtin_amdgcn_s_setprio(0); } while (0)
; #define PG8_WAIT_V(n) asm volatile("s_waitcnt vmcnt(" #n ")" ::: "memory")
; #define PG8_WAIT_L(n) asm volatile("s_waitcnt lgkmcnt(" #n ")" ::: "memory")
; #define PG8_BAR __builtin_amdgcn_s_barrier()
; #define PG8_SCHED __builtin_amdgcn_sched_barrier(0)
; template <class Epi, class Sched, bool ALIGN_EPI = false, bool SP2 = false>
; __device__ __forceinline__ void gemm_phase(PG8_LAS unsigned char* lds, const Gemm g, const Sched& S, const Epi& E) {
;     ...
;             PG8_WAIT_V(8); PG8_WAIT_L(0); PG8_BAR; PG8_MMA(0, 0, At, B0); PG8_MMA(0, 1, At, B1); PG8_BAR; PG8_SCHED;
;             PG8_LDA(At, 0, 1); PG8_STAGE(PG8_SB(0, 0), b2, voffB); PG8_STAGE(PG8_SB(0, 1), b2 + hstepB, voffB); PG8_STAGE(PG8_SA(0, 0), a2, voffA);
;             PG8_WAIT_V(8); PG8_WAIT_L(0); PG8_BAR; PG8_MMA(1, 0, At, B0); PG8_MMA(1, 1, At, B1); PG8_BAR; PG8_SCHED;
	s_waitcnt lgkmcnt(0)
	v_mfma_f32_16x16x32_bf16 v[124:127], v[146:149], v[192:195], v[124:127]
	v_mfma_f32_16x16x32_bf16 v[120:123], v[164:167], v[192:195], v[120:123]
	v_mfma_f32_16x16x32_bf16 v[108:111], v[146:149], v[200:203], v[108:111]
	v_mfma_f32_16x16x32_bf16 v[104:107], v[164:167], v[200:203], v[104:107]
	v_mfma_f32_16x16x32_bf16 v[92:95], v[146:149], v[208:211], v[92:95]
	v_mfma_f32_16x16x32_bf16 v[88:91], v[164:167], v[208:211], v[88:91]
	v_mfma_f32_16x16x32_bf16 v[76:79], v[146:149], v[216:219], v[76:79]
	v_mfma_f32_16x16x32_bf16 v[72:75], v[164:167], v[216:219], v[72:75]
	v_mfma_f32_16x16x32_bf16 v[124:127], v[160:163], v[196:199], v[124:127]
	v_mfma_f32_16x16x32_bf16 v[120:123], v[168:171], v[196:199], v[120:123]
	v_mfma_f32_16x16x32_bf16 v[108:111], v[160:163], v[204:207], v[108:111]
	v_mfma_f32_16x16x32_bf16 v[104:107], v[168:171], v[204:207], v[104:107]
	v_mfma_f32_16x16x32_bf16 v[92:95], v[160:163], v[212:215], v[92:95]
	v_mfma_f32_16x16x32_bf16 v[88:91], v[168:171], v[212:215], v[88:91]
	v_mfma_f32_16x16x32_bf16 v[76:79], v[160:163], v[220:223], v[76:79]
	v_mfma_f32_16x16x32_bf16 v[72:75], v[168:171], v[220:223], v[72:75]
	v_mfma_f32_16x16x32_bf16 v[116:119], v[172:175], v[192:195], v[116:119]
	v_mfma_f32_16x16x32_bf16 v[112:115], v[180:183], v[192:195], v[112:115]
	v_mfma_f32_16x16x32_bf16 v[100:103], v[172:175], v[200:203], v[100:103]
	v_mfma_f32_16x16x32_bf16 v[96:99], v[180:183], v[200:203], v[96:99]
	v_mfma_f32_16x16x32_bf16 v[84:87], v[172:175], v[208:211], v[84:87]
	v_mfma_f32_16x16x32_bf16 v[80:83], v[180:183], v[208:211], v[80:83]
	v_mfma_f32_16x16x32_bf16 v[68:71], v[172:175], v[216:219], v[68:71]
	v_mfma_f32_16x16x32_bf16 v[64:67], v[180:183], v[216:219], v[64:67]
	v_mfma_f32_16x16x32_bf16 v[116:119], v[176:179], v[196:199], v[116:119]
	v_mfma_f32_16x16x32_bf16 v[112:115], v[188:191], v[196:199], v[112:115]
	v_mfma_f32_16x16x32_bf16 v[100:103], v[176:179], v[204:207], v[100:103]
	v_mfma_f32_16x16x32_bf16 v[96:99], v[188:191], v[204:207], v[96:99]
	v_mfma_f32_16x16x32_bf16 v[84:87], v[176:179], v[212:215], v[84:87]
	v_mfma_f32_16x16x32_bf16 v[80:83], v[188:191], v[212:215], v[80:83]
	v_mfma_f32_16x16x32_bf16 v[68:71], v[176:179], v[220:223], v[68:71]
	v_mfma_f32_16x16x32_bf16 v[64:67], v[188:191], v[220:223], v[64:67]
	s_barrier
	s_add_i32 s70, s59, s49
	v_lshl_add_u64 v[150:151], s[40:41], 0, v[130:131]
	s_mov_b32 m0, s70
	ds_read_b128 v[192:195], v158 offset:16384
	ds_read_b128 v[196:199], v158 offset:17408
	ds_read_b128 v[200:203], v158 offset:18432
	ds_read_b128 v[204:207], v158 offset:19456
	ds_read_b128 v[208:211], v158 offset:20480
	ds_read_b128 v[212:215], v158 offset:21504
	ds_read_b128 v[216:219], v158 offset:22528
	ds_read_b128 v[220:223], v158 offset:23552
	global_load_lds_dwordx4 v[150:151], off
	s_add_i32 m0, s70, 0x2000
	s_add_u32 s70, s40, 0x200000
	v_lshl_add_u64 v[184:185], s[40:41], 0, v[134:135]
	s_addc_u32 s71, s41, 0
	s_add_i32 s72, s60, s49
	global_load_lds_dwordx4 v[184:185], off
	v_lshl_add_u64 v[224:225], s[70:71], 0, v[130:131]
	s_mov_b32 m0, s72
	v_lshl_add_u64 v[228:229], s[42:43], 0, v[132:133]
	global_load_lds_dwordx4 v[224:225], off
	v_lshl_add_u64 v[224:225], s[70:71], 0, v[134:135]
	s_add_i32 m0, s72, 0x2000
	s_nop 0
	global_load_lds_dwordx4 v[224:225], off
	v_lshl_add_u64 v[224:225], s[42:43], 0, v[128:129]
	s_mov_b32 m0, s50
	s_nop 0
	global_load_lds_dwordx4 v[224:225], off
	s_mov_b32 m0, s51
	s_nop 0
	global_load_lds_dwordx4 v[228:229], off
	s_waitcnt vmcnt(8)
	s_waitcnt lgkmcnt(0)
	s_barrier
	s_waitcnt lgkmcnt(0)
	v_mfma_f32_16x16x32_bf16 v[60:63], v[146:149], v[192:195], v[60:63]
	v_mfma_f32_16x16x32_bf16 v[56:59], v[164:167], v[192:195], v[56:59]
	v_mfma_f32_16x16x32_bf16 v[44:47], v[146:149], v[200:203], v[44:47]
	v_mfma_f32_16x16x32_bf16 v[40:43], v[164:167], v[200:203], v[40:43]
	v_mfma_f32_16x16x32_bf16 v[28:31], v[146:149], v[208:211], v[28:31]
	v_mfma_f32_16x16x32_bf16 v[24:27], v[164:167], v[208:211], v[24:27]
	v_mfma_f32_16x16x32_bf16 v[12:15], v[146:149], v[216:219], v[12:15]
	v_mfma_f32_16x16x32_bf16 v[8:11], v[164:167], v[216:219], v[8:11]
	v_mfma_f32_16x16x32_bf16 v[60:63], v[160:163], v[196:199], v[60:63]
	v_mfma_f32_16x16x32_bf16 v[56:59], v[168:171], v[196:199], v[56:59]
	v_mfma_f32_16x16x32_bf16 v[44:47], v[160:163], v[204:207], v[44:47]
	v_mfma_f32_16x16x32_bf16 v[40:43], v[168:171], v[204:207], v[40:43]
	v_mfma_f32_16x16x32_bf16 v[28:31], v[160:163], v[212:215], v[28:31]
	v_mfma_f32_16x16x32_bf16 v[24:27], v[168:171], v[212:215], v[24:27]
	v_mfma_f32_16x16x32_bf16 v[12:15], v[160:163], v[220:223], v[12:15]
	v_mfma_f32_16x16x32_bf16 v[8:11], v[168:171], v[220:223], v[8:11]
	v_mfma_f32_16x16x32_bf16 v[52:55], v[172:175], v[192:195], v[52:55]
	v_mfma_f32_16x16x32_bf16 v[48:51], v[180:183], v[192:195], v[48:51]
	v_mfma_f32_16x16x32_bf16 v[36:39], v[172:175], v[200:203], v[36:39]
	v_mfma_f32_16x16x32_bf16 v[32:35], v[180:183], v[200:203], v[32:35]
	v_mfma_f32_16x16x32_bf16 v[20:23], v[172:175], v[208:211], v[20:23]
	v_mfma_f32_16x16x32_bf16 v[16:19], v[180:183], v[208:211], v[16:19]
	v_mfma_f32_16x16x32_bf16 v[4:7], v[172:175], v[216:219], v[4:7]
	v_mfma_f32_16x16x32_bf16 v[0:3], v[180:183], v[216:219], v[0:3]
	v_mfma_f32_16x16x32_bf16 v[52:55], v[176:179], v[196:199], v[52:55]
	v_mfma_f32_16x16x32_bf16 v[48:51], v[188:191], v[196:199], v[48:51]
	v_mfma_f32_16x16x32_bf16 v[36:39], v[176:179], v[204:207], v[36:39]
	v_mfma_f32_16x16x32_bf16 v[32:35], v[188:191], v[204:207], v[32:35]
	v_mfma_f32_16x16x32_bf16 v[20:23], v[176:179], v[212:215], v[20:23]
	v_mfma_f32_16x16x32_bf16 v[16:19], v[188:191], v[212:215], v[16:19]
	v_mfma_f32_16x16x32_bf16 v[4:7], v[176:179], v[220:223], v[4:7]
	v_mfma_f32_16x16x32_bf16 v[0:3], v[188:191], v[220:223], v[0:3]
	s_barrier
; #define PG8_STAGE(bufoff, gbase, voff) do { _Pragma("unroll") for (int _i = 0; _i < 2; ++_i) \
;         __builtin_amdgcn_global_load_lds((const unsigned*)((const char*)(gbase) + (voff)[_i]), (PG8_LAS unsigned*)(lds + (bufoff) + ldsw + _i * 8192), 16, 0, 0); } while (0)
; #define PG8_LDA(dst, b, h) do { _Pragma("unroll") for (int m = 0; m < 4; ++m) _Pragma("unroll") for (int k = 0; k < 2; ++k) dst[m][k] = *(const PG8_LAS bf16x8*)(lds + PG8_SA(b, h) + aoff + m * 2048 + k * 1024); } while (0)
; #define PG8_LDB(dst, b, h) do { _Pragma("unroll") for (int n = 0; n < 2; ++n) _Pragma("unroll") for (int k = 0; k < 2; ++k) dst[n][k] = *(const PG8_LAS bf16x8*)(lds + PG8_SB(b, h) + boff + n * 2048 + k * 1024); } while (0)
; #define PG8_MMA(ai, bj, At, Bt) do { __builtin_amdgcn_s_setprio(1); _Pragma("unroll") for (int m = 0; m < 4; ++m) _Pragma("unroll") for (int n = 0; n < 2; ++n) _Pragma("unroll") for (int k = 0; k < 2; ++k) \
;         acc[ai][bj][m][n] = __builtin_amdgcn_mfma_f32_16x16x32_bf16(Bt[n][k], At[m][k], acc[ai][bj][m][n], 0, 0, 0); __builtin_amdgcn_s_setprio(0); } while (0)
; #define PG8_WAIT_V(n) asm volatile("s_waitcnt vmcnt(" #n ")" ::: "memory")
; #define PG8_WAIT_L(n) asm volatile("s_waitcnt lgkmcnt(" #n ")" ::: "memory")
; #define PG8_BAR __builtin_amdgcn_s_barrier()
; #define PG8_SCHED __builtin_amdgcn_sched_barrier(0)
; template <class Epi, class Sched, bool ALIGN_EPI = false, bool SP2 = false>
; __device__ __forceinline__ void gemm_phase(PG8_LAS unsigned char* lds, const Gemm g, const Sched& S, const Epi& E) {
;     ...
;             PG8_LDB(B0, 1, 0); PG8_LDB(B1, 1, 1); PG8_SCHED; PG8_LDA(At, 1, 0); PG8_STAGE(PG8_SA(0, 1), a2 + hstepA, voffA);
;             PG8_WAIT_V(8); PG8_WAIT_L(0); PG8_BAR; PG8_MMA(0, 0, At, B0); PG8_MMA(0, 1, At, B1); PG8_BAR; PG8_SCHED;
	s_add_i32 s70, 0, 0x18000
	v_add_u32_e32 v159, s70, v154
	s_add_i32 s71, 0, 0x1c000
	ds_read_b128 v[146:149], v159
	ds_read_b128 v[160:163], v159 offset:1024
	ds_read_b128 v[164:167], v159 offset:2048
	ds_read_b128 v[168:171], v159 offset:3072
	v_add_u32_e32 v159, s71, v154
	ds_read_b128 v[172:175], v159
	ds_read_b128 v[176:179], v159 offset:1024
	ds_read_b128 v[180:183], v159 offset:2048
	ds_read_b128 v[188:191], v159 offset:3072
	s_add_u32 s42, s42, 0x200000
	s_addc_u32 s43, s43, 0
	s_mov_b32 m0, s52
	v_lshl_add_u64 v[230:231], s[42:43], 0, v[128:129]
	ds_read_b128 v[192:195], v158 offset:32768
	ds_read_b128 v[196:199], v158 offset:33792
	ds_read_b128 v[200:203], v158 offset:34816
	ds_read_b128 v[204:207], v158 offset:35840
	ds_read_b128 v[208:211], v158 offset:36864
	ds_read_b128 v[212:215], v158 offset:37888
	ds_read_b128 v[216:219], v158 offset:38912
	ds_read_b128 v[220:223], v158 offset:39936
	global_load_lds_dwordx4 v[230:231], off
	v_lshl_add_u64 v[230:231], s[42:43], 0, v[132:133]
	s_mov_b32 m0, s53
	s_nop 0
	global_load_lds_dwordx4 v[230:231], off
	s_waitcnt vmcnt(8)
	s_waitcnt lgkmcnt(0)
	s_barrier
	s_waitcnt lgkmcnt(0)
	v_mfma_f32_16x16x32_bf16 v[124:127], v[146:149], v[192:195], v[124:127]
	v_mfma_f32_16x16x32_bf16 v[120:123], v[164:167], v[192:195], v[120:123]
	v_mfma_f32_16x16x32_bf16 v[108:111], v[146:149], v[200:203], v[108:111]
	v_mfma_f32_16x16x32_bf16 v[104:107], v[164:167], v[200:203], v[104:107]
	v_mfma_f32_16x16x32_bf16 v[92:95], v[146:149], v[208:211], v[92:95]
	v_mfma_f32_16x16x32_bf16 v[88:91], v[164:167], v[208:211], v[88:91]
	v_mfma_f32_16x16x32_bf16 v[76:79], v[146:149], v[216:219], v[76:79]
	v_mfma_f32_16x16x32_bf16 v[72:75], v[164:167], v[216:219], v[72:75]
	v_mfma_f32_16x16x32_bf16 v[124:127], v[160:163], v[196:199], v[124:127]
	v_mfma_f32_16x16x32_bf16 v[120:123], v[168:171], v[196:199], v[120:123]
	v_mfma_f32_16x16x32_bf16 v[108:111], v[160:163], v[204:207], v[108:111]
	v_mfma_f32_16x16x32_bf16 v[104:107], v[168:171], v[204:207], v[104:107]
	v_mfma_f32_16x16x32_bf16 v[92:95], v[160:163], v[212:215], v[92:95]
	v_mfma_f32_16x16x32_bf16 v[88:91], v[168:171], v[212:215], v[88:91]
	v_mfma_f32_16x16x32_bf16 v[76:79], v[160:163], v[220:223], v[76:79]
	v_mfma_f32_16x16x32_bf16 v[72:75], v[168:171], v[220:223], v[72:75]
	v_mfma_f32_16x16x32_bf16 v[116:119], v[172:175], v[192:195], v[116:119]
	v_mfma_f32_16x16x32_bf16 v[112:115], v[180:183], v[192:195], v[112:115]
	v_mfma_f32_16x16x32_bf16 v[100:103], v[172:175], v[200:203], v[100:103]
	v_mfma_f32_16x16x32_bf16 v[96:99], v[180:183], v[200:203], v[96:99]
	v_mfma_f32_16x16x32_bf16 v[84:87], v[172:175], v[208:211], v[84:87]
	v_mfma_f32_16x16x32_bf16 v[80:83], v[180:183], v[208:211], v[80:83]
	v_mfma_f32_16x16x32_bf16 v[68:71], v[172:175], v[216:219], v[68:71]
	v_mfma_f32_16x16x32_bf16 v[64:67], v[180:183], v[216:219], v[64:67]
	v_mfma_f32_16x16x32_bf16 v[116:119], v[176:179], v[196:199], v[116:119]
	v_mfma_f32_16x16x32_bf16 v[112:115], v[188:191], v[196:199], v[112:115]
	v_mfma_f32_16x16x32_bf16 v[100:103], v[176:179], v[204:207], v[100:103]
	v_mfma_f32_16x16x32_bf16 v[96:99], v[188:191], v[204:207], v[96:99]
	v_mfma_f32_16x16x32_bf16 v[84:87], v[176:179], v[212:215], v[84:87]
	v_mfma_f32_16x16x32_bf16 v[80:83], v[188:191], v[212:215], v[80:83]
	v_mfma_f32_16x16x32_bf16 v[68:71], v[176:179], v[220:223], v[68:71]
	v_mfma_f32_16x16x32_bf16 v[64:67], v[188:191], v[220:223], v[64:67]
	s_barrier
; #define PG8_STAGE(bufoff, gbase, voff) do { _Pragma("unroll") for (int _i = 0; _i < 2; ++_i) \
;         __builtin_amdgcn_global_load_lds((const unsigned*)((const char*)(gbase) + (voff)[_i]), (PG8_LAS unsigned*)(lds + (bufoff) + ldsw + _i * 8192), 16, 0, 0); } while (0)
; #define PG8_LDA(dst, b, h) do { _Pragma("unroll") for (int m = 0; m < 4; ++m) _Pragma("unroll") for (int k = 0; k < 2; ++k) dst[m][k] = *(const PG8_LAS bf16x8*)(lds + PG8_SA(b, h) + aoff + m * 2048 + k * 1024); } while (0)
; #define PG8_MMA(ai, bj, At, Bt) do { __builtin_amdgcn_s_setprio(1); _Pragma("unroll") for (int m = 0; m < 4; ++m) _Pragma("unroll") for (int n = 0; n < 2; ++n) _Pragma("unroll") for (int k = 0; k < 2; ++k) \
;         acc[ai][bj][m][n] = __builtin_amdgcn_mfma_f32_16x16x32_bf16(Bt[n][k], At[m][k], acc[ai][bj][m][n], 0, 0, 0); __builtin_amdgcn_s_setprio(0); } while (0)
; #define PG8_WAIT_V(n) asm volatile("s_waitcnt vmcnt(" #n ")" ::: "memory")
; #define PG8_WAIT_L(n) asm volatile("s_waitcnt lgkmcnt(" #n ")" ::: "memory")
; #define PG8_BAR __builtin_amdgcn_s_barrier()
; #define PG8_SCHED __builtin_amdgcn_sched_barrier(0)
; template <class Epi, class Sched, bool ALIGN_EPI = false, bool SP2 = false>
; __device__ __forceinline__ void gemm_phase(PG8_LAS unsigned char* lds, const Gemm g, const Sched& S, const Epi& E) {
;     ...
;         for (int t = 0; t < nt; t += 2) {
;     ...
;             PG8_LDA(At, 1, 1); PG8_STAGE(PG8_SB(1, 0), b3, voffB); PG8_STAGE(PG8_SB(1, 1), b3 + hstepB, voffB); PG8_STAGE(PG8_SA(1, 0), a3, voffA);
;             PG8_WAIT_V(8); PG8_WAIT_L(0); PG8_BAR; PG8_MMA(1, 0, At, B0); PG8_MMA(1, 1, At, B1); PG8_BAR; PG8_SCHED;
	s_add_i32 s42, s70, s49
	v_lshl_add_u64 v[150:151], v[150:151], 0, s[10:11]
	s_mov_b32 m0, s42
	ds_read_b128 v[192:195], v158 offset:49152
	ds_read_b128 v[196:199], v158 offset:50176
	ds_read_b128 v[200:203], v158 offset:51200
	ds_read_b128 v[204:207], v158 offset:52224
	ds_read_b128 v[208:211], v158 offset:53248
	ds_read_b128 v[212:215], v158 offset:54272
	ds_read_b128 v[216:219], v158 offset:55296
	ds_read_b128 v[220:223], v158 offset:56320
	global_load_lds_dwordx4 v[150:151], off
	s_add_i32 m0, s42, 0x2000
	s_add_u32 s40, s40, 0x200080
	v_lshl_add_u64 v[150:151], v[184:185], 0, s[10:11]
	s_addc_u32 s41, s41, 0
	s_add_i32 s42, s71, s49
	global_load_lds_dwordx4 v[150:151], off
	v_lshl_add_u64 v[150:151], s[40:41], 0, v[130:131]
	s_mov_b32 m0, s42
	s_nop 0
	global_load_lds_dwordx4 v[150:151], off
	v_lshl_add_u64 v[150:151], s[40:41], 0, v[134:135]
	s_add_i32 m0, s42, 0x2000
	s_nop 0
	global_load_lds_dwordx4 v[150:151], off
	v_lshl_add_u64 v[150:151], v[224:225], 0, s[10:11]
	s_mov_b32 m0, s56
	s_nop 0
	global_load_lds_dwordx4 v[150:151], off
	v_lshl_add_u64 v[150:151], v[228:229], 0, s[10:11]
	s_mov_b32 m0, s57
	s_nop 0
	global_load_lds_dwordx4 v[150:151], off
	s_waitcnt vmcnt(8)
	s_waitcnt lgkmcnt(0)
	s_barrier
	s_waitcnt lgkmcnt(0)
	v_mfma_f32_16x16x32_bf16 v[60:63], v[146:149], v[192:195], v[60:63]
	v_mfma_f32_16x16x32_bf16 v[56:59], v[164:167], v[192:195], v[56:59]
	v_mfma_f32_16x16x32_bf16 v[44:47], v[146:149], v[200:203], v[44:47]
	v_mfma_f32_16x16x32_bf16 v[40:43], v[164:167], v[200:203], v[40:43]
	v_mfma_f32_16x16x32_bf16 v[28:31], v[146:149], v[208:211], v[28:31]
	v_mfma_f32_16x16x32_bf16 v[24:27], v[164:167], v[208:211], v[24:27]
	v_mfma_f32_16x16x32_bf16 v[12:15], v[146:149], v[216:219], v[12:15]
	v_mfma_f32_16x16x32_bf16 v[8:11], v[164:167], v[216:219], v[8:11]
	v_mfma_f32_16x16x32_bf16 v[60:63], v[160:163], v[196:199], v[60:63]
	v_mfma_f32_16x16x32_bf16 v[56:59], v[168:171], v[196:199], v[56:59]
	v_mfma_f32_16x16x32_bf16 v[44:47], v[160:163], v[204:207], v[44:47]
	v_mfma_f32_16x16x32_bf16 v[40:43], v[168:171], v[204:207], v[40:43]
	v_mfma_f32_16x16x32_bf16 v[28:31], v[160:163], v[212:215], v[28:31]
	v_mfma_f32_16x16x32_bf16 v[24:27], v[168:171], v[212:215], v[24:27]
	v_mfma_f32_16x16x32_bf16 v[12:15], v[160:163], v[220:223], v[12:15]
	v_mfma_f32_16x16x32_bf16 v[8:11], v[168:171], v[220:223], v[8:11]
	v_mfma_f32_16x16x32_bf16 v[52:55], v[172:175], v[192:195], v[52:55]
	v_mfma_f32_16x16x32_bf16 v[48:51], v[180:183], v[192:195], v[48:51]
	v_mfma_f32_16x16x32_bf16 v[36:39], v[172:175], v[200:203], v[36:39]
	v_mfma_f32_16x16x32_bf16 v[32:35], v[180:183], v[200:203], v[32:35]
	v_mfma_f32_16x16x32_bf16 v[20:23], v[172:175], v[208:211], v[20:23]
	v_mfma_f32_16x16x32_bf16 v[16:19], v[180:183], v[208:211], v[16:19]
	v_mfma_f32_16x16x32_bf16 v[4:7], v[172:175], v[216:219], v[4:7]
	v_mfma_f32_16x16x32_bf16 v[0:3], v[180:183], v[216:219], v[0:3]
	v_mfma_f32_16x16x32_bf16 v[52:55], v[176:179], v[196:199], v[52:55]
	v_mfma_f32_16x16x32_bf16 v[48:51], v[188:191], v[196:199], v[48:51]
	v_mfma_f32_16x16x32_bf16 v[36:39], v[176:179], v[204:207], v[36:39]
	v_mfma_f32_16x16x32_bf16 v[32:35], v[188:191], v[204:207], v[32:35]
	v_mfma_f32_16x16x32_bf16 v[20:23], v[176:179], v[212:215], v[20:23]
	v_mfma_f32_16x16x32_bf16 v[16:19], v[188:191], v[212:215], v[16:19]
	v_mfma_f32_16x16x32_bf16 v[4:7], v[176:179], v[220:223], v[4:7]
	v_mfma_f32_16x16x32_bf16 v[0:3], v[188:191], v[220:223], v[0:3]
	s_barrier
	s_add_u32 s67, s67, 0x100
	s_addc_u32 s68, s68, 0
	s_add_u32 s38, s38, 0x100
	s_addc_u32 s39, s39, 0
	s_cmp_ge_i32 s69, s55
	s_mov_b32 s40, s69
	s_cbranch_scc0 .LBB0_899
	s_setprio 0

; #define PG8_STAGE(bufoff, gbase, voff) do { _Pragma("unroll") for (int _i = 0; _i < 2; ++_i) \
;         __builtin_amdgcn_global_load_lds((const unsigned*)((const char*)(gbase) + (voff)[_i]), (PG8_LAS unsigned*)(lds + (bufoff) + ldsw + _i * 8192), 16, 0, 0); } while (0)
; #define PG8_LDA(dst, b, h) do { _Pragma("unroll") for (int m = 0; m < 4; ++m) _Pragma("unroll") for (int k = 0; k < 2; ++k) dst[m][k] = *(const PG8_LAS bf16x8*)(lds + PG8_SA(b, h) + aoff + m * 2048 + k * 1024); } while (0)
; #define PG8_LDB(dst, b, h) do { _Pragma("unroll") for (int n = 0; n < 2; ++n) _Pragma("unroll") for (int k = 0; k < 2; ++k) dst[n][k] = *(const PG8_LAS bf16x8*)(lds + PG8_SB(b, h) + boff + n * 2048 + k * 1024); } while (0)
; #define PG8_MMA(ai, bj, At, Bt) do { __builtin_amdgcn_s_setprio(1); _Pragma("unroll") for (int m = 0; m < 4; ++m) _Pragma("unroll") for (int n = 0; n < 2; ++n) _Pragma("unroll") for (int k = 0; k < 2; ++k) \
;         acc[ai][bj][m][n] = __builtin_amdgcn_mfma_f32_16x16x32_bf16(Bt[n][k], At[m][k], acc[ai][bj][m][n], 0, 0, 0); __builtin_amdgcn_s_setprio(0); } while (0)
; #define PG8_WAIT_V(n) asm volatile("s_waitcnt vmcnt(" #n ")" ::: "memory")
; #define PG8_WAIT_L(n) asm volatile("s_waitcnt lgkmcnt(" #n ")" ::: "memory")
; #define PG8_BAR __builtin_amdgcn_s_barrier()
; #define PG8_SCHED __builtin_amdgcn_sched_barrier(0)
; template <class Epi, class Sched, bool ALIGN_EPI = false, bool SP2 = false>
; __device__ __forceinline__ void gemm_phase(PG8_LAS unsigned char* lds, const Gemm g, const Sched& S, const Epi& E) {
;     ...
;             PG8_LDB(B0, 0, 0); PG8_LDB(B1, 0, 1); PG8_SCHED; PG8_LDA(At, 0, 0); PG8_STAGE(PG8_SA(1, 1), a1 + hstepA, voffA);
;             PG8_WAIT_V(8); PG8_WAIT_L(0); PG8_BAR; PG8_MMA(0, 0, At, B0); PG8_MMA(0, 1, At, B1); PG8_BAR; PG8_SCHED;
;     ...
;         for (int a = 0; a < 2; ++a)
; #pragma unroll
;             for (int b = 0; b < 2; ++b)
; #pragma unroll
;                 for (int m = 0; m < 4; ++m)
; #pragma unroll
;                     for (int n = 0; n < 2; ++n) acc[a][b][m][n] = (f32x4){0.f, 0.f, 0.f, 0.f};
;         cur = nxt; cA = nA; cB = nB; ++ui;
.LBB0_986:
	s_ashr_i32 s35, s34, 31
	s_lshl_b64 s[36:37], s[34:35], 17
	s_add_u32 s36, s48, s36
	s_addc_u32 s37, s49, s37
	s_ashr_i32 s31, s30, 31
	s_lshl_b64 s[38:39], s[30:31], 17
	s_add_u32 s38, s50, s38
	v_mov_b32_e32 v127, 0
	s_addc_u32 s39, s51, s39
	s_and_b64 vcc, exec, s[6:7]
	v_mov_b32_e32 v126, v127
	v_mov_b32_e32 v125, v127
	v_mov_b32_e32 v124, v127
	v_mov_b32_e32 v123, v127
	v_mov_b32_e32 v122, v127
	v_mov_b32_e32 v121, v127
	v_mov_b32_e32 v120, v127
	v_mov_b32_e32 v111, v127
	v_mov_b32_e32 v110, v127
	v_mov_b32_e32 v109, v127
	v_mov_b32_e32 v108, v127
	v_mov_b32_e32 v107, v127
	v_mov_b32_e32 v106, v127
	v_mov_b32_e32 v105, v127
	v_mov_b32_e32 v104, v127
	v_mov_b32_e32 v95, v127
	v_mov_b32_e32 v94, v127
	v_mov_b32_e32 v93, v127
	v_mov_b32_e32 v92, v127
	v_mov_b32_e32 v91, v127
	v_mov_b32_e32 v90, v127
	v_mov_b32_e32 v89, v127
	v_mov_b32_e32 v88, v127
	v_mov_b32_e32 v79, v127
	v_mov_b32_e32 v78, v127
	v_mov_b32_e32 v77, v127
	v_mov_b32_e32 v76, v127
	v_mov_b32_e32 v75, v127
	v_mov_b32_e32 v74, v127
	v_mov_b32_e32 v73, v127
	v_mov_b32_e32 v72, v127
	v_mov_b32_e32 v119, v127
	v_mov_b32_e32 v118, v127
	v_mov_b32_e32 v117, v127
	v_mov_b32_e32 v116, v127
	v_mov_b32_e32 v115, v127
	v_mov_b32_e32 v114, v127
	v_mov_b32_e32 v113, v127
	v_mov_b32_e32 v112, v127
	v_mov_b32_e32 v103, v127
	v_mov_b32_e32 v102, v127
	v_mov_b32_e32 v101, v127
	v_mov_b32_e32 v100, v127
	v_mov_b32_e32 v99, v127
	v_mov_b32_e32 v98, v127
	v_mov_b32_e32 v97, v127
	v_mov_b32_e32 v96, v127
	v_mov_b32_e32 v87, v127
	v_mov_b32_e32 v86, v127
	v_mov_b32_e32 v85, v127
	v_mov_b32_e32 v84, v127
	v_mov_b32_e32 v83, v127
	v_mov_b32_e32 v82, v127
	v_mov_b32_e32 v81, v127
	v_mov_b32_e32 v80, v127
	v_mov_b32_e32 v71, v127
	v_mov_b32_e32 v70, v127
	v_mov_b32_e32 v69, v127
	v_mov_b32_e32 v68, v127
	v_mov_b32_e32 v67, v127
	v_mov_b32_e32 v66, v127
	v_mov_b32_e32 v65, v127
	v_mov_b32_e32 v64, v127
	v_mov_b32_e32 v63, v127
	v_mov_b32_e32 v62, v127
	v_mov_b32_e32 v61, v127
	v_mov_b32_e32 v60, v127
	v_mov_b32_e32 v59, v127
	v_mov_b32_e32 v58, v127
	v_mov_b32_e32 v57, v127
	v_mov_b32_e32 v56, v127
	v_mov_b32_e32 v47, v127
	v_mov_b32_e32 v46, v127
	v_mov_b32_e32 v45, v127
	v_mov_b32_e32 v44, v127
	v_mov_b32_e32 v43, v127
	v_mov_b32_e32 v42, v127
	v_mov_b32_e32 v41, v127
	v_mov_b32_e32 v40, v127
	v_mov_b32_e32 v31, v127
	v_mov_b32_e32 v30, v127
	v_mov_b32_e32 v29, v127
	v_mov_b32_e32 v28, v127
	v_mov_b32_e32 v27, v127
	v_mov_b32_e32 v26, v127
	v_mov_b32_e32 v25, v127
	v_mov_b32_e32 v24, v127
	v_mov_b32_e32 v15, v127
	v_mov_b32_e32 v14, v127
	v_mov_b32_e32 v13, v127
	v_mov_b32_e32 v12, v127
	v_mov_b32_e32 v11, v127
	v_mov_b32_e32 v10, v127
	v_mov_b32_e32 v9, v127
	v_mov_b32_e32 v8, v127
	v_mov_b32_e32 v55, v127
	v_mov_b32_e32 v54, v127
	v_mov_b32_e32 v53, v127
	v_mov_b32_e32 v52, v127
	v_mov_b32_e32 v51, v127
	v_mov_b32_e32 v50, v127
	v_mov_b32_e32 v49, v127
	v_mov_b32_e32 v48, v127
	v_mov_b32_e32 v39, v127
	v_mov_b32_e32 v38, v127
	v_mov_b32_e32 v37, v127
	v_mov_b32_e32 v36, v127
	v_mov_b32_e32 v35, v127
	v_mov_b32_e32 v34, v127
	v_mov_b32_e32 v33, v127
	v_mov_b32_e32 v32, v127
	v_mov_b32_e32 v23, v127
	v_mov_b32_e32 v22, v127
	v_mov_b32_e32 v21, v127
	v_mov_b32_e32 v20, v127
	v_mov_b32_e32 v19, v127
	v_mov_b32_e32 v18, v127
	v_mov_b32_e32 v17, v127
	v_mov_b32_e32 v16, v127
	v_mov_b32_e32 v7, v127
	v_mov_b32_e32 v6, v127
	v_mov_b32_e32 v5, v127
	v_mov_b32_e32 v4, v127
	v_mov_b32_e32 v3, v127
	v_mov_b32_e32 v2, v127
	v_mov_b32_e32 v1, v127
	v_mov_b32_e32 v0, v127
	s_cbranch_vccnz .LBB0_989
	s_and_b64 s[44:45], s[8:9], exec
	s_cselect_b32 s31, s37, s43
	s_cselect_b32 s35, s36, s42
	s_cselect_b32 s67, s39, s41
	s_cselect_b32 s68, s38, s40
	s_add_u32 s69, s40, 0x100
	s_addc_u32 s70, s41, 0
	s_add_u32 s40, s42, 0x10080
	s_addc_u32 s41, s43, 0
	s_mov_b32 s42, 0
	v_readfirstlane_b32 s32, v227
	s_nop 3
	s_lshr_b32 s32, s32, 6
	s_cmp_ge_u32 s32, 4
	s_cbranch_scc0 .Lprio_6
	s_setprio 1
.Lprio_6:
.LBB0_988:
	ds_read_b128 v[150:153], v147
	ds_read_b128 v[154:157], v147 offset:1024
	ds_read_b128 v[158:161], v147 offset:2048
	ds_read_b128 v[162:165], v147 offset:3072
	ds_read_b128 v[166:169], v148
	ds_read_b128 v[170:173], v148 offset:1024
	ds_read_b128 v[174:177], v148 offset:2048
	ds_read_b128 v[178:181], v148 offset:3072
	s_add_i32 s71, s42, 2
	s_add_u32 s43, s40, 0xffff0080
	s_addc_u32 s44, s41, -1
	s_cmp_eq_u32 s60, s42
	s_cselect_b32 s42, s68, s69
	s_cselect_b32 s45, s31, s44
	s_cselect_b32 s44, s35, s43
	s_cselect_b32 s43, s67, s70
	v_lshl_add_u64 v[216:217], s[40:41], 0, v[138:139]
	s_add_i32 m0, s29, 0xc000
	ds_read_b128 v[182:185], v149
	ds_read_b128 v[188:191], v149 offset:1024
	ds_read_b128 v[192:195], v149 offset:2048
	ds_read_b128 v[196:199], v149 offset:3072
	ds_read_b128 v[200:203], v149 offset:4096
	ds_read_b128 v[204:207], v149 offset:5120
	ds_read_b128 v[208:211], v149 offset:6144
	ds_read_b128 v[212:215], v149 offset:7168
	global_load_lds_dwordx4 v[216:217], off
	v_lshl_add_u64 v[216:217], s[40:41], 0, v[136:137]
	s_add_i32 m0, s29, 0xe000
	s_nop 0
	global_load_lds_dwordx4 v[216:217], off
	s_waitcnt vmcnt(8)
	s_waitcnt lgkmcnt(0)
	s_barrier
; #define PG8_STAGE(bufoff, gbase, voff) do { _Pragma("unroll") for (int _i = 0; _i < 2; ++_i) \
;         __builtin_amdgcn_global_load_lds((const unsigned*)((const char*)(gbase) + (voff)[_i]), (PG8_LAS unsigned*)(lds + (bufoff) + ldsw + _i * 8192), 16, 0, 0); } while (0)
; #define PG8_LDA(dst, b, h) do { _Pragma("unroll") for (int m = 0; m < 4; ++m) _Pragma("unroll") for (int k = 0; k < 2; ++k) dst[m][k] = *(const PG8_LAS bf16x8*)(lds + PG8_SA(b, h) + aoff + m * 2048 + k * 1024); } while (0)
; #define PG8_MMA(ai, bj, At, Bt) do { __builtin_amdgcn_s_setprio(1); _Pragma("unroll") for (int m = 0; m < 4; ++m) _Pragma("unroll") for (int n = 0; n < 2; ++n) _Pragma("unroll") for (int k = 0; k < 2; ++k) \
;         acc[ai][bj][m][n] = __builtin_amdgcn_mfma_f32_16x16x32_bf16(Bt[n][k], At[m][k], acc[ai][bj][m][n], 0, 0, 0); __builtin_amdgcn_s_setprio(0); } while (0)
; #define PG8_WAIT_V(n) asm volatile("s_waitcnt vmcnt(" #n ")" ::: "memory")
; #define PG8_WAIT_L(n) asm volatile("s_waitcnt lgkmcnt(" #n ")" ::: "memory")
; #define PG8_BAR __builtin_amdgcn_s_barrier()
; #define PG8_SCHED __builtin_amdgcn_sched_barrier(0)
; template <class Epi, class Sched, bool ALIGN_EPI = false, bool SP2 = false>
; __device__ __forceinline__ void gemm_phase(PG8_LAS unsigned char* lds, const Gemm g, const Sched& S, const Epi& E) {
;     ...
;             PG8_WAIT_V(8); PG8_WAIT_L(0); PG8_BAR; PG8_MMA(0, 0, At, B0); PG8_MMA(0, 1, At, B1); PG8_BAR; PG8_SCHED;
;             PG8_LDA(At, 0, 1); PG8_STAGE(PG8_SB(0, 0), b2, voffB); PG8_STAGE(PG8_SB(0, 1), b2 + hstepB, voffB); PG8_STAGE(PG8_SA(0, 0), a2, voffA);
;             PG8_WAIT_V(8); PG8_WAIT_L(0); PG8_BAR; PG8_MMA(1, 0, At, B0); PG8_MMA(1, 1, At, B1); PG8_BAR; PG8_SCHED;
	s_waitcnt lgkmcnt(0)
	v_mfma_f32_16x16x32_bf16 v[124:127], v[150:153], v[182:185], v[124:127]
	v_mfma_f32_16x16x32_bf16 v[120:123], v[158:161], v[182:185], v[120:123]
	v_mfma_f32_16x16x32_bf16 v[108:111], v[150:153], v[192:195], v[108:111]
	v_mfma_f32_16x16x32_bf16 v[104:107], v[158:161], v[192:195], v[104:107]
	v_mfma_f32_16x16x32_bf16 v[92:95], v[150:153], v[200:203], v[92:95]
	v_mfma_f32_16x16x32_bf16 v[88:91], v[158:161], v[200:203], v[88:91]
	v_mfma_f32_16x16x32_bf16 v[76:79], v[150:153], v[208:211], v[76:79]
	v_mfma_f32_16x16x32_bf16 v[72:75], v[158:161], v[208:211], v[72:75]
	v_mfma_f32_16x16x32_bf16 v[124:127], v[154:157], v[188:191], v[124:127]
	v_mfma_f32_16x16x32_bf16 v[120:123], v[162:165], v[188:191], v[120:123]
	v_mfma_f32_16x16x32_bf16 v[108:111], v[154:157], v[196:199], v[108:111]
	v_mfma_f32_16x16x32_bf16 v[104:107], v[162:165], v[196:199], v[104:107]
	v_mfma_f32_16x16x32_bf16 v[92:95], v[154:157], v[204:207], v[92:95]
	v_mfma_f32_16x16x32_bf16 v[88:91], v[162:165], v[204:207], v[88:91]
	v_mfma_f32_16x16x32_bf16 v[76:79], v[154:157], v[212:215], v[76:79]
	v_mfma_f32_16x16x32_bf16 v[72:75], v[162:165], v[212:215], v[72:75]
	v_mfma_f32_16x16x32_bf16 v[116:119], v[166:169], v[182:185], v[116:119]
	v_mfma_f32_16x16x32_bf16 v[112:115], v[174:177], v[182:185], v[112:115]
	v_mfma_f32_16x16x32_bf16 v[100:103], v[166:169], v[192:195], v[100:103]
	v_mfma_f32_16x16x32_bf16 v[96:99], v[174:177], v[192:195], v[96:99]
	v_mfma_f32_16x16x32_bf16 v[84:87], v[166:169], v[200:203], v[84:87]
	v_mfma_f32_16x16x32_bf16 v[80:83], v[174:177], v[200:203], v[80:83]
	v_mfma_f32_16x16x32_bf16 v[68:71], v[166:169], v[208:211], v[68:71]
	v_mfma_f32_16x16x32_bf16 v[64:67], v[174:177], v[208:211], v[64:67]
	v_mfma_f32_16x16x32_bf16 v[116:119], v[170:173], v[188:191], v[116:119]
	v_mfma_f32_16x16x32_bf16 v[112:115], v[178:181], v[188:191], v[112:115]
	v_mfma_f32_16x16x32_bf16 v[100:103], v[170:173], v[196:199], v[100:103]
	v_mfma_f32_16x16x32_bf16 v[96:99], v[178:181], v[196:199], v[96:99]
	v_mfma_f32_16x16x32_bf16 v[84:87], v[170:173], v[204:207], v[84:87]
	v_mfma_f32_16x16x32_bf16 v[80:83], v[178:181], v[204:207], v[80:83]
	v_mfma_f32_16x16x32_bf16 v[68:71], v[170:173], v[212:215], v[68:71]
	v_mfma_f32_16x16x32_bf16 v[64:67], v[178:181], v[212:215], v[64:67]
	s_barrier
	s_add_i32 s72, s61, s52
	v_lshl_add_u64 v[216:217], s[42:43], 0, v[130:131]
	s_mov_b32 m0, s72
	ds_read_b128 v[182:185], v149 offset:16384
	ds_read_b128 v[188:191], v149 offset:17408
	ds_read_b128 v[192:195], v149 offset:18432
	ds_read_b128 v[196:199], v149 offset:19456
	ds_read_b128 v[200:203], v149 offset:20480
	ds_read_b128 v[204:207], v149 offset:21504
	ds_read_b128 v[208:211], v149 offset:22528
	ds_read_b128 v[212:215], v149 offset:23552
	global_load_lds_dwordx4 v[216:217], off
	s_add_i32 m0, s72, 0x2000
	s_add_u32 s72, s42, 0x10000
	v_lshl_add_u64 v[218:219], s[42:43], 0, v[134:135]
	s_addc_u32 s73, s43, 0
	s_add_i32 s74, s62, s52
	global_load_lds_dwordx4 v[218:219], off
	v_lshl_add_u64 v[220:221], s[72:73], 0, v[130:131]
	s_mov_b32 m0, s74
	v_lshl_add_u64 v[222:223], s[44:45], 0, v[132:133]
	global_load_lds_dwordx4 v[220:221], off
	v_lshl_add_u64 v[220:221], s[72:73], 0, v[134:135]
	s_add_i32 m0, s74, 0x2000
	s_nop 0
	global_load_lds_dwordx4 v[220:221], off
	v_lshl_add_u64 v[220:221], s[44:45], 0, v[128:129]
	s_mov_b32 m0, s29
	s_nop 0
	global_load_lds_dwordx4 v[220:221], off
	s_mov_b32 m0, s53
	s_nop 0
	global_load_lds_dwordx4 v[222:223], off
	s_waitcnt vmcnt(8)
	s_waitcnt lgkmcnt(0)
	s_barrier
	s_waitcnt lgkmcnt(0)
	v_mfma_f32_16x16x32_bf16 v[60:63], v[150:153], v[182:185], v[60:63]
	v_mfma_f32_16x16x32_bf16 v[56:59], v[158:161], v[182:185], v[56:59]
	v_mfma_f32_16x16x32_bf16 v[44:47], v[150:153], v[192:195], v[44:47]
	v_mfma_f32_16x16x32_bf16 v[40:43], v[158:161], v[192:195], v[40:43]
	v_mfma_f32_16x16x32_bf16 v[28:31], v[150:153], v[200:203], v[28:31]
	v_mfma_f32_16x16x32_bf16 v[24:27], v[158:161], v[200:203], v[24:27]
	v_mfma_f32_16x16x32_bf16 v[12:15], v[150:153], v[208:211], v[12:15]
	v_mfma_f32_16x16x32_bf16 v[8:11], v[158:161], v[208:211], v[8:11]
	v_mfma_f32_16x16x32_bf16 v[60:63], v[154:157], v[188:191], v[60:63]
	v_mfma_f32_16x16x32_bf16 v[56:59], v[162:165], v[188:191], v[56:59]
	v_mfma_f32_16x16x32_bf16 v[44:47], v[154:157], v[196:199], v[44:47]
	v_mfma_f32_16x16x32_bf16 v[40:43], v[162:165], v[196:199], v[40:43]
	v_mfma_f32_16x16x32_bf16 v[28:31], v[154:157], v[204:207], v[28:31]
	v_mfma_f32_16x16x32_bf16 v[24:27], v[162:165], v[204:207], v[24:27]
	v_mfma_f32_16x16x32_bf16 v[12:15], v[154:157], v[212:215], v[12:15]
	v_mfma_f32_16x16x32_bf16 v[8:11], v[162:165], v[212:215], v[8:11]
	v_mfma_f32_16x16x32_bf16 v[52:55], v[166:169], v[182:185], v[52:55]
	v_mfma_f32_16x16x32_bf16 v[48:51], v[174:177], v[182:185], v[48:51]
	v_mfma_f32_16x16x32_bf16 v[36:39], v[166:169], v[192:195], v[36:39]
	v_mfma_f32_16x16x32_bf16 v[32:35], v[174:177], v[192:195], v[32:35]
	v_mfma_f32_16x16x32_bf16 v[20:23], v[166:169], v[200:203], v[20:23]
	v_mfma_f32_16x16x32_bf16 v[16:19], v[174:177], v[200:203], v[16:19]
	v_mfma_f32_16x16x32_bf16 v[4:7], v[166:169], v[208:211], v[4:7]
	v_mfma_f32_16x16x32_bf16 v[0:3], v[174:177], v[208:211], v[0:3]
	v_mfma_f32_16x16x32_bf16 v[52:55], v[170:173], v[188:191], v[52:55]
	v_mfma_f32_16x16x32_bf16 v[48:51], v[178:181], v[188:191], v[48:51]
	v_mfma_f32_16x16x32_bf16 v[36:39], v[170:173], v[196:199], v[36:39]
	v_mfma_f32_16x16x32_bf16 v[32:35], v[178:181], v[196:199], v[32:35]
	v_mfma_f32_16x16x32_bf16 v[20:23], v[170:173], v[204:207], v[20:23]
	v_mfma_f32_16x16x32_bf16 v[16:19], v[178:181], v[204:207], v[16:19]
	v_mfma_f32_16x16x32_bf16 v[4:7], v[170:173], v[212:215], v[4:7]
	v_mfma_f32_16x16x32_bf16 v[0:3], v[178:181], v[212:215], v[0:3]
	s_barrier
; #define PG8_STAGE(bufoff, gbase, voff) do { _Pragma("unroll") for (int _i = 0; _i < 2; ++_i) \
;         __builtin_amdgcn_global_load_lds((const unsigned*)((const char*)(gbase) + (voff)[_i]), (PG8_LAS unsigned*)(lds + (bufoff) + ldsw + _i * 8192), 16, 0, 0); } while (0)
; #define PG8_LDA(dst, b, h) do { _Pragma("unroll") for (int m = 0; m < 4; ++m) _Pragma("unroll") for (int k = 0; k < 2; ++k) dst[m][k] = *(const PG8_LAS bf16x8*)(lds + PG8_SA(b, h) + aoff + m * 2048 + k * 1024); } while (0)
; #define PG8_LDB(dst, b, h) do { _Pragma("unroll") for (int n = 0; n < 2; ++n) _Pragma("unroll") for (int k = 0; k < 2; ++k) dst[n][k] = *(const PG8_LAS bf16x8*)(lds + PG8_SB(b, h) + boff + n * 2048 + k * 1024); } while (0)
; #define PG8_MMA(ai, bj, At, Bt) do { __builtin_amdgcn_s_setprio(1); _Pragma("unroll") for (int m = 0; m < 4; ++m) _Pragma("unroll") for (int n = 0; n < 2; ++n) _Pragma("unroll") for (int k = 0; k < 2; ++k) \
;         acc[ai][bj][m][n] = __builtin_amdgcn_mfma_f32_16x16x32_bf16(Bt[n][k], At[m][k], acc[ai][bj][m][n], 0, 0, 0); __builtin_amdgcn_s_setprio(0); } while (0)
; #define PG8_WAIT_V(n) asm volatile("s_waitcnt vmcnt(" #n ")" ::: "memory")
; #define PG8_WAIT_L(n) asm volatile("s_waitcnt lgkmcnt(" #n ")" ::: "memory")
; #define PG8_BAR __builtin_amdgcn_s_barrier()
; #define PG8_SCHED __builtin_amdgcn_sched_barrier(0)
; template <class Epi, class Sched, bool ALIGN_EPI = false, bool SP2 = false>
; __device__ __forceinline__ void gemm_phase(PG8_LAS unsigned char* lds, const Gemm g, const Sched& S, const Epi& E) {
;     ...
;             PG8_LDB(B0, 1, 0); PG8_LDB(B1, 1, 1); PG8_SCHED; PG8_LDA(At, 1, 0); PG8_STAGE(PG8_SA(0, 1), a2 + hstepA, voffA);
;             PG8_WAIT_V(8); PG8_WAIT_L(0); PG8_BAR; PG8_MMA(0, 0, At, B0); PG8_MMA(0, 1, At, B1); PG8_BAR; PG8_SCHED;
	s_add_i32 s72, 0, 0x18000
	s_add_i32 s73, 0, 0x1c000
	v_add_u32_e32 v162, s72, v145
	v_add_u32_e32 v178, s73, v145
	ds_read_b128 v[150:153], v162
	ds_read_b128 v[154:157], v162 offset:1024
	ds_read_b128 v[158:161], v162 offset:2048
	ds_read_b128 v[162:165], v162 offset:3072
	ds_read_b128 v[166:169], v178
	ds_read_b128 v[170:173], v178 offset:1024
	ds_read_b128 v[174:177], v178 offset:2048
	ds_read_b128 v[178:181], v178 offset:3072
	s_add_u32 s44, s44, 0x10000
	s_addc_u32 s45, s45, 0
	s_mov_b32 m0, s54
	v_lshl_add_u64 v[224:225], s[44:45], 0, v[128:129]
	ds_read_b128 v[182:185], v149 offset:32768
	ds_read_b128 v[188:191], v149 offset:33792
	ds_read_b128 v[192:195], v149 offset:34816
	ds_read_b128 v[196:199], v149 offset:35840
	ds_read_b128 v[200:203], v149 offset:36864
	ds_read_b128 v[204:207], v149 offset:37888
	ds_read_b128 v[208:211], v149 offset:38912
	ds_read_b128 v[212:215], v149 offset:39936
	global_load_lds_dwordx4 v[224:225], off
	v_lshl_add_u64 v[224:225], s[44:45], 0, v[132:133]
	s_mov_b32 m0, s55
	s_nop 0
	global_load_lds_dwordx4 v[224:225], off
	s_waitcnt vmcnt(8)
	s_waitcnt lgkmcnt(0)
	s_barrier
	s_waitcnt lgkmcnt(0)
	v_mfma_f32_16x16x32_bf16 v[124:127], v[150:153], v[182:185], v[124:127]
	v_mfma_f32_16x16x32_bf16 v[120:123], v[158:161], v[182:185], v[120:123]
	v_mfma_f32_16x16x32_bf16 v[108:111], v[150:153], v[192:195], v[108:111]
	v_mfma_f32_16x16x32_bf16 v[104:107], v[158:161], v[192:195], v[104:107]
	v_mfma_f32_16x16x32_bf16 v[92:95], v[150:153], v[200:203], v[92:95]
	v_mfma_f32_16x16x32_bf16 v[88:91], v[158:161], v[200:203], v[88:91]
	v_mfma_f32_16x16x32_bf16 v[76:79], v[150:153], v[208:211], v[76:79]
	v_mfma_f32_16x16x32_bf16 v[72:75], v[158:161], v[208:211], v[72:75]
	v_mfma_f32_16x16x32_bf16 v[124:127], v[154:157], v[188:191], v[124:127]
	v_mfma_f32_16x16x32_bf16 v[120:123], v[162:165], v[188:191], v[120:123]
	v_mfma_f32_16x16x32_bf16 v[108:111], v[154:157], v[196:199], v[108:111]
	v_mfma_f32_16x16x32_bf16 v[104:107], v[162:165], v[196:199], v[104:107]
	v_mfma_f32_16x16x32_bf16 v[92:95], v[154:157], v[204:207], v[92:95]
	v_mfma_f32_16x16x32_bf16 v[88:91], v[162:165], v[204:207], v[88:91]
	v_mfma_f32_16x16x32_bf16 v[76:79], v[154:157], v[212:215], v[76:79]
	v_mfma_f32_16x16x32_bf16 v[72:75], v[162:165], v[212:215], v[72:75]
	v_mfma_f32_16x16x32_bf16 v[116:119], v[166:169], v[182:185], v[116:119]
	v_mfma_f32_16x16x32_bf16 v[112:115], v[174:177], v[182:185], v[112:115]
	v_mfma_f32_16x16x32_bf16 v[100:103], v[166:169], v[192:195], v[100:103]
	v_mfma_f32_16x16x32_bf16 v[96:99], v[174:177], v[192:195], v[96:99]
	v_mfma_f32_16x16x32_bf16 v[84:87], v[166:169], v[200:203], v[84:87]
	v_mfma_f32_16x16x32_bf16 v[80:83], v[174:177], v[200:203], v[80:83]
	v_mfma_f32_16x16x32_bf16 v[68:71], v[166:169], v[208:211], v[68:71]
	v_mfma_f32_16x16x32_bf16 v[64:67], v[174:177], v[208:211], v[64:67]
	v_mfma_f32_16x16x32_bf16 v[116:119], v[170:173], v[188:191], v[116:119]
	v_mfma_f32_16x16x32_bf16 v[112:115], v[178:181], v[188:191], v[112:115]
	v_mfma_f32_16x16x32_bf16 v[100:103], v[170:173], v[196:199], v[100:103]
	v_mfma_f32_16x16x32_bf16 v[96:99], v[178:181], v[196:199], v[96:99]
	v_mfma_f32_16x16x32_bf16 v[84:87], v[170:173], v[204:207], v[84:87]
	v_mfma_f32_16x16x32_bf16 v[80:83], v[178:181], v[204:207], v[80:83]
	v_mfma_f32_16x16x32_bf16 v[68:71], v[170:173], v[212:215], v[68:71]
	v_mfma_f32_16x16x32_bf16 v[64:67], v[178:181], v[212:215], v[64:67]
	s_barrier
; #define PG8_STAGE(bufoff, gbase, voff) do { _Pragma("unroll") for (int _i = 0; _i < 2; ++_i) \
;         __builtin_amdgcn_global_load_lds((const unsigned*)((const char*)(gbase) + (voff)[_i]), (PG8_LAS unsigned*)(lds + (bufoff) + ldsw + _i * 8192), 16, 0, 0); } while (0)
; #define PG8_LDA(dst, b, h) do { _Pragma("unroll") for (int m = 0; m < 4; ++m) _Pragma("unroll") for (int k = 0; k < 2; ++k) dst[m][k] = *(const PG8_LAS bf16x8*)(lds + PG8_SA(b, h) + aoff + m * 2048 + k * 1024); } while (0)
; #define PG8_MMA(ai, bj, At, Bt) do { __builtin_amdgcn_s_setprio(1); _Pragma("unroll") for (int m = 0; m < 4; ++m) _Pragma("unroll") for (int n = 0; n < 2; ++n) _Pragma("unroll") for (int k = 0; k < 2; ++k) \
;         acc[ai][bj][m][n] = __builtin_amdgcn_mfma_f32_16x16x32_bf16(Bt[n][k], At[m][k], acc[ai][bj][m][n], 0, 0, 0); __builtin_amdgcn_s_setprio(0); } while (0)
; #define PG8_WAIT_V(n) asm volatile("s_waitcnt vmcnt(" #n ")" ::: "memory")
; #define PG8_WAIT_L(n) asm volatile("s_waitcnt lgkmcnt(" #n ")" ::: "memory")
; #define PG8_BAR __builtin_amdgcn_s_barrier()
; #define PG8_SCHED __builtin_amdgcn_sched_barrier(0)
; template <class Epi, class Sched, bool ALIGN_EPI = false, bool SP2 = false>
; __device__ __forceinline__ void gemm_phase(PG8_LAS unsigned char* lds, const Gemm g, const Sched& S, const Epi& E) {
;     ...
;         for (int t = 0; t < nt; t += 2) {
;             if constexpr (Epi::MIDK) { if (t == (nt >> 1)) { asm volatile("s_waitcnt vmcnt(0)" ::: "memory"); E.mid(acc, cur, wr, wc, fr, fq); asm volatile("s_waitcnt vmcnt(0)" ::: "memory"); } }
;             const bool last = (t == nt - 2);
;             const char* a1 = cA + (size_t)(t + 1) * kstep;
;             const char* a2 = last ? nA : cA + (size_t)(t + 2) * kstep; const char* b2 = last ? nB : cB + (size_t)(t + 2) * kstep;
;             const char* a3 = a2 + kstep; const char* b3 = b2 + kstep;
;     ...
;             PG8_LDA(At, 1, 1); PG8_STAGE(PG8_SB(1, 0), b3, voffB); PG8_STAGE(PG8_SB(1, 1), b3 + hstepB, voffB); PG8_STAGE(PG8_SA(1, 0), a3, voffA);
;             PG8_WAIT_V(8); PG8_WAIT_L(0); PG8_BAR; PG8_MMA(1, 0, At, B0); PG8_MMA(1, 1, At, B1); PG8_BAR; PG8_SCHED;
	s_add_i32 s44, s72, s52
	v_lshl_add_u64 v[216:217], v[216:217], 0, s[16:17]
	s_mov_b32 m0, s44
	ds_read_b128 v[182:185], v149 offset:49152
	ds_read_b128 v[188:191], v149 offset:50176
	ds_read_b128 v[192:195], v149 offset:51200
	ds_read_b128 v[196:199], v149 offset:52224
	ds_read_b128 v[200:203], v149 offset:53248
	ds_read_b128 v[204:207], v149 offset:54272
	ds_read_b128 v[208:211], v149 offset:55296
	ds_read_b128 v[212:215], v149 offset:56320
	global_load_lds_dwordx4 v[216:217], off
	s_add_i32 m0, s44, 0x2000
	s_add_u32 s42, s42, 0x10080
	v_lshl_add_u64 v[216:217], v[218:219], 0, s[16:17]
	s_addc_u32 s43, s43, 0
	s_add_i32 s44, s73, s52
	global_load_lds_dwordx4 v[216:217], off
	v_lshl_add_u64 v[216:217], s[42:43], 0, v[130:131]
	s_mov_b32 m0, s44
	s_nop 0
	global_load_lds_dwordx4 v[216:217], off
	v_lshl_add_u64 v[216:217], s[42:43], 0, v[134:135]
	s_add_i32 m0, s44, 0x2000
	s_nop 0
	global_load_lds_dwordx4 v[216:217], off
	v_lshl_add_u64 v[216:217], v[220:221], 0, s[16:17]
	s_mov_b32 m0, s58
	s_nop 0
	global_load_lds_dwordx4 v[216:217], off
	v_lshl_add_u64 v[216:217], v[222:223], 0, s[16:17]
	s_mov_b32 m0, s59
	s_nop 0
	global_load_lds_dwordx4 v[216:217], off
	s_waitcnt vmcnt(8)
	s_waitcnt lgkmcnt(0)
	s_barrier
	s_waitcnt lgkmcnt(0)
	v_mfma_f32_16x16x32_bf16 v[60:63], v[150:153], v[182:185], v[60:63]
	v_mfma_f32_16x16x32_bf16 v[56:59], v[158:161], v[182:185], v[56:59]
	v_mfma_f32_16x16x32_bf16 v[44:47], v[150:153], v[192:195], v[44:47]
	v_mfma_f32_16x16x32_bf16 v[40:43], v[158:161], v[192:195], v[40:43]
	v_mfma_f32_16x16x32_bf16 v[28:31], v[150:153], v[200:203], v[28:31]
	v_mfma_f32_16x16x32_bf16 v[24:27], v[158:161], v[200:203], v[24:27]
	v_mfma_f32_16x16x32_bf16 v[12:15], v[150:153], v[208:211], v[12:15]
	v_mfma_f32_16x16x32_bf16 v[8:11], v[158:161], v[208:211], v[8:11]
	v_mfma_f32_16x16x32_bf16 v[60:63], v[154:157], v[188:191], v[60:63]
	v_mfma_f32_16x16x32_bf16 v[56:59], v[162:165], v[188:191], v[56:59]
	v_mfma_f32_16x16x32_bf16 v[44:47], v[154:157], v[196:199], v[44:47]
	v_mfma_f32_16x16x32_bf16 v[40:43], v[162:165], v[196:199], v[40:43]
	v_mfma_f32_16x16x32_bf16 v[28:31], v[154:157], v[204:207], v[28:31]
	v_mfma_f32_16x16x32_bf16 v[24:27], v[162:165], v[204:207], v[24:27]
	v_mfma_f32_16x16x32_bf16 v[12:15], v[154:157], v[212:215], v[12:15]
	v_mfma_f32_16x16x32_bf16 v[8:11], v[162:165], v[212:215], v[8:11]
	v_mfma_f32_16x16x32_bf16 v[52:55], v[166:169], v[182:185], v[52:55]
	v_mfma_f32_16x16x32_bf16 v[48:51], v[174:177], v[182:185], v[48:51]
	v_mfma_f32_16x16x32_bf16 v[36:39], v[166:169], v[192:195], v[36:39]
	v_mfma_f32_16x16x32_bf16 v[32:35], v[174:177], v[192:195], v[32:35]
	v_mfma_f32_16x16x32_bf16 v[20:23], v[166:169], v[200:203], v[20:23]
	v_mfma_f32_16x16x32_bf16 v[16:19], v[174:177], v[200:203], v[16:19]
	v_mfma_f32_16x16x32_bf16 v[4:7], v[166:169], v[208:211], v[4:7]
	v_mfma_f32_16x16x32_bf16 v[0:3], v[174:177], v[208:211], v[0:3]
	v_mfma_f32_16x16x32_bf16 v[52:55], v[170:173], v[188:191], v[52:55]
	v_mfma_f32_16x16x32_bf16 v[48:51], v[178:181], v[188:191], v[48:51]
	v_mfma_f32_16x16x32_bf16 v[36:39], v[170:173], v[196:199], v[36:39]
	v_mfma_f32_16x16x32_bf16 v[32:35], v[178:181], v[196:199], v[32:35]
	v_mfma_f32_16x16x32_bf16 v[20:23], v[170:173], v[204:207], v[20:23]
	v_mfma_f32_16x16x32_bf16 v[16:19], v[178:181], v[204:207], v[16:19]
	v_mfma_f32_16x16x32_bf16 v[4:7], v[170:173], v[212:215], v[4:7]
	v_mfma_f32_16x16x32_bf16 v[0:3], v[178:181], v[212:215], v[0:3]
	s_barrier
	s_add_u32 s69, s69, 0x100
	s_addc_u32 s70, s70, 0
	s_add_u32 s40, s40, 0x100
	s_addc_u32 s41, s41, 0
	s_cmp_ge_i32 s71, s57
	s_mov_b32 s42, s71
	s_cbranch_scc0 .LBB0_988
	s_setprio 0

;     __host__ __device__ bool next(int i, Unit& u) const { return i < cnt ? so.next(base + i, u) : false; }
;     __host__ __device__ bool next(int i, Unit& u) const { const int L = i * G + c; if (L >= 32) return false; u.g = L >> 3; u.pm = L & 7; u.pn = 0; return true; }
; #define PG8_STAGE(bufoff, gbase, voff) do { _Pragma("unroll") for (int _i = 0; _i < 2; ++_i) \
;         __builtin_amdgcn_global_load_lds((const unsigned*)((const char*)(gbase) + (voff)[_i]), (PG8_LAS unsigned*)(lds + (bufoff) + ldsw + _i * 8192), 16, 0, 0); } while (0)
; #define PG8_LDA(dst, b, h) do { _Pragma("unroll") for (int m = 0; m < 4; ++m) _Pragma("unroll") for (int k = 0; k < 2; ++k) dst[m][k] = *(const PG8_LAS bf16x8*)(lds + PG8_SA(b, h) + aoff + m * 2048 + k * 1024); } while (0)
; #define PG8_LDB(dst, b, h) do { _Pragma("unroll") for (int n = 0; n < 2; ++n) _Pragma("unroll") for (int k = 0; k < 2; ++k) dst[n][k] = *(const PG8_LAS bf16x8*)(lds + PG8_SB(b, h) + boff + n * 2048 + k * 1024); } while (0)
; #define PG8_BAR __builtin_amdgcn_s_barrier()
; template <class Epi, class Sched, bool ALIGN_EPI = false, bool SP2 = false>
; __device__ __forceinline__ void gemm_phase(PG8_LAS unsigned char* lds, const Gemm g, const Sched& S, const Epi& E) {
;     ...
;         const bool has_next = S.next(ui + 1, nxt);
;         const char* nA = has_next ? (const char*)(g.A + (size_t)nxt.g * g.gsA) + (size_t)nxt.pm * tstepA : cA; const char* nB = has_next ? (const char*)(g.Bt + (size_t)nxt.g * g.gsB) + (size_t)nxt.pn * tstepB : cB;
;         for (int t = 0; t < nt; t += 2) {
;             if constexpr (Epi::MIDK) { if (t == (nt >> 1)) { asm volatile("s_waitcnt vmcnt(0)" ::: "memory"); E.mid(acc, cur, wr, wc, fr, fq); asm volatile("s_waitcnt vmcnt(0)" ::: "memory"); } }
;             const bool last = (t == nt - 2);
;             const char* a1 = cA + (size_t)(t + 1) * kstep;
;             const char* a2 = last ? nA : cA + (size_t)(t + 2) * kstep; const char* b2 = last ? nB : cB + (size_t)(t + 2) * kstep;
;             const char* a3 = a2 + kstep; const char* b3 = b2 + kstep;
;             if (last && has_next) S.a_ready(nxt);
;             if constexpr (SP2) {
;             PG8_LDB(B0, 0, 0); PG8_LDB(B1, 0, 1); PG8_SCHED; PG8_LDA(At, 0, 0); PG8_STAGE(PG8_SA(1, 1), a1 + hstepA, voffA);
;             PG8_WAIT_V(8); PG8_WAIT_L(0); PG8_BAR; PG8_MMA(0, 0, At, B0); PG8_MMA(0, 1, At, B1); PG8_BAR; PG8_SCHED;
.LBB0_1012:
	s_ashr_i32 s29, s28, 31
	s_lshl_b64 s[30:31], s[28:29], 20
	s_add_u32 s30, s16, s30
	s_addc_u32 s31, s17, s31
	s_ashr_i32 s27, s26, 31
	s_lshl_b64 s[34:35], s[26:27], 20
	s_add_u32 s34, s44, s34
	s_addc_u32 s35, s45, s35
	s_andn2_b64 vcc, exec, s[24:25]
	s_cbranch_vccnz .LBB0_1015
	s_and_b64 s[36:37], s[6:7], exec
	s_cselect_b32 s27, s31, s21
	s_cselect_b32 s29, s30, s20
	s_cselect_b32 s62, s35, s19
	s_cselect_b32 s63, s34, s18
	s_add_u32 s64, s18, 0x100
	s_addc_u32 s65, s19, 0
	s_add_u32 s36, s20, 0x80080
	s_addc_u32 s37, s21, 0
	s_mov_b32 s38, 0
	v_readfirstlane_b32 s32, v227
	s_nop 3
	s_lshr_b32 s32, s32, 6
	s_cmp_ge_u32 s32, 4
	s_cbranch_scc0 .Lprio_7
	s_setprio 1
.Lprio_7:
.LBB0_1014:
	v_add_u32_e32 v113, s58, v149
	ds_read_b128 v[158:161], v113
	ds_read_b128 v[162:165], v113 offset:1024
	ds_read_b128 v[166:169], v113 offset:2048
	ds_read_b128 v[170:173], v113 offset:3072
	v_add_u32_e32 v113, s59, v149
	ds_read_b128 v[174:177], v113
	ds_read_b128 v[178:181], v113 offset:1024
	ds_read_b128 v[182:185], v113 offset:2048
	ds_read_b128 v[188:191], v113 offset:3072
	s_add_i32 s66, s38, 2
	s_add_u32 s39, s36, 0xfff80080
	s_addc_u32 s40, s37, -1
	s_cmp_eq_u32 s56, s38
	s_cselect_b32 s38, s63, s64
	s_cselect_b32 s41, s27, s40
	s_cselect_b32 s40, s29, s39
	s_cselect_b32 s39, s62, s65
	v_lshl_add_u64 v[114:115], s[36:37], 0, v[142:143]
	s_add_i32 m0, s13, 0xc000
	ds_read_b128 v[192:195], v150
	ds_read_b128 v[196:199], v150 offset:1024
	ds_read_b128 v[200:203], v150 offset:2048
	ds_read_b128 v[204:207], v150 offset:3072
	ds_read_b128 v[208:211], v150 offset:4096
	ds_read_b128 v[212:215], v150 offset:5120
	ds_read_b128 v[216:219], v150 offset:6144
	ds_read_b128 v[220:223], v150 offset:7168
	global_load_lds_dwordx4 v[114:115], off
	v_lshl_add_u64 v[114:115], s[36:37], 0, v[140:141]
	s_add_i32 m0, s13, 0xe000
	s_nop 0
	global_load_lds_dwordx4 v[114:115], off
	s_waitcnt vmcnt(8)
	s_waitcnt lgkmcnt(0)
	s_barrier
	s_waitcnt lgkmcnt(0)
	v_mfma_f32_16x16x32_bf16 v[128:131], v[158:161], v[192:195], v[128:131]
	v_mfma_f32_16x16x32_bf16 v[124:127], v[166:169], v[192:195], v[124:127]
	v_mfma_f32_16x16x32_bf16 v[108:111], v[158:161], v[200:203], v[108:111]
	v_mfma_f32_16x16x32_bf16 v[104:107], v[166:169], v[200:203], v[104:107]
	v_mfma_f32_16x16x32_bf16 v[92:95], v[158:161], v[208:211], v[92:95]
	v_mfma_f32_16x16x32_bf16 v[88:91], v[166:169], v[208:211], v[88:91]
	v_mfma_f32_16x16x32_bf16 v[76:79], v[158:161], v[216:219], v[76:79]
	v_mfma_f32_16x16x32_bf16 v[72:75], v[166:169], v[216:219], v[72:75]
	v_mfma_f32_16x16x32_bf16 v[128:131], v[162:165], v[196:199], v[128:131]
	v_mfma_f32_16x16x32_bf16 v[124:127], v[170:173], v[196:199], v[124:127]
	v_mfma_f32_16x16x32_bf16 v[108:111], v[162:165], v[204:207], v[108:111]
	v_mfma_f32_16x16x32_bf16 v[104:107], v[170:173], v[204:207], v[104:107]
	v_mfma_f32_16x16x32_bf16 v[92:95], v[162:165], v[212:215], v[92:95]
	v_mfma_f32_16x16x32_bf16 v[88:91], v[170:173], v[212:215], v[88:91]
	v_mfma_f32_16x16x32_bf16 v[76:79], v[162:165], v[220:223], v[76:79]
	v_mfma_f32_16x16x32_bf16 v[72:75], v[170:173], v[220:223], v[72:75]
	v_mfma_f32_16x16x32_bf16 v[120:123], v[174:177], v[192:195], v[120:123]
	v_mfma_f32_16x16x32_bf16 v[114:117], v[182:185], v[192:195], v[116:119]
	v_mfma_f32_16x16x32_bf16 v[100:103], v[174:177], v[200:203], v[100:103]
	v_mfma_f32_16x16x32_bf16 v[96:99], v[182:185], v[200:203], v[96:99]
	v_mfma_f32_16x16x32_bf16 v[84:87], v[174:177], v[208:211], v[84:87]
	v_mfma_f32_16x16x32_bf16 v[80:83], v[182:185], v[208:211], v[80:83]
	v_mfma_f32_16x16x32_bf16 v[68:71], v[174:177], v[216:219], v[68:71]
	v_mfma_f32_16x16x32_bf16 v[64:67], v[182:185], v[216:219], v[64:67]
	v_mfma_f32_16x16x32_bf16 v[120:123], v[178:181], v[196:199], v[120:123]
	v_mfma_f32_16x16x32_bf16 v[114:117], v[188:191], v[196:199], v[114:117]
	v_mfma_f32_16x16x32_bf16 v[100:103], v[178:181], v[204:207], v[100:103]
	v_mfma_f32_16x16x32_bf16 v[96:99], v[188:191], v[204:207], v[96:99]
	v_mfma_f32_16x16x32_bf16 v[84:87], v[178:181], v[212:215], v[84:87]
	v_mfma_f32_16x16x32_bf16 v[80:83], v[188:191], v[212:215], v[80:83]
	v_mfma_f32_16x16x32_bf16 v[68:71], v[178:181], v[220:223], v[68:71]
	v_mfma_f32_16x16x32_bf16 v[64:67], v[188:191], v[220:223], v[64:67]
	s_barrier
	s_add_i32 s67, s58, s43
	v_lshl_add_u64 v[152:153], s[38:39], 0, v[134:135]
	s_mov_b32 m0, s67
	ds_read_b128 v[192:195], v150 offset:16384
	ds_read_b128 v[196:199], v150 offset:17408
	ds_read_b128 v[200:203], v150 offset:18432
	ds_read_b128 v[204:207], v150 offset:19456
	ds_read_b128 v[208:211], v150 offset:20480
	ds_read_b128 v[212:215], v150 offset:21504
	ds_read_b128 v[216:219], v150 offset:22528
	ds_read_b128 v[220:223], v150 offset:23552
	global_load_lds_dwordx4 v[152:153], off
	s_add_i32 m0, s67, 0x2000
	s_add_u32 s68, s38, 0x80000
	v_lshl_add_u64 v[224:225], s[38:39], 0, v[138:139]
	s_addc_u32 s69, s39, 0
	s_add_i32 s67, s59, s43
	global_load_lds_dwordx4 v[224:225], off
	v_lshl_add_u64 v[118:119], s[68:69], 0, v[134:135]
	s_mov_b32 m0, s67
	v_lshl_add_u64 v[226:227], s[40:41], 0, v[132:133]
	global_load_lds_dwordx4 v[118:119], off
	v_lshl_add_u64 v[118:119], s[68:69], 0, v[138:139]
	s_add_i32 m0, s67, 0x2000
	v_lshl_add_u64 v[228:229], s[40:41], 0, v[136:137]
	global_load_lds_dwordx4 v[118:119], off
	s_mov_b32 m0, s13
	s_nop 0
	global_load_lds_dwordx4 v[226:227], off
	s_mov_b32 m0, s48
	s_nop 0
	global_load_lds_dwordx4 v[228:229], off
	s_waitcnt vmcnt(8)
	s_waitcnt lgkmcnt(0)
	s_barrier
; #define PG8_STAGE(bufoff, gbase, voff) do { _Pragma("unroll") for (int _i = 0; _i < 2; ++_i) \
;         __builtin_amdgcn_global_load_lds((const unsigned*)((const char*)(gbase) + (voff)[_i]), (PG8_LAS unsigned*)(lds + (bufoff) + ldsw + _i * 8192), 16, 0, 0); } while (0)
; #define PG8_LDA(dst, b, h) do { _Pragma("unroll") for (int m = 0; m < 4; ++m) _Pragma("unroll") for (int k = 0; k < 2; ++k) dst[m][k] = *(const PG8_LAS bf16x8*)(lds + PG8_SA(b, h) + aoff + m * 2048 + k * 1024); } while (0)
; #define PG8_LDB(dst, b, h) do { _Pragma("unroll") for (int n = 0; n < 2; ++n) _Pragma("unroll") for (int k = 0; k < 2; ++k) dst[n][k] = *(const PG8_LAS bf16x8*)(lds + PG8_SB(b, h) + boff + n * 2048 + k * 1024); } while (0)
; #define PG8_MMA(ai, bj, At, Bt) do { __builtin_amdgcn_s_setprio(1); _Pragma("unroll") for (int m = 0; m < 4; ++m) _Pragma("unroll") for (int n = 0; n < 2; ++n) _Pragma("unroll") for (int k = 0; k < 2; ++k) \
;         acc[ai][bj][m][n] = __builtin_amdgcn_mfma_f32_16x16x32_bf16(Bt[n][k], At[m][k], acc[ai][bj][m][n], 0, 0, 0); __builtin_amdgcn_s_setprio(0); } while (0)
; #define PG8_WAIT_V(n) asm volatile("s_waitcnt vmcnt(" #n ")" ::: "memory")
; #define PG8_WAIT_L(n) asm volatile("s_waitcnt lgkmcnt(" #n ")" ::: "memory")
; #define PG8_BAR __builtin_amdgcn_s_barrier()
; #define PG8_SCHED __builtin_amdgcn_sched_barrier(0)
; template <class Epi, class Sched, bool ALIGN_EPI = false, bool SP2 = false>
; __device__ __forceinline__ void gemm_phase(PG8_LAS unsigned char* lds, const Gemm g, const Sched& S, const Epi& E) {
;     ...
;             PG8_LDA(At, 0, 1); PG8_STAGE(PG8_SB(0, 0), b2, voffB); PG8_STAGE(PG8_SB(0, 1), b2 + hstepB, voffB); PG8_STAGE(PG8_SA(0, 0), a2, voffA);
;             PG8_WAIT_V(8); PG8_WAIT_L(0); PG8_BAR; PG8_MMA(1, 0, At, B0); PG8_MMA(1, 1, At, B1); PG8_BAR; PG8_SCHED;
;             PG8_LDB(B0, 1, 0); PG8_LDB(B1, 1, 1); PG8_SCHED; PG8_LDA(At, 1, 0); PG8_STAGE(PG8_SA(0, 1), a2 + hstepA, voffA);
;             PG8_WAIT_V(8); PG8_WAIT_L(0); PG8_BAR; PG8_MMA(0, 0, At, B0); PG8_MMA(0, 1, At, B1); PG8_BAR; PG8_SCHED;
	s_waitcnt lgkmcnt(0)
	v_mfma_f32_16x16x32_bf16 v[60:63], v[158:161], v[192:195], v[60:63]
	v_mfma_f32_16x16x32_bf16 v[56:59], v[166:169], v[192:195], v[56:59]
	v_mfma_f32_16x16x32_bf16 v[44:47], v[158:161], v[200:203], v[44:47]
	v_mfma_f32_16x16x32_bf16 v[40:43], v[166:169], v[200:203], v[40:43]
	v_mfma_f32_16x16x32_bf16 v[28:31], v[158:161], v[208:211], v[28:31]
	v_mfma_f32_16x16x32_bf16 v[24:27], v[166:169], v[208:211], v[24:27]
	v_mfma_f32_16x16x32_bf16 v[12:15], v[158:161], v[216:219], v[12:15]
	v_mfma_f32_16x16x32_bf16 v[8:11], v[166:169], v[216:219], v[8:11]
	v_mfma_f32_16x16x32_bf16 v[60:63], v[162:165], v[196:199], v[60:63]
	v_mfma_f32_16x16x32_bf16 v[56:59], v[170:173], v[196:199], v[56:59]
	v_mfma_f32_16x16x32_bf16 v[44:47], v[162:165], v[204:207], v[44:47]
	v_mfma_f32_16x16x32_bf16 v[40:43], v[170:173], v[204:207], v[40:43]
	v_mfma_f32_16x16x32_bf16 v[28:31], v[162:165], v[212:215], v[28:31]
	v_mfma_f32_16x16x32_bf16 v[24:27], v[170:173], v[212:215], v[24:27]
	v_mfma_f32_16x16x32_bf16 v[12:15], v[162:165], v[220:223], v[12:15]
	v_mfma_f32_16x16x32_bf16 v[8:11], v[170:173], v[220:223], v[8:11]
	v_mfma_f32_16x16x32_bf16 v[52:55], v[174:177], v[192:195], v[52:55]
	v_mfma_f32_16x16x32_bf16 v[48:51], v[182:185], v[192:195], v[48:51]
	v_mfma_f32_16x16x32_bf16 v[36:39], v[174:177], v[200:203], v[36:39]
	v_mfma_f32_16x16x32_bf16 v[32:35], v[182:185], v[200:203], v[32:35]
	v_mfma_f32_16x16x32_bf16 v[20:23], v[174:177], v[208:211], v[20:23]
	v_mfma_f32_16x16x32_bf16 v[16:19], v[182:185], v[208:211], v[16:19]
	v_mfma_f32_16x16x32_bf16 v[4:7], v[174:177], v[216:219], v[4:7]
	v_mfma_f32_16x16x32_bf16 v[0:3], v[182:185], v[216:219], v[0:3]
	v_mfma_f32_16x16x32_bf16 v[52:55], v[178:181], v[196:199], v[52:55]
	v_mfma_f32_16x16x32_bf16 v[48:51], v[188:191], v[196:199], v[48:51]
	v_mfma_f32_16x16x32_bf16 v[36:39], v[178:181], v[204:207], v[36:39]
	v_mfma_f32_16x16x32_bf16 v[32:35], v[188:191], v[204:207], v[32:35]
	v_mfma_f32_16x16x32_bf16 v[20:23], v[178:181], v[212:215], v[20:23]
	v_mfma_f32_16x16x32_bf16 v[16:19], v[188:191], v[212:215], v[16:19]
	v_mfma_f32_16x16x32_bf16 v[4:7], v[178:181], v[220:223], v[4:7]
	v_mfma_f32_16x16x32_bf16 v[0:3], v[188:191], v[220:223], v[0:3]
	s_barrier
	s_add_i32 s67, 0, 0x18000
	v_add_u32_e32 v113, s67, v149
	s_add_i32 s68, 0, 0x1c000
	ds_read_b128 v[158:161], v113
	ds_read_b128 v[162:165], v113 offset:1024
	ds_read_b128 v[166:169], v113 offset:2048
	ds_read_b128 v[170:173], v113 offset:3072
	v_add_u32_e32 v113, s68, v149
	ds_read_b128 v[174:177], v113
	ds_read_b128 v[178:181], v113 offset:1024
	ds_read_b128 v[182:185], v113 offset:2048
	ds_read_b128 v[188:191], v113 offset:3072
	s_add_u32 s40, s40, 0x80000
	s_addc_u32 s41, s41, 0
	s_mov_b32 m0, s49
	v_lshl_add_u64 v[118:119], s[40:41], 0, v[132:133]
	ds_read_b128 v[192:195], v150 offset:32768
	ds_read_b128 v[196:199], v150 offset:33792
	ds_read_b128 v[200:203], v150 offset:34816
	ds_read_b128 v[204:207], v150 offset:35840
	ds_read_b128 v[208:211], v150 offset:36864
	ds_read_b128 v[212:215], v150 offset:37888
	ds_read_b128 v[216:219], v150 offset:38912
	ds_read_b128 v[220:223], v150 offset:39936
	global_load_lds_dwordx4 v[118:119], off
	v_lshl_add_u64 v[118:119], s[40:41], 0, v[136:137]
	s_mov_b32 m0, s50
	s_nop 0
	global_load_lds_dwordx4 v[118:119], off
	s_waitcnt vmcnt(8)
	s_waitcnt lgkmcnt(0)
	s_barrier
	s_waitcnt lgkmcnt(0)
	v_mfma_f32_16x16x32_bf16 v[128:131], v[158:161], v[192:195], v[128:131]
	v_mfma_f32_16x16x32_bf16 v[124:127], v[166:169], v[192:195], v[124:127]
	v_mfma_f32_16x16x32_bf16 v[108:111], v[158:161], v[200:203], v[108:111]
	v_mfma_f32_16x16x32_bf16 v[104:107], v[166:169], v[200:203], v[104:107]
	v_mfma_f32_16x16x32_bf16 v[92:95], v[158:161], v[208:211], v[92:95]
	v_mfma_f32_16x16x32_bf16 v[88:91], v[166:169], v[208:211], v[88:91]
	v_mfma_f32_16x16x32_bf16 v[76:79], v[158:161], v[216:219], v[76:79]
	v_mfma_f32_16x16x32_bf16 v[72:75], v[166:169], v[216:219], v[72:75]
	v_mfma_f32_16x16x32_bf16 v[128:131], v[162:165], v[196:199], v[128:131]
	v_mfma_f32_16x16x32_bf16 v[124:127], v[170:173], v[196:199], v[124:127]
	v_mfma_f32_16x16x32_bf16 v[108:111], v[162:165], v[204:207], v[108:111]
	v_mfma_f32_16x16x32_bf16 v[104:107], v[170:173], v[204:207], v[104:107]
	v_mfma_f32_16x16x32_bf16 v[92:95], v[162:165], v[212:215], v[92:95]
	v_mfma_f32_16x16x32_bf16 v[88:91], v[170:173], v[212:215], v[88:91]
	v_mfma_f32_16x16x32_bf16 v[76:79], v[162:165], v[220:223], v[76:79]
	v_mfma_f32_16x16x32_bf16 v[72:75], v[170:173], v[220:223], v[72:75]
	v_mfma_f32_16x16x32_bf16 v[118:121], v[174:177], v[192:195], v[120:123]
	v_mfma_f32_16x16x32_bf16 v[114:117], v[182:185], v[192:195], v[114:117]
	v_mfma_f32_16x16x32_bf16 v[100:103], v[174:177], v[200:203], v[100:103]
	v_mfma_f32_16x16x32_bf16 v[96:99], v[182:185], v[200:203], v[96:99]
	v_mfma_f32_16x16x32_bf16 v[84:87], v[174:177], v[208:211], v[84:87]
	v_mfma_f32_16x16x32_bf16 v[80:83], v[182:185], v[208:211], v[80:83]
	v_mfma_f32_16x16x32_bf16 v[68:71], v[174:177], v[216:219], v[68:71]
	v_mfma_f32_16x16x32_bf16 v[64:67], v[182:185], v[216:219], v[64:67]
	v_mfma_f32_16x16x32_bf16 v[120:123], v[178:181], v[196:199], v[118:121]
	v_mfma_f32_16x16x32_bf16 v[116:119], v[188:191], v[196:199], v[114:117]
	v_mfma_f32_16x16x32_bf16 v[100:103], v[178:181], v[204:207], v[100:103]
	v_mfma_f32_16x16x32_bf16 v[96:99], v[188:191], v[204:207], v[96:99]
	v_mfma_f32_16x16x32_bf16 v[84:87], v[178:181], v[212:215], v[84:87]
	v_mfma_f32_16x16x32_bf16 v[80:83], v[188:191], v[212:215], v[80:83]
	v_mfma_f32_16x16x32_bf16 v[68:71], v[178:181], v[220:223], v[68:71]
	v_mfma_f32_16x16x32_bf16 v[64:67], v[188:191], v[220:223], v[64:67]
	s_barrier
; #define PG8_STAGE(bufoff, gbase, voff) do { _Pragma("unroll") for (int _i = 0; _i < 2; ++_i) \
;         __builtin_amdgcn_global_load_lds((const unsigned*)((const char*)(gbase) + (voff)[_i]), (PG8_LAS unsigned*)(lds + (bufoff) + ldsw + _i * 8192), 16, 0, 0); } while (0)
; #define PG8_LDA(dst, b, h) do { _Pragma("unroll") for (int m = 0; m < 4; ++m) _Pragma("unroll") for (int k = 0; k < 2; ++k) dst[m][k] = *(const PG8_LAS bf16x8*)(lds + PG8_SA(b, h) + aoff + m * 2048 + k * 1024); } while (0)
; #define PG8_MMA(ai, bj, At, Bt) do { __builtin_amdgcn_s_setprio(1); _Pragma("unroll") for (int m = 0; m < 4; ++m) _Pragma("unroll") for (int n = 0; n < 2; ++n) _Pragma("unroll") for (int k = 0; k < 2; ++k) \
;         acc[ai][bj][m][n] = __builtin_amdgcn_mfma_f32_16x16x32_bf16(Bt[n][k], At[m][k], acc[ai][bj][m][n], 0, 0, 0); __builtin_amdgcn_s_setprio(0); } while (0)
; #define PG8_WAIT_V(n) asm volatile("s_waitcnt vmcnt(" #n ")" ::: "memory")
; #define PG8_WAIT_L(n) asm volatile("s_waitcnt lgkmcnt(" #n ")" ::: "memory")
; #define PG8_BAR __builtin_amdgcn_s_barrier()
; #define PG8_SCHED __builtin_amdgcn_sched_barrier(0)
; template <class Epi, class Sched, bool ALIGN_EPI = false, bool SP2 = false>
; __device__ __forceinline__ void gemm_phase(PG8_LAS unsigned char* lds, const Gemm g, const Sched& S, const Epi& E) {
;     ...
;         for (int t = 0; t < nt; t += 2) {
;             if constexpr (Epi::MIDK) { if (t == (nt >> 1)) { asm volatile("s_waitcnt vmcnt(0)" ::: "memory"); E.mid(acc, cur, wr, wc, fr, fq); asm volatile("s_waitcnt vmcnt(0)" ::: "memory"); } }
;             const bool last = (t == nt - 2);
;             const char* a1 = cA + (size_t)(t + 1) * kstep;
;             const char* a2 = last ? nA : cA + (size_t)(t + 2) * kstep; const char* b2 = last ? nB : cB + (size_t)(t + 2) * kstep;
;             const char* a3 = a2 + kstep; const char* b3 = b2 + kstep;
;     ...
;             PG8_LDA(At, 1, 1); PG8_STAGE(PG8_SB(1, 0), b3, voffB); PG8_STAGE(PG8_SB(1, 1), b3 + hstepB, voffB); PG8_STAGE(PG8_SA(1, 0), a3, voffA);
;             PG8_WAIT_V(8); PG8_WAIT_L(0); PG8_BAR; PG8_MMA(1, 0, At, B0); PG8_MMA(1, 1, At, B1); PG8_BAR; PG8_SCHED;
	s_add_i32 s40, s67, s43
	v_lshl_add_u64 v[114:115], v[152:153], 0, s[22:23]
	s_mov_b32 m0, s40
	ds_read_b128 v[192:195], v150 offset:49152
	ds_read_b128 v[196:199], v150 offset:50176
	ds_read_b128 v[200:203], v150 offset:51200
	ds_read_b128 v[204:207], v150 offset:52224
	ds_read_b128 v[208:211], v150 offset:53248
	ds_read_b128 v[212:215], v150 offset:54272
	ds_read_b128 v[216:219], v150 offset:55296
	ds_read_b128 v[220:223], v150 offset:56320
	global_load_lds_dwordx4 v[114:115], off
	s_add_i32 m0, s40, 0x2000
	s_add_u32 s38, s38, 0x80080
	v_lshl_add_u64 v[114:115], v[224:225], 0, s[22:23]
	s_addc_u32 s39, s39, 0
	s_add_i32 s40, s68, s43
	global_load_lds_dwordx4 v[114:115], off
	v_lshl_add_u64 v[114:115], s[38:39], 0, v[134:135]
	s_mov_b32 m0, s40
	s_nop 0
	global_load_lds_dwordx4 v[114:115], off
	v_lshl_add_u64 v[114:115], s[38:39], 0, v[138:139]
	s_add_i32 m0, s40, 0x2000
	s_nop 0
	global_load_lds_dwordx4 v[114:115], off
	v_lshl_add_u64 v[114:115], v[226:227], 0, s[22:23]
	s_mov_b32 m0, s54
	s_nop 0
	global_load_lds_dwordx4 v[114:115], off
	v_lshl_add_u64 v[114:115], v[228:229], 0, s[22:23]
	s_mov_b32 m0, s55
	s_nop 0
	global_load_lds_dwordx4 v[114:115], off
	s_waitcnt vmcnt(8)
	s_waitcnt lgkmcnt(0)
	s_barrier
	s_waitcnt lgkmcnt(0)
	v_mfma_f32_16x16x32_bf16 v[60:63], v[158:161], v[192:195], v[60:63]
	v_mfma_f32_16x16x32_bf16 v[56:59], v[166:169], v[192:195], v[56:59]
	v_mfma_f32_16x16x32_bf16 v[44:47], v[158:161], v[200:203], v[44:47]
	v_mfma_f32_16x16x32_bf16 v[40:43], v[166:169], v[200:203], v[40:43]
	v_mfma_f32_16x16x32_bf16 v[28:31], v[158:161], v[208:211], v[28:31]
	v_mfma_f32_16x16x32_bf16 v[24:27], v[166:169], v[208:211], v[24:27]
	v_mfma_f32_16x16x32_bf16 v[12:15], v[158:161], v[216:219], v[12:15]
	v_mfma_f32_16x16x32_bf16 v[8:11], v[166:169], v[216:219], v[8:11]
	v_mfma_f32_16x16x32_bf16 v[60:63], v[162:165], v[196:199], v[60:63]
	v_mfma_f32_16x16x32_bf16 v[56:59], v[170:173], v[196:199], v[56:59]
	v_mfma_f32_16x16x32_bf16 v[44:47], v[162:165], v[204:207], v[44:47]
	v_mfma_f32_16x16x32_bf16 v[40:43], v[170:173], v[204:207], v[40:43]
	v_mfma_f32_16x16x32_bf16 v[28:31], v[162:165], v[212:215], v[28:31]
	v_mfma_f32_16x16x32_bf16 v[24:27], v[170:173], v[212:215], v[24:27]
	v_mfma_f32_16x16x32_bf16 v[12:15], v[162:165], v[220:223], v[12:15]
	v_mfma_f32_16x16x32_bf16 v[8:11], v[170:173], v[220:223], v[8:11]
	v_mfma_f32_16x16x32_bf16 v[52:55], v[174:177], v[192:195], v[52:55]
	v_mfma_f32_16x16x32_bf16 v[48:51], v[182:185], v[192:195], v[48:51]
	v_mfma_f32_16x16x32_bf16 v[36:39], v[174:177], v[200:203], v[36:39]
	v_mfma_f32_16x16x32_bf16 v[32:35], v[182:185], v[200:203], v[32:35]
	v_mfma_f32_16x16x32_bf16 v[20:23], v[174:177], v[208:211], v[20:23]
	v_mfma_f32_16x16x32_bf16 v[16:19], v[182:185], v[208:211], v[16:19]
	v_mfma_f32_16x16x32_bf16 v[4:7], v[174:177], v[216:219], v[4:7]
	v_mfma_f32_16x16x32_bf16 v[0:3], v[182:185], v[216:219], v[0:3]
	v_mfma_f32_16x16x32_bf16 v[52:55], v[178:181], v[196:199], v[52:55]
	v_mfma_f32_16x16x32_bf16 v[48:51], v[188:191], v[196:199], v[48:51]
	v_mfma_f32_16x16x32_bf16 v[36:39], v[178:181], v[204:207], v[36:39]
	v_mfma_f32_16x16x32_bf16 v[32:35], v[188:191], v[204:207], v[32:35]
	v_mfma_f32_16x16x32_bf16 v[20:23], v[178:181], v[212:215], v[20:23]
	v_mfma_f32_16x16x32_bf16 v[16:19], v[188:191], v[212:215], v[16:19]
	v_mfma_f32_16x16x32_bf16 v[4:7], v[178:181], v[220:223], v[4:7]
	v_mfma_f32_16x16x32_bf16 v[0:3], v[188:191], v[220:223], v[0:3]
	s_barrier
	s_add_u32 s64, s64, 0x100
	s_addc_u32 s65, s65, 0
	s_add_u32 s36, s36, 0x100
	s_addc_u32 s37, s37, 0
	s_cmp_ge_i32 s66, s53
	s_mov_b32 s38, s66
	s_cbranch_scc0 .LBB0_1014
	s_setprio 0
